# P1: norm loop 3-deep prefetch, BW-row wave sums by DPP, KD table as one wave per (dg,tau) with 16B loads; alignment pads keep later code offsets
# speedup vs baseline: 1.0136x; 1.0121x over previous
; __device__ __forceinline__ void store_bf4(bf16_t* p, f32x4 v) { uint2 o; o.x = pk2(v[0], v[1]); o.y = pk2(v[2], v[3]); *(uint2*)p = o; }
; __device__ __forceinline__ void norm_row_pre(const f32x4 (&v)[4], const float* __restrict__ g, const float* __restrict__ shift, const float* __restrict__ scale, bf16_t* __restrict__ dst, int lane) {
;     float ss = 0.f;
; #pragma unroll
;     for (int j = 0; j < 4; ++j) ss += v[j][0] * v[j][0] + v[j][1] * v[j][1] + v[j][2] * v[j][2] + v[j][3] * v[j][3];
;     ss = wave_sum(ss);
;     const float rstd = rsqrtf(ss * (1.f / 1024.f) + 1e-6f);
; #pragma unroll
;     for (int j = 0; j < 4; ++j) {
;         const int c4 = lane + 64 * j;
;         const f32x4 g4 = ((const f32x4*)g)[c4], sh = ((const f32x4*)shift)[c4], sc = ((const f32x4*)scale)[c4];
;         f32x4 h = (v[j] * rstd) * g4; h = h * (sc + 1.f) + sh;
;         store_bf4(dst + c4 * 4, h);
;     }
; __device__ __forceinline__ void phase1(const Params& P) {
;     ...
;         int row = blockIdx.x * 8 + w;
;         f32x4 vn[4];
;         if (row < NT) { const float* src = row < NL ? P.in[0] + (size_t)row * 1024 : P.in[2] + (size_t)(row - NL) * 1024;
; #pragma unroll
;             for (int j = 0; j < 4; ++j) vn[j] = ((const f32x4*)src)[lane + 64 * j]; }
;         while (row < NT) {
;             f32x4 v[4];
; #pragma unroll
;             for (int j = 0; j < 4; ++j) v[j] = vn[j];
;             const int nrow = row + stride;
;             if (nrow < NT) { const float* src = nrow < NL ? P.in[0] + (size_t)nrow * 1024 : P.in[2] + (size_t)(nrow - NL) * 1024;
; #pragma unroll
;                 for (int j = 0; j < 4; ++j) vn[j] = ((const f32x4*)src)[lane + 64 * j]; }
;             const int mr = row < NL ? (row >> 13) : 4;
;             norm_row_pre(v, P.in[6], mod + mr * 9216 + 0, mod + mr * 9216 + 1024, H + (size_t)row * 1024, lane);
.Lp1n17_start:
	global_load_dwordx4 v[48:51], v32, s[48:49]
	global_load_dwordx4 v[52:55], v32, s[48:49] offset:1024
	global_load_dwordx4 v[56:59], v32, s[48:49] offset:2048
	global_load_dwordx4 v[60:63], v32, s[48:49] offset:3072
	s_mov_b32 s10, 0
	s_add_u32 s12, s2, s10
	s_addc_u32 s13, s3, 0
	s_add_u32 s14, s12, 0x1000
	s_addc_u32 s15, s13, 0
	global_load_dwordx4 v[80:83], v32, s[12:13]
	global_load_dwordx4 v[84:87], v32, s[12:13] offset:1024
	global_load_dwordx4 v[88:91], v32, s[12:13] offset:2048
	global_load_dwordx4 v[92:95], v32, s[12:13] offset:3072
	global_load_dwordx4 v[64:67], v32, s[14:15]
	global_load_dwordx4 v[68:71], v32, s[14:15] offset:1024
	global_load_dwordx4 v[72:75], v32, s[14:15] offset:2048
	global_load_dwordx4 v[76:79], v32, s[14:15] offset:3072
	global_load_dwordx4 v[112:115], v32, s[6:7]
	global_load_dwordx4 v[116:119], v32, s[6:7] offset:1024
	global_load_dwordx4 v[120:123], v32, s[6:7] offset:2048
	global_load_dwordx4 v[124:127], v32, s[6:7] offset:3072
	s_add_u32 s6, s6, 0x800000
	s_addc_u32 s7, s7, 0
	global_load_dwordx4 v[128:131], v32, s[6:7]
	global_load_dwordx4 v[132:135], v32, s[6:7] offset:1024
	global_load_dwordx4 v[136:139], v32, s[6:7] offset:2048
	global_load_dwordx4 v[140:143], v32, s[6:7] offset:3072
	s_add_u32 s6, s6, 0x800000
	s_addc_u32 s7, s7, 0
	global_load_dwordx4 v[144:147], v32, s[6:7]
	global_load_dwordx4 v[148:151], v32, s[6:7] offset:1024
	global_load_dwordx4 v[152:155], v32, s[6:7] offset:2048
	global_load_dwordx4 v[156:159], v32, s[6:7] offset:3072
	s_waitcnt vmcnt(8)
	v_pk_add_f32 v[64:65], v[64:65], 1.0 op_sel_hi:[1,0]
	v_pk_add_f32 v[66:67], v[66:67], 1.0 op_sel_hi:[1,0]
	v_pk_add_f32 v[68:69], v[68:69], 1.0 op_sel_hi:[1,0]
	v_pk_add_f32 v[70:71], v[70:71], 1.0 op_sel_hi:[1,0]
	v_pk_add_f32 v[72:73], v[72:73], 1.0 op_sel_hi:[1,0]
	v_pk_add_f32 v[74:75], v[74:75], 1.0 op_sel_hi:[1,0]
	v_pk_add_f32 v[76:77], v[76:77], 1.0 op_sel_hi:[1,0]
	v_pk_add_f32 v[78:79], v[78:79], 1.0 op_sel_hi:[1,0]
	v_pk_mul_f32 v[96:97], v[112:113], v[112:113]
	v_pk_fma_f32 v[96:97], v[114:115], v[114:115], v[96:97]
	v_pk_fma_f32 v[96:97], v[116:117], v[116:117], v[96:97]
	v_pk_fma_f32 v[96:97], v[118:119], v[118:119], v[96:97]
	v_pk_fma_f32 v[96:97], v[120:121], v[120:121], v[96:97]
	v_pk_fma_f32 v[96:97], v[122:123], v[122:123], v[96:97]
	v_pk_fma_f32 v[96:97], v[124:125], v[124:125], v[96:97]
	v_pk_fma_f32 v[96:97], v[126:127], v[126:127], v[96:97]
	v_add_f32_e32 v96, v96, v97
	s_nop 1
	v_add_f32_dpp v97, v96, v96 quad_perm:[1,0,3,2] row_mask:0xf bank_mask:0xf
	s_nop 1
	v_add_f32_dpp v96, v97, v97 quad_perm:[2,3,0,1] row_mask:0xf bank_mask:0xf
	s_nop 1
	v_add_f32_dpp v97, v96, v96 row_half_mirror row_mask:0xf bank_mask:0xf
	s_nop 1
	v_add_f32_dpp v96, v97, v97 row_mirror row_mask:0xf bank_mask:0xf
	s_nop 1
	v_readlane_b32 s16, v96, 0
	v_readlane_b32 s17, v96, 16
	v_readlane_b32 s18, v96, 32
	v_readlane_b32 s19, v96, 48
	s_nop 1
	v_mov_b32_e32 v96, s16
	v_add_f32_e32 v96, s17, v96
	v_add_f32_e32 v96, s18, v96
	v_add_f32_e32 v96, s19, v96
	v_mov_b32_e32 v98, 0x358637bd
	v_fmamk_f32 v96, v96, 0x3a800000, v98
	v_rsq_f32_e32 v96, v96
	s_nop 0
	v_pk_mul_f32 v[112:113], v[112:113], v[96:97] op_sel_hi:[1,0]
	v_pk_mul_f32 v[114:115], v[114:115], v[96:97] op_sel_hi:[1,0]
	v_pk_mul_f32 v[116:117], v[116:117], v[96:97] op_sel_hi:[1,0]
	v_pk_mul_f32 v[118:119], v[118:119], v[96:97] op_sel_hi:[1,0]
	v_pk_mul_f32 v[120:121], v[120:121], v[96:97] op_sel_hi:[1,0]
	v_pk_mul_f32 v[122:123], v[122:123], v[96:97] op_sel_hi:[1,0]
	v_pk_mul_f32 v[124:125], v[124:125], v[96:97] op_sel_hi:[1,0]
	v_pk_mul_f32 v[126:127], v[126:127], v[96:97] op_sel_hi:[1,0]
	v_pk_mul_f32 v[112:113], v[48:49], v[112:113]
	v_pk_mul_f32 v[114:115], v[50:51], v[114:115]
	v_pk_mul_f32 v[116:117], v[52:53], v[116:117]
	v_pk_mul_f32 v[118:119], v[54:55], v[118:119]
	v_pk_mul_f32 v[120:121], v[56:57], v[120:121]
	v_pk_mul_f32 v[122:123], v[58:59], v[122:123]
	v_pk_mul_f32 v[124:125], v[60:61], v[124:125]
	v_pk_mul_f32 v[126:127], v[62:63], v[126:127]
	v_pk_fma_f32 v[112:113], v[64:65], v[112:113], v[80:81]
	v_pk_fma_f32 v[114:115], v[66:67], v[114:115], v[82:83]
	v_pk_fma_f32 v[116:117], v[68:69], v[116:117], v[84:85]
	v_pk_fma_f32 v[118:119], v[70:71], v[118:119], v[86:87]
	v_pk_fma_f32 v[120:121], v[72:73], v[120:121], v[88:89]
	v_pk_fma_f32 v[122:123], v[74:75], v[122:123], v[90:91]
	v_pk_fma_f32 v[124:125], v[76:77], v[124:125], v[92:93]
	v_pk_fma_f32 v[126:127], v[78:79], v[126:127], v[94:95]
	v_cvt_pk_bf16_f32 v100, v112, v113
	v_cvt_pk_bf16_f32 v101, v114, v115
	v_cvt_pk_bf16_f32 v102, v116, v117
	v_cvt_pk_bf16_f32 v103, v118, v119
	v_cvt_pk_bf16_f32 v104, v120, v121
	v_cvt_pk_bf16_f32 v105, v122, v123
	v_cvt_pk_bf16_f32 v106, v124, v125
	v_cvt_pk_bf16_f32 v107, v126, v127
	global_store_dwordx2 v33, v[100:101], s[8:9]
	global_store_dwordx2 v33, v[102:103], s[8:9] offset:512
	global_store_dwordx2 v33, v[104:105], s[8:9] offset:1024
	global_store_dwordx2 v33, v[106:107], s[8:9] offset:1536
	s_add_u32 s6, s6, 0x800000
	s_addc_u32 s7, s7, 0
	global_load_dwordx4 v[112:115], v32, s[6:7]
	global_load_dwordx4 v[116:119], v32, s[6:7] offset:1024
	global_load_dwordx4 v[120:123], v32, s[6:7] offset:2048
	global_load_dwordx4 v[124:127], v32, s[6:7] offset:3072
	s_waitcnt vmcnt(12)
; __device__ __forceinline__ void store_bf4(bf16_t* p, f32x4 v) { uint2 o; o.x = pk2(v[0], v[1]); o.y = pk2(v[2], v[3]); *(uint2*)p = o; }
; __device__ __forceinline__ void norm_row_pre(const f32x4 (&v)[4], const float* __restrict__ g, const float* __restrict__ shift, const float* __restrict__ scale, bf16_t* __restrict__ dst, int lane) {
;     float ss = 0.f;
; #pragma unroll
;     for (int j = 0; j < 4; ++j) ss += v[j][0] * v[j][0] + v[j][1] * v[j][1] + v[j][2] * v[j][2] + v[j][3] * v[j][3];
;     ss = wave_sum(ss);
;     const float rstd = rsqrtf(ss * (1.f / 1024.f) + 1e-6f);
; #pragma unroll
;     for (int j = 0; j < 4; ++j) {
;         const int c4 = lane + 64 * j;
;         const f32x4 g4 = ((const f32x4*)g)[c4], sh = ((const f32x4*)shift)[c4], sc = ((const f32x4*)scale)[c4];
;         f32x4 h = (v[j] * rstd) * g4; h = h * (sc + 1.f) + sh;
;         store_bf4(dst + c4 * 4, h);
;     }
; }
; __device__ __forceinline__ void phase1(const Params& P) {
;     ...
;         const int stride = gridDim.x * 8;
;         int row = blockIdx.x * 8 + w;
;         f32x4 vn[4];
;         if (row < NT) { const float* src = row < NL ? P.in[0] + (size_t)row * 1024 : P.in[2] + (size_t)(row - NL) * 1024;
; #pragma unroll
;             for (int j = 0; j < 4; ++j) vn[j] = ((const f32x4*)src)[lane + 64 * j]; }
;         while (row < NT) {
;             f32x4 v[4];
; #pragma unroll
;             for (int j = 0; j < 4; ++j) v[j] = vn[j];
;             const int nrow = row + stride;
;             if (nrow < NT) { const float* src = nrow < NL ? P.in[0] + (size_t)nrow * 1024 : P.in[2] + (size_t)(nrow - NL) * 1024;
; #pragma unroll
;                 for (int j = 0; j < 4; ++j) vn[j] = ((const f32x4*)src)[lane + 64 * j]; }
;             const int mr = row < NL ? (row >> 13) : 4;
;             norm_row_pre(v, P.in[6], mod + mr * 9216 + 0, mod + mr * 9216 + 1024, H + (size_t)row * 1024, lane);
;             if (row >= NL) {
; #pragma unroll
;                 for (int j = 0; j < 4; ++j) ((f32x4*)((float*)(P.ws + OFF_E) + (size_t)(row - NL) * 1024))[lane + 64 * j] = v[j];
;             }
;             row = nrow;
;         }
	v_pk_mul_f32 v[96:97], v[128:129], v[128:129]
	v_pk_fma_f32 v[96:97], v[130:131], v[130:131], v[96:97]
	v_pk_fma_f32 v[96:97], v[132:133], v[132:133], v[96:97]
	v_pk_fma_f32 v[96:97], v[134:135], v[134:135], v[96:97]
	v_pk_fma_f32 v[96:97], v[136:137], v[136:137], v[96:97]
	v_pk_fma_f32 v[96:97], v[138:139], v[138:139], v[96:97]
	v_pk_fma_f32 v[96:97], v[140:141], v[140:141], v[96:97]
	v_pk_fma_f32 v[96:97], v[142:143], v[142:143], v[96:97]
	v_add_f32_e32 v96, v96, v97
	s_nop 1
	v_add_f32_dpp v97, v96, v96 quad_perm:[1,0,3,2] row_mask:0xf bank_mask:0xf
	s_nop 1
	v_add_f32_dpp v96, v97, v97 quad_perm:[2,3,0,1] row_mask:0xf bank_mask:0xf
	s_nop 1
	v_add_f32_dpp v97, v96, v96 row_half_mirror row_mask:0xf bank_mask:0xf
	s_nop 1
	v_add_f32_dpp v96, v97, v97 row_mirror row_mask:0xf bank_mask:0xf
	s_nop 1
	v_readlane_b32 s16, v96, 0
	v_readlane_b32 s17, v96, 16
	v_readlane_b32 s18, v96, 32
	v_readlane_b32 s19, v96, 48
	s_nop 1
	v_mov_b32_e32 v96, s16
	v_add_f32_e32 v96, s17, v96
	v_add_f32_e32 v96, s18, v96
	v_add_f32_e32 v96, s19, v96
	v_mov_b32_e32 v98, 0x358637bd
	v_fmamk_f32 v96, v96, 0x3a800000, v98
	v_rsq_f32_e32 v96, v96
	s_nop 0
	v_pk_mul_f32 v[128:129], v[128:129], v[96:97] op_sel_hi:[1,0]
	v_pk_mul_f32 v[130:131], v[130:131], v[96:97] op_sel_hi:[1,0]
	v_pk_mul_f32 v[132:133], v[132:133], v[96:97] op_sel_hi:[1,0]
	v_pk_mul_f32 v[134:135], v[134:135], v[96:97] op_sel_hi:[1,0]
	v_pk_mul_f32 v[136:137], v[136:137], v[96:97] op_sel_hi:[1,0]
	v_pk_mul_f32 v[138:139], v[138:139], v[96:97] op_sel_hi:[1,0]
	v_pk_mul_f32 v[140:141], v[140:141], v[96:97] op_sel_hi:[1,0]
	v_pk_mul_f32 v[142:143], v[142:143], v[96:97] op_sel_hi:[1,0]
	v_pk_mul_f32 v[128:129], v[48:49], v[128:129]
	v_pk_mul_f32 v[130:131], v[50:51], v[130:131]
	v_pk_mul_f32 v[132:133], v[52:53], v[132:133]
	v_pk_mul_f32 v[134:135], v[54:55], v[134:135]
	v_pk_mul_f32 v[136:137], v[56:57], v[136:137]
	v_pk_mul_f32 v[138:139], v[58:59], v[138:139]
	v_pk_mul_f32 v[140:141], v[60:61], v[140:141]
	v_pk_mul_f32 v[142:143], v[62:63], v[142:143]
	v_pk_fma_f32 v[128:129], v[64:65], v[128:129], v[80:81]
	v_pk_fma_f32 v[130:131], v[66:67], v[130:131], v[82:83]
	v_pk_fma_f32 v[132:133], v[68:69], v[132:133], v[84:85]
	v_pk_fma_f32 v[134:135], v[70:71], v[134:135], v[86:87]
	v_pk_fma_f32 v[136:137], v[72:73], v[136:137], v[88:89]
	v_pk_fma_f32 v[138:139], v[74:75], v[138:139], v[90:91]
	v_pk_fma_f32 v[140:141], v[76:77], v[140:141], v[92:93]
	v_pk_fma_f32 v[142:143], v[78:79], v[142:143], v[94:95]
	v_cvt_pk_bf16_f32 v100, v128, v129
	v_cvt_pk_bf16_f32 v101, v130, v131
	v_cvt_pk_bf16_f32 v102, v132, v133
	v_cvt_pk_bf16_f32 v103, v134, v135
	v_cvt_pk_bf16_f32 v104, v136, v137
	v_cvt_pk_bf16_f32 v105, v138, v139
	v_cvt_pk_bf16_f32 v106, v140, v141
	v_cvt_pk_bf16_f32 v107, v142, v143
	s_add_u32 s8, s8, 0x400000
	s_addc_u32 s9, s9, 0
	global_store_dwordx2 v33, v[100:101], s[8:9]
	global_store_dwordx2 v33, v[102:103], s[8:9] offset:512
	global_store_dwordx2 v33, v[104:105], s[8:9] offset:1024
	global_store_dwordx2 v33, v[106:107], s[8:9] offset:1536
	s_add_u32 s6, s6, 0x800000
	s_addc_u32 s7, s7, 0
	global_load_dwordx4 v[128:131], v32, s[6:7]
	global_load_dwordx4 v[132:135], v32, s[6:7] offset:1024
	global_load_dwordx4 v[136:139], v32, s[6:7] offset:2048
	global_load_dwordx4 v[140:143], v32, s[6:7] offset:3072
	s_mov_b32 s10, 36864
	s_add_u32 s12, s2, s10
	s_addc_u32 s13, s3, 0
	s_add_u32 s14, s12, 0x1000
	s_addc_u32 s15, s13, 0
	global_load_dwordx4 v[192:195], v32, s[12:13]
	global_load_dwordx4 v[196:199], v32, s[12:13] offset:1024
	global_load_dwordx4 v[200:203], v32, s[12:13] offset:2048
	global_load_dwordx4 v[204:207], v32, s[12:13] offset:3072
	global_load_dwordx4 v[176:179], v32, s[14:15]
	global_load_dwordx4 v[180:183], v32, s[14:15] offset:1024
	global_load_dwordx4 v[184:187], v32, s[14:15] offset:2048
	global_load_dwordx4 v[188:191], v32, s[14:15] offset:3072
	s_waitcnt vmcnt(24)
	v_pk_mul_f32 v[96:97], v[144:145], v[144:145]
	v_pk_fma_f32 v[96:97], v[146:147], v[146:147], v[96:97]
	v_pk_fma_f32 v[96:97], v[148:149], v[148:149], v[96:97]
	v_pk_fma_f32 v[96:97], v[150:151], v[150:151], v[96:97]
	v_pk_fma_f32 v[96:97], v[152:153], v[152:153], v[96:97]
	v_pk_fma_f32 v[96:97], v[154:155], v[154:155], v[96:97]
	v_pk_fma_f32 v[96:97], v[156:157], v[156:157], v[96:97]
	v_pk_fma_f32 v[96:97], v[158:159], v[158:159], v[96:97]
	v_add_f32_e32 v96, v96, v97
	s_nop 1
	v_add_f32_dpp v97, v96, v96 quad_perm:[1,0,3,2] row_mask:0xf bank_mask:0xf
	s_nop 1
	v_add_f32_dpp v96, v97, v97 quad_perm:[2,3,0,1] row_mask:0xf bank_mask:0xf
	s_nop 1
	v_add_f32_dpp v97, v96, v96 row_half_mirror row_mask:0xf bank_mask:0xf
	s_nop 1
	v_add_f32_dpp v96, v97, v97 row_mirror row_mask:0xf bank_mask:0xf
	s_nop 1
	v_readlane_b32 s16, v96, 0
	v_readlane_b32 s17, v96, 16
	v_readlane_b32 s18, v96, 32
	v_readlane_b32 s19, v96, 48
	s_nop 1
	v_mov_b32_e32 v96, s16
	v_add_f32_e32 v96, s17, v96
	v_add_f32_e32 v96, s18, v96
	v_add_f32_e32 v96, s19, v96
	v_mov_b32_e32 v98, 0x358637bd
	v_fmamk_f32 v96, v96, 0x3a800000, v98
	v_rsq_f32_e32 v96, v96
	s_nop 0
	v_pk_mul_f32 v[144:145], v[144:145], v[96:97] op_sel_hi:[1,0]
	v_pk_mul_f32 v[146:147], v[146:147], v[96:97] op_sel_hi:[1,0]
	v_pk_mul_f32 v[148:149], v[148:149], v[96:97] op_sel_hi:[1,0]
	v_pk_mul_f32 v[150:151], v[150:151], v[96:97] op_sel_hi:[1,0]
	v_pk_mul_f32 v[152:153], v[152:153], v[96:97] op_sel_hi:[1,0]
	v_pk_mul_f32 v[154:155], v[154:155], v[96:97] op_sel_hi:[1,0]
	v_pk_mul_f32 v[156:157], v[156:157], v[96:97] op_sel_hi:[1,0]
	v_pk_mul_f32 v[158:159], v[158:159], v[96:97] op_sel_hi:[1,0]
	v_pk_mul_f32 v[144:145], v[48:49], v[144:145]
	v_pk_mul_f32 v[146:147], v[50:51], v[146:147]
; __device__ __forceinline__ void store_bf4(bf16_t* p, f32x4 v) { uint2 o; o.x = pk2(v[0], v[1]); o.y = pk2(v[2], v[3]); *(uint2*)p = o; }
; __device__ __forceinline__ void norm_row_pre(const f32x4 (&v)[4], const float* __restrict__ g, const float* __restrict__ shift, const float* __restrict__ scale, bf16_t* __restrict__ dst, int lane) {
;     float ss = 0.f;
; #pragma unroll
;     for (int j = 0; j < 4; ++j) ss += v[j][0] * v[j][0] + v[j][1] * v[j][1] + v[j][2] * v[j][2] + v[j][3] * v[j][3];
;     ss = wave_sum(ss);
;     const float rstd = rsqrtf(ss * (1.f / 1024.f) + 1e-6f);
; #pragma unroll
;     for (int j = 0; j < 4; ++j) {
;         const int c4 = lane + 64 * j;
;         const f32x4 g4 = ((const f32x4*)g)[c4], sh = ((const f32x4*)shift)[c4], sc = ((const f32x4*)scale)[c4];
;         f32x4 h = (v[j] * rstd) * g4; h = h * (sc + 1.f) + sh;
;         store_bf4(dst + c4 * 4, h);
;     }
; }
; __device__ __forceinline__ void phase1(const Params& P) {
;     ...
;         const int stride = gridDim.x * 8;
;         int row = blockIdx.x * 8 + w;
;         f32x4 vn[4];
;         if (row < NT) { const float* src = row < NL ? P.in[0] + (size_t)row * 1024 : P.in[2] + (size_t)(row - NL) * 1024;
; #pragma unroll
;             for (int j = 0; j < 4; ++j) vn[j] = ((const f32x4*)src)[lane + 64 * j]; }
;         while (row < NT) {
;             f32x4 v[4];
; #pragma unroll
;             for (int j = 0; j < 4; ++j) v[j] = vn[j];
;             const int nrow = row + stride;
;             if (nrow < NT) { const float* src = nrow < NL ? P.in[0] + (size_t)nrow * 1024 : P.in[2] + (size_t)(nrow - NL) * 1024;
; #pragma unroll
;                 for (int j = 0; j < 4; ++j) vn[j] = ((const f32x4*)src)[lane + 64 * j]; }
;             const int mr = row < NL ? (row >> 13) : 4;
;             norm_row_pre(v, P.in[6], mod + mr * 9216 + 0, mod + mr * 9216 + 1024, H + (size_t)row * 1024, lane);
;             if (row >= NL) {
; #pragma unroll
;                 for (int j = 0; j < 4; ++j) ((f32x4*)((float*)(P.ws + OFF_E) + (size_t)(row - NL) * 1024))[lane + 64 * j] = v[j];
;             }
;             row = nrow;
;         }
	v_pk_mul_f32 v[148:149], v[52:53], v[148:149]
	v_pk_mul_f32 v[150:151], v[54:55], v[150:151]
	v_pk_mul_f32 v[152:153], v[56:57], v[152:153]
	v_pk_mul_f32 v[154:155], v[58:59], v[154:155]
	v_pk_mul_f32 v[156:157], v[60:61], v[156:157]
	v_pk_mul_f32 v[158:159], v[62:63], v[158:159]
	v_pk_fma_f32 v[144:145], v[64:65], v[144:145], v[80:81]
	v_pk_fma_f32 v[146:147], v[66:67], v[146:147], v[82:83]
	v_pk_fma_f32 v[148:149], v[68:69], v[148:149], v[84:85]
	v_pk_fma_f32 v[150:151], v[70:71], v[150:151], v[86:87]
	v_pk_fma_f32 v[152:153], v[72:73], v[152:153], v[88:89]
	v_pk_fma_f32 v[154:155], v[74:75], v[154:155], v[90:91]
	v_pk_fma_f32 v[156:157], v[76:77], v[156:157], v[92:93]
	v_pk_fma_f32 v[158:159], v[78:79], v[158:159], v[94:95]
	v_cvt_pk_bf16_f32 v100, v144, v145
	v_cvt_pk_bf16_f32 v101, v146, v147
	v_cvt_pk_bf16_f32 v102, v148, v149
	v_cvt_pk_bf16_f32 v103, v150, v151
	v_cvt_pk_bf16_f32 v104, v152, v153
	v_cvt_pk_bf16_f32 v105, v154, v155
	v_cvt_pk_bf16_f32 v106, v156, v157
	v_cvt_pk_bf16_f32 v107, v158, v159
	s_add_u32 s8, s8, 0x400000
	s_addc_u32 s9, s9, 0
	global_store_dwordx2 v33, v[100:101], s[8:9]
	global_store_dwordx2 v33, v[102:103], s[8:9] offset:512
	global_store_dwordx2 v33, v[104:105], s[8:9] offset:1024
	global_store_dwordx2 v33, v[106:107], s[8:9] offset:1536
	s_add_u32 s6, s6, 0x800000
	s_addc_u32 s7, s7, 0
	global_load_dwordx4 v[144:147], v32, s[6:7]
	global_load_dwordx4 v[148:151], v32, s[6:7] offset:1024
	global_load_dwordx4 v[152:155], v32, s[6:7] offset:2048
	global_load_dwordx4 v[156:159], v32, s[6:7] offset:3072
	s_waitcnt vmcnt(24)
	v_pk_mul_f32 v[96:97], v[112:113], v[112:113]
	v_pk_fma_f32 v[96:97], v[114:115], v[114:115], v[96:97]
	v_pk_fma_f32 v[96:97], v[116:117], v[116:117], v[96:97]
	v_pk_fma_f32 v[96:97], v[118:119], v[118:119], v[96:97]
	v_pk_fma_f32 v[96:97], v[120:121], v[120:121], v[96:97]
	v_pk_fma_f32 v[96:97], v[122:123], v[122:123], v[96:97]
	v_pk_fma_f32 v[96:97], v[124:125], v[124:125], v[96:97]
	v_pk_fma_f32 v[96:97], v[126:127], v[126:127], v[96:97]
	v_add_f32_e32 v96, v96, v97
	s_nop 1
	v_add_f32_dpp v97, v96, v96 quad_perm:[1,0,3,2] row_mask:0xf bank_mask:0xf
	s_nop 1
	v_add_f32_dpp v96, v97, v97 quad_perm:[2,3,0,1] row_mask:0xf bank_mask:0xf
	s_nop 1
	v_add_f32_dpp v97, v96, v96 row_half_mirror row_mask:0xf bank_mask:0xf
	s_nop 1
	v_add_f32_dpp v96, v97, v97 row_mirror row_mask:0xf bank_mask:0xf
	s_nop 1
	v_readlane_b32 s16, v96, 0
	v_readlane_b32 s17, v96, 16
	v_readlane_b32 s18, v96, 32
	v_readlane_b32 s19, v96, 48
	s_nop 1
	v_mov_b32_e32 v96, s16
	v_add_f32_e32 v96, s17, v96
	v_add_f32_e32 v96, s18, v96
	v_add_f32_e32 v96, s19, v96
	v_mov_b32_e32 v98, 0x358637bd
	v_fmamk_f32 v96, v96, 0x3a800000, v98
	v_rsq_f32_e32 v96, v96
	s_nop 0
	v_pk_mul_f32 v[112:113], v[112:113], v[96:97] op_sel_hi:[1,0]
	v_pk_mul_f32 v[114:115], v[114:115], v[96:97] op_sel_hi:[1,0]
	v_pk_mul_f32 v[116:117], v[116:117], v[96:97] op_sel_hi:[1,0]
	v_pk_mul_f32 v[118:119], v[118:119], v[96:97] op_sel_hi:[1,0]
	v_pk_mul_f32 v[120:121], v[120:121], v[96:97] op_sel_hi:[1,0]
	v_pk_mul_f32 v[122:123], v[122:123], v[96:97] op_sel_hi:[1,0]
	v_pk_mul_f32 v[124:125], v[124:125], v[96:97] op_sel_hi:[1,0]
	v_pk_mul_f32 v[126:127], v[126:127], v[96:97] op_sel_hi:[1,0]
	v_pk_mul_f32 v[112:113], v[48:49], v[112:113]
	v_pk_mul_f32 v[114:115], v[50:51], v[114:115]
	v_pk_mul_f32 v[116:117], v[52:53], v[116:117]
	v_pk_mul_f32 v[118:119], v[54:55], v[118:119]
	v_pk_mul_f32 v[120:121], v[56:57], v[120:121]
	v_pk_mul_f32 v[122:123], v[58:59], v[122:123]
	v_pk_mul_f32 v[124:125], v[60:61], v[124:125]
	v_pk_mul_f32 v[126:127], v[62:63], v[126:127]
	v_pk_fma_f32 v[112:113], v[64:65], v[112:113], v[80:81]
	v_pk_fma_f32 v[114:115], v[66:67], v[114:115], v[82:83]
	v_pk_fma_f32 v[116:117], v[68:69], v[116:117], v[84:85]
	v_pk_fma_f32 v[118:119], v[70:71], v[118:119], v[86:87]
	v_pk_fma_f32 v[120:121], v[72:73], v[120:121], v[88:89]
	v_pk_fma_f32 v[122:123], v[74:75], v[122:123], v[90:91]
	v_pk_fma_f32 v[124:125], v[76:77], v[124:125], v[92:93]
	v_pk_fma_f32 v[126:127], v[78:79], v[126:127], v[94:95]
	v_cvt_pk_bf16_f32 v100, v112, v113
	v_cvt_pk_bf16_f32 v101, v114, v115
	v_cvt_pk_bf16_f32 v102, v116, v117
	v_cvt_pk_bf16_f32 v103, v118, v119
	v_cvt_pk_bf16_f32 v104, v120, v121
	v_cvt_pk_bf16_f32 v105, v122, v123
	v_cvt_pk_bf16_f32 v106, v124, v125
	v_cvt_pk_bf16_f32 v107, v126, v127
	s_add_u32 s8, s8, 0x400000
	s_addc_u32 s9, s9, 0
	global_store_dwordx2 v33, v[100:101], s[8:9]
	global_store_dwordx2 v33, v[102:103], s[8:9] offset:512
	global_store_dwordx2 v33, v[104:105], s[8:9] offset:1024
	global_store_dwordx2 v33, v[106:107], s[8:9] offset:1536
	s_add_u32 s6, s6, 0x800000
	s_addc_u32 s7, s7, 0
	global_load_dwordx4 v[112:115], v32, s[6:7]
	global_load_dwordx4 v[116:119], v32, s[6:7] offset:1024
	global_load_dwordx4 v[120:123], v32, s[6:7] offset:2048
	global_load_dwordx4 v[124:127], v32, s[6:7] offset:3072
	s_waitcnt vmcnt(16)
; __device__ __forceinline__ void store_bf4(bf16_t* p, f32x4 v) { uint2 o; o.x = pk2(v[0], v[1]); o.y = pk2(v[2], v[3]); *(uint2*)p = o; }
; __device__ __forceinline__ void norm_row_pre(const f32x4 (&v)[4], const float* __restrict__ g, const float* __restrict__ shift, const float* __restrict__ scale, bf16_t* __restrict__ dst, int lane) {
;     float ss = 0.f;
; #pragma unroll
;     for (int j = 0; j < 4; ++j) ss += v[j][0] * v[j][0] + v[j][1] * v[j][1] + v[j][2] * v[j][2] + v[j][3] * v[j][3];
;     ss = wave_sum(ss);
;     const float rstd = rsqrtf(ss * (1.f / 1024.f) + 1e-6f);
; #pragma unroll
;     for (int j = 0; j < 4; ++j) {
;         const int c4 = lane + 64 * j;
;         const f32x4 g4 = ((const f32x4*)g)[c4], sh = ((const f32x4*)shift)[c4], sc = ((const f32x4*)scale)[c4];
;         f32x4 h = (v[j] * rstd) * g4; h = h * (sc + 1.f) + sh;
;         store_bf4(dst + c4 * 4, h);
;     }
; }
; __device__ __forceinline__ void phase1(const Params& P) {
;     ...
;         const int stride = gridDim.x * 8;
;         int row = blockIdx.x * 8 + w;
;         f32x4 vn[4];
;         if (row < NT) { const float* src = row < NL ? P.in[0] + (size_t)row * 1024 : P.in[2] + (size_t)(row - NL) * 1024;
; #pragma unroll
;             for (int j = 0; j < 4; ++j) vn[j] = ((const f32x4*)src)[lane + 64 * j]; }
;         while (row < NT) {
;             f32x4 v[4];
; #pragma unroll
;             for (int j = 0; j < 4; ++j) v[j] = vn[j];
;             const int nrow = row + stride;
;             if (nrow < NT) { const float* src = nrow < NL ? P.in[0] + (size_t)nrow * 1024 : P.in[2] + (size_t)(nrow - NL) * 1024;
; #pragma unroll
;                 for (int j = 0; j < 4; ++j) vn[j] = ((const f32x4*)src)[lane + 64 * j]; }
;             const int mr = row < NL ? (row >> 13) : 4;
;             norm_row_pre(v, P.in[6], mod + mr * 9216 + 0, mod + mr * 9216 + 1024, H + (size_t)row * 1024, lane);
;             if (row >= NL) {
; #pragma unroll
;                 for (int j = 0; j < 4; ++j) ((f32x4*)((float*)(P.ws + OFF_E) + (size_t)(row - NL) * 1024))[lane + 64 * j] = v[j];
;             }
;             row = nrow;
;         }
	v_pk_add_f32 v[176:177], v[176:177], 1.0 op_sel_hi:[1,0]
	v_pk_add_f32 v[178:179], v[178:179], 1.0 op_sel_hi:[1,0]
	v_pk_add_f32 v[180:181], v[180:181], 1.0 op_sel_hi:[1,0]
	v_pk_add_f32 v[182:183], v[182:183], 1.0 op_sel_hi:[1,0]
	v_pk_add_f32 v[184:185], v[184:185], 1.0 op_sel_hi:[1,0]
	v_pk_add_f32 v[186:187], v[186:187], 1.0 op_sel_hi:[1,0]
	v_pk_add_f32 v[188:189], v[188:189], 1.0 op_sel_hi:[1,0]
	v_pk_add_f32 v[190:191], v[190:191], 1.0 op_sel_hi:[1,0]
	v_pk_mul_f32 v[96:97], v[128:129], v[128:129]
	v_pk_fma_f32 v[96:97], v[130:131], v[130:131], v[96:97]
	v_pk_fma_f32 v[96:97], v[132:133], v[132:133], v[96:97]
	v_pk_fma_f32 v[96:97], v[134:135], v[134:135], v[96:97]
	v_pk_fma_f32 v[96:97], v[136:137], v[136:137], v[96:97]
	v_pk_fma_f32 v[96:97], v[138:139], v[138:139], v[96:97]
	v_pk_fma_f32 v[96:97], v[140:141], v[140:141], v[96:97]
	v_pk_fma_f32 v[96:97], v[142:143], v[142:143], v[96:97]
	v_add_f32_e32 v96, v96, v97
	s_nop 1
	v_add_f32_dpp v97, v96, v96 quad_perm:[1,0,3,2] row_mask:0xf bank_mask:0xf
	s_nop 1
	v_add_f32_dpp v96, v97, v97 quad_perm:[2,3,0,1] row_mask:0xf bank_mask:0xf
	s_nop 1
	v_add_f32_dpp v97, v96, v96 row_half_mirror row_mask:0xf bank_mask:0xf
	s_nop 1
	v_add_f32_dpp v96, v97, v97 row_mirror row_mask:0xf bank_mask:0xf
	s_nop 1
	v_readlane_b32 s16, v96, 0
	v_readlane_b32 s17, v96, 16
	v_readlane_b32 s18, v96, 32
	v_readlane_b32 s19, v96, 48
	s_nop 1
	v_mov_b32_e32 v96, s16
	v_add_f32_e32 v96, s17, v96
	v_add_f32_e32 v96, s18, v96
	v_add_f32_e32 v96, s19, v96
	v_mov_b32_e32 v98, 0x358637bd
	v_fmamk_f32 v96, v96, 0x3a800000, v98
	v_rsq_f32_e32 v96, v96
	s_nop 0
	v_pk_mul_f32 v[128:129], v[128:129], v[96:97] op_sel_hi:[1,0]
	v_pk_mul_f32 v[130:131], v[130:131], v[96:97] op_sel_hi:[1,0]
	v_pk_mul_f32 v[132:133], v[132:133], v[96:97] op_sel_hi:[1,0]
	v_pk_mul_f32 v[134:135], v[134:135], v[96:97] op_sel_hi:[1,0]
	v_pk_mul_f32 v[136:137], v[136:137], v[96:97] op_sel_hi:[1,0]
	v_pk_mul_f32 v[138:139], v[138:139], v[96:97] op_sel_hi:[1,0]
	v_pk_mul_f32 v[140:141], v[140:141], v[96:97] op_sel_hi:[1,0]
	v_pk_mul_f32 v[142:143], v[142:143], v[96:97] op_sel_hi:[1,0]
	v_pk_mul_f32 v[128:129], v[48:49], v[128:129]
	v_pk_mul_f32 v[130:131], v[50:51], v[130:131]
	v_pk_mul_f32 v[132:133], v[52:53], v[132:133]
	v_pk_mul_f32 v[134:135], v[54:55], v[134:135]
	v_pk_mul_f32 v[136:137], v[56:57], v[136:137]
	v_pk_mul_f32 v[138:139], v[58:59], v[138:139]
	v_pk_mul_f32 v[140:141], v[60:61], v[140:141]
	v_pk_mul_f32 v[142:143], v[62:63], v[142:143]
	v_pk_fma_f32 v[128:129], v[176:177], v[128:129], v[192:193]
	v_pk_fma_f32 v[130:131], v[178:179], v[130:131], v[194:195]
	v_pk_fma_f32 v[132:133], v[180:181], v[132:133], v[196:197]
	v_pk_fma_f32 v[134:135], v[182:183], v[134:135], v[198:199]
	v_pk_fma_f32 v[136:137], v[184:185], v[136:137], v[200:201]
	v_pk_fma_f32 v[138:139], v[186:187], v[138:139], v[202:203]
	v_pk_fma_f32 v[140:141], v[188:189], v[140:141], v[204:205]
	v_pk_fma_f32 v[142:143], v[190:191], v[142:143], v[206:207]
	v_cvt_pk_bf16_f32 v100, v128, v129
	v_cvt_pk_bf16_f32 v101, v130, v131
	v_cvt_pk_bf16_f32 v102, v132, v133
	v_cvt_pk_bf16_f32 v103, v134, v135
	v_cvt_pk_bf16_f32 v104, v136, v137
	v_cvt_pk_bf16_f32 v105, v138, v139
	v_cvt_pk_bf16_f32 v106, v140, v141
	v_cvt_pk_bf16_f32 v107, v142, v143
	s_add_u32 s8, s8, 0x400000
	s_addc_u32 s9, s9, 0
	global_store_dwordx2 v33, v[100:101], s[8:9]
	global_store_dwordx2 v33, v[102:103], s[8:9] offset:512
	global_store_dwordx2 v33, v[104:105], s[8:9] offset:1024
	global_store_dwordx2 v33, v[106:107], s[8:9] offset:1536
	s_add_u32 s6, s6, 0x800000
	s_addc_u32 s7, s7, 0
	global_load_dwordx4 v[128:131], v32, s[6:7]
	global_load_dwordx4 v[132:135], v32, s[6:7] offset:1024
	global_load_dwordx4 v[136:139], v32, s[6:7] offset:2048
	global_load_dwordx4 v[140:143], v32, s[6:7] offset:3072
	s_waitcnt vmcnt(16)
	v_pk_mul_f32 v[96:97], v[144:145], v[144:145]
	v_pk_fma_f32 v[96:97], v[146:147], v[146:147], v[96:97]
	v_pk_fma_f32 v[96:97], v[148:149], v[148:149], v[96:97]
	v_pk_fma_f32 v[96:97], v[150:151], v[150:151], v[96:97]
	v_pk_fma_f32 v[96:97], v[152:153], v[152:153], v[96:97]
	v_pk_fma_f32 v[96:97], v[154:155], v[154:155], v[96:97]
	v_pk_fma_f32 v[96:97], v[156:157], v[156:157], v[96:97]
	v_pk_fma_f32 v[96:97], v[158:159], v[158:159], v[96:97]
	v_add_f32_e32 v96, v96, v97
	s_nop 1
	v_add_f32_dpp v97, v96, v96 quad_perm:[1,0,3,2] row_mask:0xf bank_mask:0xf
	s_nop 1
	v_add_f32_dpp v96, v97, v97 quad_perm:[2,3,0,1] row_mask:0xf bank_mask:0xf
	s_nop 1
	v_add_f32_dpp v97, v96, v96 row_half_mirror row_mask:0xf bank_mask:0xf
	s_nop 1
	v_add_f32_dpp v96, v97, v97 row_mirror row_mask:0xf bank_mask:0xf
	s_nop 1
	v_readlane_b32 s16, v96, 0
	v_readlane_b32 s17, v96, 16
	v_readlane_b32 s18, v96, 32
	v_readlane_b32 s19, v96, 48
	s_nop 1
	v_mov_b32_e32 v96, s16
	v_add_f32_e32 v96, s17, v96
	v_add_f32_e32 v96, s18, v96
	v_add_f32_e32 v96, s19, v96
	v_mov_b32_e32 v98, 0x358637bd
	v_fmamk_f32 v96, v96, 0x3a800000, v98
	v_rsq_f32_e32 v96, v96
	s_nop 0
	v_pk_mul_f32 v[144:145], v[144:145], v[96:97] op_sel_hi:[1,0]
	v_pk_mul_f32 v[146:147], v[146:147], v[96:97] op_sel_hi:[1,0]
	v_pk_mul_f32 v[148:149], v[148:149], v[96:97] op_sel_hi:[1,0]
	v_pk_mul_f32 v[150:151], v[150:151], v[96:97] op_sel_hi:[1,0]
	v_pk_mul_f32 v[152:153], v[152:153], v[96:97] op_sel_hi:[1,0]
	v_pk_mul_f32 v[154:155], v[154:155], v[96:97] op_sel_hi:[1,0]
	v_pk_mul_f32 v[156:157], v[156:157], v[96:97] op_sel_hi:[1,0]
	v_pk_mul_f32 v[158:159], v[158:159], v[96:97] op_sel_hi:[1,0]
	v_pk_mul_f32 v[144:145], v[48:49], v[144:145]
	v_pk_mul_f32 v[146:147], v[50:51], v[146:147]
	v_pk_mul_f32 v[148:149], v[52:53], v[148:149]
; __device__ __forceinline__ void store_bf4(bf16_t* p, f32x4 v) { uint2 o; o.x = pk2(v[0], v[1]); o.y = pk2(v[2], v[3]); *(uint2*)p = o; }
; __device__ __forceinline__ void norm_row_pre(const f32x4 (&v)[4], const float* __restrict__ g, const float* __restrict__ shift, const float* __restrict__ scale, bf16_t* __restrict__ dst, int lane) {
;     float ss = 0.f;
; #pragma unroll
;     for (int j = 0; j < 4; ++j) ss += v[j][0] * v[j][0] + v[j][1] * v[j][1] + v[j][2] * v[j][2] + v[j][3] * v[j][3];
;     ss = wave_sum(ss);
;     const float rstd = rsqrtf(ss * (1.f / 1024.f) + 1e-6f);
; #pragma unroll
;     for (int j = 0; j < 4; ++j) {
;         const int c4 = lane + 64 * j;
;         const f32x4 g4 = ((const f32x4*)g)[c4], sh = ((const f32x4*)shift)[c4], sc = ((const f32x4*)scale)[c4];
;         f32x4 h = (v[j] * rstd) * g4; h = h * (sc + 1.f) + sh;
;         store_bf4(dst + c4 * 4, h);
;     }
; }
; __device__ __forceinline__ void phase1(const Params& P) {
;     ...
;         const int stride = gridDim.x * 8;
;         int row = blockIdx.x * 8 + w;
;         f32x4 vn[4];
;         if (row < NT) { const float* src = row < NL ? P.in[0] + (size_t)row * 1024 : P.in[2] + (size_t)(row - NL) * 1024;
; #pragma unroll
;             for (int j = 0; j < 4; ++j) vn[j] = ((const f32x4*)src)[lane + 64 * j]; }
;         while (row < NT) {
;             f32x4 v[4];
; #pragma unroll
;             for (int j = 0; j < 4; ++j) v[j] = vn[j];
;             const int nrow = row + stride;
;             if (nrow < NT) { const float* src = nrow < NL ? P.in[0] + (size_t)nrow * 1024 : P.in[2] + (size_t)(nrow - NL) * 1024;
; #pragma unroll
;                 for (int j = 0; j < 4; ++j) vn[j] = ((const f32x4*)src)[lane + 64 * j]; }
;             const int mr = row < NL ? (row >> 13) : 4;
;             norm_row_pre(v, P.in[6], mod + mr * 9216 + 0, mod + mr * 9216 + 1024, H + (size_t)row * 1024, lane);
;             if (row >= NL) {
; #pragma unroll
;                 for (int j = 0; j < 4; ++j) ((f32x4*)((float*)(P.ws + OFF_E) + (size_t)(row - NL) * 1024))[lane + 64 * j] = v[j];
;             }
;             row = nrow;
;         }
	v_pk_mul_f32 v[150:151], v[54:55], v[150:151]
	v_pk_mul_f32 v[152:153], v[56:57], v[152:153]
	v_pk_mul_f32 v[154:155], v[58:59], v[154:155]
	v_pk_mul_f32 v[156:157], v[60:61], v[156:157]
	v_pk_mul_f32 v[158:159], v[62:63], v[158:159]
	v_pk_fma_f32 v[144:145], v[176:177], v[144:145], v[192:193]
	v_pk_fma_f32 v[146:147], v[178:179], v[146:147], v[194:195]
	v_pk_fma_f32 v[148:149], v[180:181], v[148:149], v[196:197]
	v_pk_fma_f32 v[150:151], v[182:183], v[150:151], v[198:199]
	v_pk_fma_f32 v[152:153], v[184:185], v[152:153], v[200:201]
	v_pk_fma_f32 v[154:155], v[186:187], v[154:155], v[202:203]
	v_pk_fma_f32 v[156:157], v[188:189], v[156:157], v[204:205]
	v_pk_fma_f32 v[158:159], v[190:191], v[158:159], v[206:207]
	v_cvt_pk_bf16_f32 v100, v144, v145
	v_cvt_pk_bf16_f32 v101, v146, v147
	v_cvt_pk_bf16_f32 v102, v148, v149
	v_cvt_pk_bf16_f32 v103, v150, v151
	v_cvt_pk_bf16_f32 v104, v152, v153
	v_cvt_pk_bf16_f32 v105, v154, v155
	v_cvt_pk_bf16_f32 v106, v156, v157
	v_cvt_pk_bf16_f32 v107, v158, v159
	s_add_u32 s8, s8, 0x400000
	s_addc_u32 s9, s9, 0
	global_store_dwordx2 v33, v[100:101], s[8:9]
	global_store_dwordx2 v33, v[102:103], s[8:9] offset:512
	global_store_dwordx2 v33, v[104:105], s[8:9] offset:1024
	global_store_dwordx2 v33, v[106:107], s[8:9] offset:1536
	s_add_u32 s6, s6, 0x800000
	s_addc_u32 s7, s7, 0
	global_load_dwordx4 v[144:147], v32, s[6:7]
	global_load_dwordx4 v[148:151], v32, s[6:7] offset:1024
	global_load_dwordx4 v[152:155], v32, s[6:7] offset:2048
	global_load_dwordx4 v[156:159], v32, s[6:7] offset:3072
	s_mov_b32 s10, 73728
	s_add_u32 s12, s2, s10
	s_addc_u32 s13, s3, 0
	s_add_u32 s14, s12, 0x1000
	s_addc_u32 s15, s13, 0
	global_load_dwordx4 v[80:83], v32, s[12:13]
	global_load_dwordx4 v[84:87], v32, s[12:13] offset:1024
	global_load_dwordx4 v[88:91], v32, s[12:13] offset:2048
	global_load_dwordx4 v[92:95], v32, s[12:13] offset:3072
	global_load_dwordx4 v[64:67], v32, s[14:15]
	global_load_dwordx4 v[68:71], v32, s[14:15] offset:1024
	global_load_dwordx4 v[72:75], v32, s[14:15] offset:2048
	global_load_dwordx4 v[76:79], v32, s[14:15] offset:3072
	s_waitcnt vmcnt(24)
	v_pk_mul_f32 v[96:97], v[112:113], v[112:113]
	v_pk_fma_f32 v[96:97], v[114:115], v[114:115], v[96:97]
	v_pk_fma_f32 v[96:97], v[116:117], v[116:117], v[96:97]
	v_pk_fma_f32 v[96:97], v[118:119], v[118:119], v[96:97]
	v_pk_fma_f32 v[96:97], v[120:121], v[120:121], v[96:97]
	v_pk_fma_f32 v[96:97], v[122:123], v[122:123], v[96:97]
	v_pk_fma_f32 v[96:97], v[124:125], v[124:125], v[96:97]
	v_pk_fma_f32 v[96:97], v[126:127], v[126:127], v[96:97]
	v_add_f32_e32 v96, v96, v97
	s_nop 1
	v_add_f32_dpp v97, v96, v96 quad_perm:[1,0,3,2] row_mask:0xf bank_mask:0xf
	s_nop 1
	v_add_f32_dpp v96, v97, v97 quad_perm:[2,3,0,1] row_mask:0xf bank_mask:0xf
	s_nop 1
	v_add_f32_dpp v97, v96, v96 row_half_mirror row_mask:0xf bank_mask:0xf
	s_nop 1
	v_add_f32_dpp v96, v97, v97 row_mirror row_mask:0xf bank_mask:0xf
	s_nop 1
	v_readlane_b32 s16, v96, 0
	v_readlane_b32 s17, v96, 16
	v_readlane_b32 s18, v96, 32
	v_readlane_b32 s19, v96, 48
	s_nop 1
	v_mov_b32_e32 v96, s16
	v_add_f32_e32 v96, s17, v96
	v_add_f32_e32 v96, s18, v96
	v_add_f32_e32 v96, s19, v96
	v_mov_b32_e32 v98, 0x358637bd
	v_fmamk_f32 v96, v96, 0x3a800000, v98
	v_rsq_f32_e32 v96, v96
	s_nop 0
	v_pk_mul_f32 v[112:113], v[112:113], v[96:97] op_sel_hi:[1,0]
	v_pk_mul_f32 v[114:115], v[114:115], v[96:97] op_sel_hi:[1,0]
	v_pk_mul_f32 v[116:117], v[116:117], v[96:97] op_sel_hi:[1,0]
	v_pk_mul_f32 v[118:119], v[118:119], v[96:97] op_sel_hi:[1,0]
	v_pk_mul_f32 v[120:121], v[120:121], v[96:97] op_sel_hi:[1,0]
	v_pk_mul_f32 v[122:123], v[122:123], v[96:97] op_sel_hi:[1,0]
	v_pk_mul_f32 v[124:125], v[124:125], v[96:97] op_sel_hi:[1,0]
	v_pk_mul_f32 v[126:127], v[126:127], v[96:97] op_sel_hi:[1,0]
	v_pk_mul_f32 v[112:113], v[48:49], v[112:113]
	v_pk_mul_f32 v[114:115], v[50:51], v[114:115]
	v_pk_mul_f32 v[116:117], v[52:53], v[116:117]
	v_pk_mul_f32 v[118:119], v[54:55], v[118:119]
	v_pk_mul_f32 v[120:121], v[56:57], v[120:121]
	v_pk_mul_f32 v[122:123], v[58:59], v[122:123]
	v_pk_mul_f32 v[124:125], v[60:61], v[124:125]
	v_pk_mul_f32 v[126:127], v[62:63], v[126:127]
	v_pk_fma_f32 v[112:113], v[176:177], v[112:113], v[192:193]
	v_pk_fma_f32 v[114:115], v[178:179], v[114:115], v[194:195]
	v_pk_fma_f32 v[116:117], v[180:181], v[116:117], v[196:197]
	v_pk_fma_f32 v[118:119], v[182:183], v[118:119], v[198:199]
	v_pk_fma_f32 v[120:121], v[184:185], v[120:121], v[200:201]
	v_pk_fma_f32 v[122:123], v[186:187], v[122:123], v[202:203]
	v_pk_fma_f32 v[124:125], v[188:189], v[124:125], v[204:205]
	v_pk_fma_f32 v[126:127], v[190:191], v[126:127], v[206:207]
	v_cvt_pk_bf16_f32 v100, v112, v113
	v_cvt_pk_bf16_f32 v101, v114, v115
	v_cvt_pk_bf16_f32 v102, v116, v117
	v_cvt_pk_bf16_f32 v103, v118, v119
	v_cvt_pk_bf16_f32 v104, v120, v121
	v_cvt_pk_bf16_f32 v105, v122, v123
	v_cvt_pk_bf16_f32 v106, v124, v125
	v_cvt_pk_bf16_f32 v107, v126, v127
	s_add_u32 s8, s8, 0x400000
	s_addc_u32 s9, s9, 0
	global_store_dwordx2 v33, v[100:101], s[8:9]
	global_store_dwordx2 v33, v[102:103], s[8:9] offset:512
	global_store_dwordx2 v33, v[104:105], s[8:9] offset:1024
	global_store_dwordx2 v33, v[106:107], s[8:9] offset:1536
	s_add_u32 s6, s6, 0x800000
	s_addc_u32 s7, s7, 0
	global_load_dwordx4 v[112:115], v32, s[6:7]
	global_load_dwordx4 v[116:119], v32, s[6:7] offset:1024
	global_load_dwordx4 v[120:123], v32, s[6:7] offset:2048
	global_load_dwordx4 v[124:127], v32, s[6:7] offset:3072
	s_waitcnt vmcnt(24)
; __device__ __forceinline__ void store_bf4(bf16_t* p, f32x4 v) { uint2 o; o.x = pk2(v[0], v[1]); o.y = pk2(v[2], v[3]); *(uint2*)p = o; }
; __device__ __forceinline__ void norm_row_pre(const f32x4 (&v)[4], const float* __restrict__ g, const float* __restrict__ shift, const float* __restrict__ scale, bf16_t* __restrict__ dst, int lane) {
;     float ss = 0.f;
; #pragma unroll
;     for (int j = 0; j < 4; ++j) ss += v[j][0] * v[j][0] + v[j][1] * v[j][1] + v[j][2] * v[j][2] + v[j][3] * v[j][3];
;     ss = wave_sum(ss);
;     const float rstd = rsqrtf(ss * (1.f / 1024.f) + 1e-6f);
; #pragma unroll
;     for (int j = 0; j < 4; ++j) {
;         const int c4 = lane + 64 * j;
;         const f32x4 g4 = ((const f32x4*)g)[c4], sh = ((const f32x4*)shift)[c4], sc = ((const f32x4*)scale)[c4];
;         f32x4 h = (v[j] * rstd) * g4; h = h * (sc + 1.f) + sh;
;         store_bf4(dst + c4 * 4, h);
;     }
; }
; __device__ __forceinline__ void phase1(const Params& P) {
;     ...
;         const int stride = gridDim.x * 8;
;         int row = blockIdx.x * 8 + w;
;         f32x4 vn[4];
;         if (row < NT) { const float* src = row < NL ? P.in[0] + (size_t)row * 1024 : P.in[2] + (size_t)(row - NL) * 1024;
; #pragma unroll
;             for (int j = 0; j < 4; ++j) vn[j] = ((const f32x4*)src)[lane + 64 * j]; }
;         while (row < NT) {
;             f32x4 v[4];
; #pragma unroll
;             for (int j = 0; j < 4; ++j) v[j] = vn[j];
;             const int nrow = row + stride;
;             if (nrow < NT) { const float* src = nrow < NL ? P.in[0] + (size_t)nrow * 1024 : P.in[2] + (size_t)(nrow - NL) * 1024;
; #pragma unroll
;                 for (int j = 0; j < 4; ++j) vn[j] = ((const f32x4*)src)[lane + 64 * j]; }
;             const int mr = row < NL ? (row >> 13) : 4;
;             norm_row_pre(v, P.in[6], mod + mr * 9216 + 0, mod + mr * 9216 + 1024, H + (size_t)row * 1024, lane);
;             if (row >= NL) {
; #pragma unroll
;                 for (int j = 0; j < 4; ++j) ((f32x4*)((float*)(P.ws + OFF_E) + (size_t)(row - NL) * 1024))[lane + 64 * j] = v[j];
;             }
;             row = nrow;
;         }
	v_pk_mul_f32 v[96:97], v[128:129], v[128:129]
	v_pk_fma_f32 v[96:97], v[130:131], v[130:131], v[96:97]
	v_pk_fma_f32 v[96:97], v[132:133], v[132:133], v[96:97]
	v_pk_fma_f32 v[96:97], v[134:135], v[134:135], v[96:97]
	v_pk_fma_f32 v[96:97], v[136:137], v[136:137], v[96:97]
	v_pk_fma_f32 v[96:97], v[138:139], v[138:139], v[96:97]
	v_pk_fma_f32 v[96:97], v[140:141], v[140:141], v[96:97]
	v_pk_fma_f32 v[96:97], v[142:143], v[142:143], v[96:97]
	v_add_f32_e32 v96, v96, v97
	s_nop 1
	v_add_f32_dpp v97, v96, v96 quad_perm:[1,0,3,2] row_mask:0xf bank_mask:0xf
	s_nop 1
	v_add_f32_dpp v96, v97, v97 quad_perm:[2,3,0,1] row_mask:0xf bank_mask:0xf
	s_nop 1
	v_add_f32_dpp v97, v96, v96 row_half_mirror row_mask:0xf bank_mask:0xf
	s_nop 1
	v_add_f32_dpp v96, v97, v97 row_mirror row_mask:0xf bank_mask:0xf
	s_nop 1
	v_readlane_b32 s16, v96, 0
	v_readlane_b32 s17, v96, 16
	v_readlane_b32 s18, v96, 32
	v_readlane_b32 s19, v96, 48
	s_nop 1
	v_mov_b32_e32 v96, s16
	v_add_f32_e32 v96, s17, v96
	v_add_f32_e32 v96, s18, v96
	v_add_f32_e32 v96, s19, v96
	v_mov_b32_e32 v98, 0x358637bd
	v_fmamk_f32 v96, v96, 0x3a800000, v98
	v_rsq_f32_e32 v96, v96
	s_nop 0
	v_pk_mul_f32 v[128:129], v[128:129], v[96:97] op_sel_hi:[1,0]
	v_pk_mul_f32 v[130:131], v[130:131], v[96:97] op_sel_hi:[1,0]
	v_pk_mul_f32 v[132:133], v[132:133], v[96:97] op_sel_hi:[1,0]
	v_pk_mul_f32 v[134:135], v[134:135], v[96:97] op_sel_hi:[1,0]
	v_pk_mul_f32 v[136:137], v[136:137], v[96:97] op_sel_hi:[1,0]
	v_pk_mul_f32 v[138:139], v[138:139], v[96:97] op_sel_hi:[1,0]
	v_pk_mul_f32 v[140:141], v[140:141], v[96:97] op_sel_hi:[1,0]
	v_pk_mul_f32 v[142:143], v[142:143], v[96:97] op_sel_hi:[1,0]
	v_pk_mul_f32 v[128:129], v[48:49], v[128:129]
	v_pk_mul_f32 v[130:131], v[50:51], v[130:131]
	v_pk_mul_f32 v[132:133], v[52:53], v[132:133]
	v_pk_mul_f32 v[134:135], v[54:55], v[134:135]
	v_pk_mul_f32 v[136:137], v[56:57], v[136:137]
	v_pk_mul_f32 v[138:139], v[58:59], v[138:139]
	v_pk_mul_f32 v[140:141], v[60:61], v[140:141]
	v_pk_mul_f32 v[142:143], v[62:63], v[142:143]
	v_pk_fma_f32 v[128:129], v[176:177], v[128:129], v[192:193]
	v_pk_fma_f32 v[130:131], v[178:179], v[130:131], v[194:195]
	v_pk_fma_f32 v[132:133], v[180:181], v[132:133], v[196:197]
	v_pk_fma_f32 v[134:135], v[182:183], v[134:135], v[198:199]
	v_pk_fma_f32 v[136:137], v[184:185], v[136:137], v[200:201]
	v_pk_fma_f32 v[138:139], v[186:187], v[138:139], v[202:203]
	v_pk_fma_f32 v[140:141], v[188:189], v[140:141], v[204:205]
	v_pk_fma_f32 v[142:143], v[190:191], v[142:143], v[206:207]
	v_cvt_pk_bf16_f32 v100, v128, v129
	v_cvt_pk_bf16_f32 v101, v130, v131
	v_cvt_pk_bf16_f32 v102, v132, v133
	v_cvt_pk_bf16_f32 v103, v134, v135
	v_cvt_pk_bf16_f32 v104, v136, v137
	v_cvt_pk_bf16_f32 v105, v138, v139
	v_cvt_pk_bf16_f32 v106, v140, v141
	v_cvt_pk_bf16_f32 v107, v142, v143
	s_add_u32 s8, s8, 0x400000
	s_addc_u32 s9, s9, 0
	global_store_dwordx2 v33, v[100:101], s[8:9]
	global_store_dwordx2 v33, v[102:103], s[8:9] offset:512
	global_store_dwordx2 v33, v[104:105], s[8:9] offset:1024
	global_store_dwordx2 v33, v[106:107], s[8:9] offset:1536
	s_add_u32 s6, s6, 0x800000
	s_addc_u32 s7, s7, 0
	global_load_dwordx4 v[128:131], v32, s[6:7]
	global_load_dwordx4 v[132:135], v32, s[6:7] offset:1024
	global_load_dwordx4 v[136:139], v32, s[6:7] offset:2048
	global_load_dwordx4 v[140:143], v32, s[6:7] offset:3072
	s_waitcnt vmcnt(16)
	v_pk_add_f32 v[64:65], v[64:65], 1.0 op_sel_hi:[1,0]
	v_pk_add_f32 v[66:67], v[66:67], 1.0 op_sel_hi:[1,0]
	v_pk_add_f32 v[68:69], v[68:69], 1.0 op_sel_hi:[1,0]
	v_pk_add_f32 v[70:71], v[70:71], 1.0 op_sel_hi:[1,0]
	v_pk_add_f32 v[72:73], v[72:73], 1.0 op_sel_hi:[1,0]
	v_pk_add_f32 v[74:75], v[74:75], 1.0 op_sel_hi:[1,0]
	v_pk_add_f32 v[76:77], v[76:77], 1.0 op_sel_hi:[1,0]
	v_pk_add_f32 v[78:79], v[78:79], 1.0 op_sel_hi:[1,0]
	v_pk_mul_f32 v[96:97], v[144:145], v[144:145]
	v_pk_fma_f32 v[96:97], v[146:147], v[146:147], v[96:97]
	v_pk_fma_f32 v[96:97], v[148:149], v[148:149], v[96:97]
	v_pk_fma_f32 v[96:97], v[150:151], v[150:151], v[96:97]
	v_pk_fma_f32 v[96:97], v[152:153], v[152:153], v[96:97]
	v_pk_fma_f32 v[96:97], v[154:155], v[154:155], v[96:97]
	v_pk_fma_f32 v[96:97], v[156:157], v[156:157], v[96:97]
	v_pk_fma_f32 v[96:97], v[158:159], v[158:159], v[96:97]
	v_add_f32_e32 v96, v96, v97
	s_nop 1
	v_add_f32_dpp v97, v96, v96 quad_perm:[1,0,3,2] row_mask:0xf bank_mask:0xf
	s_nop 1
	v_add_f32_dpp v96, v97, v97 quad_perm:[2,3,0,1] row_mask:0xf bank_mask:0xf
	s_nop 1
	v_add_f32_dpp v97, v96, v96 row_half_mirror row_mask:0xf bank_mask:0xf
	s_nop 1
	v_add_f32_dpp v96, v97, v97 row_mirror row_mask:0xf bank_mask:0xf
	s_nop 1
	v_readlane_b32 s16, v96, 0
	v_readlane_b32 s17, v96, 16
	v_readlane_b32 s18, v96, 32
	v_readlane_b32 s19, v96, 48
	s_nop 1
	v_mov_b32_e32 v96, s16
	v_add_f32_e32 v96, s17, v96
	v_add_f32_e32 v96, s18, v96
	v_add_f32_e32 v96, s19, v96
	v_mov_b32_e32 v98, 0x358637bd
	v_fmamk_f32 v96, v96, 0x3a800000, v98
	v_rsq_f32_e32 v96, v96
	s_nop 0
	v_pk_mul_f32 v[144:145], v[144:145], v[96:97] op_sel_hi:[1,0]
	v_pk_mul_f32 v[146:147], v[146:147], v[96:97] op_sel_hi:[1,0]
	v_pk_mul_f32 v[148:149], v[148:149], v[96:97] op_sel_hi:[1,0]
	v_pk_mul_f32 v[150:151], v[150:151], v[96:97] op_sel_hi:[1,0]
	v_pk_mul_f32 v[152:153], v[152:153], v[96:97] op_sel_hi:[1,0]
	v_pk_mul_f32 v[154:155], v[154:155], v[96:97] op_sel_hi:[1,0]
	v_pk_mul_f32 v[156:157], v[156:157], v[96:97] op_sel_hi:[1,0]
	v_pk_mul_f32 v[158:159], v[158:159], v[96:97] op_sel_hi:[1,0]
	v_pk_mul_f32 v[144:145], v[48:49], v[144:145]
	v_pk_mul_f32 v[146:147], v[50:51], v[146:147]
	v_pk_mul_f32 v[148:149], v[52:53], v[148:149]
	v_pk_mul_f32 v[150:151], v[54:55], v[150:151]
; __device__ __forceinline__ void store_bf4(bf16_t* p, f32x4 v) { uint2 o; o.x = pk2(v[0], v[1]); o.y = pk2(v[2], v[3]); *(uint2*)p = o; }
; __device__ __forceinline__ void norm_row_pre(const f32x4 (&v)[4], const float* __restrict__ g, const float* __restrict__ shift, const float* __restrict__ scale, bf16_t* __restrict__ dst, int lane) {
;     float ss = 0.f;
; #pragma unroll
;     for (int j = 0; j < 4; ++j) ss += v[j][0] * v[j][0] + v[j][1] * v[j][1] + v[j][2] * v[j][2] + v[j][3] * v[j][3];
;     ss = wave_sum(ss);
;     const float rstd = rsqrtf(ss * (1.f / 1024.f) + 1e-6f);
; #pragma unroll
;     for (int j = 0; j < 4; ++j) {
;         const int c4 = lane + 64 * j;
;         const f32x4 g4 = ((const f32x4*)g)[c4], sh = ((const f32x4*)shift)[c4], sc = ((const f32x4*)scale)[c4];
;         f32x4 h = (v[j] * rstd) * g4; h = h * (sc + 1.f) + sh;
;         store_bf4(dst + c4 * 4, h);
;     }
; }
; __device__ __forceinline__ void phase1(const Params& P) {
;     ...
;         const int stride = gridDim.x * 8;
;         int row = blockIdx.x * 8 + w;
;         f32x4 vn[4];
;         if (row < NT) { const float* src = row < NL ? P.in[0] + (size_t)row * 1024 : P.in[2] + (size_t)(row - NL) * 1024;
; #pragma unroll
;             for (int j = 0; j < 4; ++j) vn[j] = ((const f32x4*)src)[lane + 64 * j]; }
;         while (row < NT) {
;             f32x4 v[4];
; #pragma unroll
;             for (int j = 0; j < 4; ++j) v[j] = vn[j];
;             const int nrow = row + stride;
;             if (nrow < NT) { const float* src = nrow < NL ? P.in[0] + (size_t)nrow * 1024 : P.in[2] + (size_t)(nrow - NL) * 1024;
; #pragma unroll
;                 for (int j = 0; j < 4; ++j) vn[j] = ((const f32x4*)src)[lane + 64 * j]; }
;             const int mr = row < NL ? (row >> 13) : 4;
;             norm_row_pre(v, P.in[6], mod + mr * 9216 + 0, mod + mr * 9216 + 1024, H + (size_t)row * 1024, lane);
;             if (row >= NL) {
; #pragma unroll
;                 for (int j = 0; j < 4; ++j) ((f32x4*)((float*)(P.ws + OFF_E) + (size_t)(row - NL) * 1024))[lane + 64 * j] = v[j];
;             }
;             row = nrow;
;         }
	v_pk_mul_f32 v[152:153], v[56:57], v[152:153]
	v_pk_mul_f32 v[154:155], v[58:59], v[154:155]
	v_pk_mul_f32 v[156:157], v[60:61], v[156:157]
	v_pk_mul_f32 v[158:159], v[62:63], v[158:159]
	v_pk_fma_f32 v[144:145], v[64:65], v[144:145], v[80:81]
	v_pk_fma_f32 v[146:147], v[66:67], v[146:147], v[82:83]
	v_pk_fma_f32 v[148:149], v[68:69], v[148:149], v[84:85]
	v_pk_fma_f32 v[150:151], v[70:71], v[150:151], v[86:87]
	v_pk_fma_f32 v[152:153], v[72:73], v[152:153], v[88:89]
	v_pk_fma_f32 v[154:155], v[74:75], v[154:155], v[90:91]
	v_pk_fma_f32 v[156:157], v[76:77], v[156:157], v[92:93]
	v_pk_fma_f32 v[158:159], v[78:79], v[158:159], v[94:95]
	v_cvt_pk_bf16_f32 v100, v144, v145
	v_cvt_pk_bf16_f32 v101, v146, v147
	v_cvt_pk_bf16_f32 v102, v148, v149
	v_cvt_pk_bf16_f32 v103, v150, v151
	v_cvt_pk_bf16_f32 v104, v152, v153
	v_cvt_pk_bf16_f32 v105, v154, v155
	v_cvt_pk_bf16_f32 v106, v156, v157
	v_cvt_pk_bf16_f32 v107, v158, v159
	s_add_u32 s8, s8, 0x400000
	s_addc_u32 s9, s9, 0
	global_store_dwordx2 v33, v[100:101], s[8:9]
	global_store_dwordx2 v33, v[102:103], s[8:9] offset:512
	global_store_dwordx2 v33, v[104:105], s[8:9] offset:1024
	global_store_dwordx2 v33, v[106:107], s[8:9] offset:1536
	s_add_u32 s6, s6, 0x800000
	s_addc_u32 s7, s7, 0
	global_load_dwordx4 v[144:147], v32, s[6:7]
	global_load_dwordx4 v[148:151], v32, s[6:7] offset:1024
	global_load_dwordx4 v[152:155], v32, s[6:7] offset:2048
	global_load_dwordx4 v[156:159], v32, s[6:7] offset:3072
	s_waitcnt vmcnt(16)
	v_pk_mul_f32 v[96:97], v[112:113], v[112:113]
	v_pk_fma_f32 v[96:97], v[114:115], v[114:115], v[96:97]
	v_pk_fma_f32 v[96:97], v[116:117], v[116:117], v[96:97]
	v_pk_fma_f32 v[96:97], v[118:119], v[118:119], v[96:97]
	v_pk_fma_f32 v[96:97], v[120:121], v[120:121], v[96:97]
	v_pk_fma_f32 v[96:97], v[122:123], v[122:123], v[96:97]
	v_pk_fma_f32 v[96:97], v[124:125], v[124:125], v[96:97]
	v_pk_fma_f32 v[96:97], v[126:127], v[126:127], v[96:97]
	v_add_f32_e32 v96, v96, v97
	s_nop 1
	v_add_f32_dpp v97, v96, v96 quad_perm:[1,0,3,2] row_mask:0xf bank_mask:0xf
	s_nop 1
	v_add_f32_dpp v96, v97, v97 quad_perm:[2,3,0,1] row_mask:0xf bank_mask:0xf
	s_nop 1
	v_add_f32_dpp v97, v96, v96 row_half_mirror row_mask:0xf bank_mask:0xf
	s_nop 1
	v_add_f32_dpp v96, v97, v97 row_mirror row_mask:0xf bank_mask:0xf
	s_nop 1
	v_readlane_b32 s16, v96, 0
	v_readlane_b32 s17, v96, 16
	v_readlane_b32 s18, v96, 32
	v_readlane_b32 s19, v96, 48
	s_nop 1
	v_mov_b32_e32 v96, s16
	v_add_f32_e32 v96, s17, v96
	v_add_f32_e32 v96, s18, v96
	v_add_f32_e32 v96, s19, v96
	v_mov_b32_e32 v98, 0x358637bd
	v_fmamk_f32 v96, v96, 0x3a800000, v98
	v_rsq_f32_e32 v96, v96
	s_nop 0
	v_pk_mul_f32 v[112:113], v[112:113], v[96:97] op_sel_hi:[1,0]
	v_pk_mul_f32 v[114:115], v[114:115], v[96:97] op_sel_hi:[1,0]
	v_pk_mul_f32 v[116:117], v[116:117], v[96:97] op_sel_hi:[1,0]
	v_pk_mul_f32 v[118:119], v[118:119], v[96:97] op_sel_hi:[1,0]
	v_pk_mul_f32 v[120:121], v[120:121], v[96:97] op_sel_hi:[1,0]
	v_pk_mul_f32 v[122:123], v[122:123], v[96:97] op_sel_hi:[1,0]
	v_pk_mul_f32 v[124:125], v[124:125], v[96:97] op_sel_hi:[1,0]
	v_pk_mul_f32 v[126:127], v[126:127], v[96:97] op_sel_hi:[1,0]
	v_pk_mul_f32 v[112:113], v[48:49], v[112:113]
	v_pk_mul_f32 v[114:115], v[50:51], v[114:115]
	v_pk_mul_f32 v[116:117], v[52:53], v[116:117]
	v_pk_mul_f32 v[118:119], v[54:55], v[118:119]
	v_pk_mul_f32 v[120:121], v[56:57], v[120:121]
	v_pk_mul_f32 v[122:123], v[58:59], v[122:123]
	v_pk_mul_f32 v[124:125], v[60:61], v[124:125]
	v_pk_mul_f32 v[126:127], v[62:63], v[126:127]
	v_pk_fma_f32 v[112:113], v[64:65], v[112:113], v[80:81]
	v_pk_fma_f32 v[114:115], v[66:67], v[114:115], v[82:83]
	v_pk_fma_f32 v[116:117], v[68:69], v[116:117], v[84:85]
	v_pk_fma_f32 v[118:119], v[70:71], v[118:119], v[86:87]
	v_pk_fma_f32 v[120:121], v[72:73], v[120:121], v[88:89]
	v_pk_fma_f32 v[122:123], v[74:75], v[122:123], v[90:91]
	v_pk_fma_f32 v[124:125], v[76:77], v[124:125], v[92:93]
	v_pk_fma_f32 v[126:127], v[78:79], v[126:127], v[94:95]
	v_cvt_pk_bf16_f32 v100, v112, v113
	v_cvt_pk_bf16_f32 v101, v114, v115
	v_cvt_pk_bf16_f32 v102, v116, v117
	v_cvt_pk_bf16_f32 v103, v118, v119
	v_cvt_pk_bf16_f32 v104, v120, v121
	v_cvt_pk_bf16_f32 v105, v122, v123
	v_cvt_pk_bf16_f32 v106, v124, v125
	v_cvt_pk_bf16_f32 v107, v126, v127
	s_add_u32 s8, s8, 0x400000
	s_addc_u32 s9, s9, 0
	global_store_dwordx2 v33, v[100:101], s[8:9]
	global_store_dwordx2 v33, v[102:103], s[8:9] offset:512
	global_store_dwordx2 v33, v[104:105], s[8:9] offset:1024
	global_store_dwordx2 v33, v[106:107], s[8:9] offset:1536
	s_add_u32 s6, s6, 0x800000
	s_addc_u32 s7, s7, 0
	global_load_dwordx4 v[112:115], v32, s[6:7]
	global_load_dwordx4 v[116:119], v32, s[6:7] offset:1024
	global_load_dwordx4 v[120:123], v32, s[6:7] offset:2048
	global_load_dwordx4 v[124:127], v32, s[6:7] offset:3072
	s_mov_b32 s10, 110592
	s_add_u32 s12, s2, s10
	s_addc_u32 s13, s3, 0
	s_add_u32 s14, s12, 0x1000
	s_addc_u32 s15, s13, 0
	global_load_dwordx4 v[192:195], v32, s[12:13]
	global_load_dwordx4 v[196:199], v32, s[12:13] offset:1024
	global_load_dwordx4 v[200:203], v32, s[12:13] offset:2048
	global_load_dwordx4 v[204:207], v32, s[12:13] offset:3072
	global_load_dwordx4 v[176:179], v32, s[14:15]
	global_load_dwordx4 v[180:183], v32, s[14:15] offset:1024
	global_load_dwordx4 v[184:187], v32, s[14:15] offset:2048
	global_load_dwordx4 v[188:191], v32, s[14:15] offset:3072
	s_waitcnt vmcnt(24)
; __device__ __forceinline__ void store_bf4(bf16_t* p, f32x4 v) { uint2 o; o.x = pk2(v[0], v[1]); o.y = pk2(v[2], v[3]); *(uint2*)p = o; }
; __device__ __forceinline__ void norm_row_pre(const f32x4 (&v)[4], const float* __restrict__ g, const float* __restrict__ shift, const float* __restrict__ scale, bf16_t* __restrict__ dst, int lane) {
;     float ss = 0.f;
; #pragma unroll
;     for (int j = 0; j < 4; ++j) ss += v[j][0] * v[j][0] + v[j][1] * v[j][1] + v[j][2] * v[j][2] + v[j][3] * v[j][3];
;     ss = wave_sum(ss);
;     const float rstd = rsqrtf(ss * (1.f / 1024.f) + 1e-6f);
; #pragma unroll
;     for (int j = 0; j < 4; ++j) {
;         const int c4 = lane + 64 * j;
;         const f32x4 g4 = ((const f32x4*)g)[c4], sh = ((const f32x4*)shift)[c4], sc = ((const f32x4*)scale)[c4];
;         f32x4 h = (v[j] * rstd) * g4; h = h * (sc + 1.f) + sh;
;         store_bf4(dst + c4 * 4, h);
;     }
; }
; __device__ __forceinline__ void phase1(const Params& P) {
;     ...
;         const int stride = gridDim.x * 8;
;         int row = blockIdx.x * 8 + w;
;         f32x4 vn[4];
;         if (row < NT) { const float* src = row < NL ? P.in[0] + (size_t)row * 1024 : P.in[2] + (size_t)(row - NL) * 1024;
; #pragma unroll
;             for (int j = 0; j < 4; ++j) vn[j] = ((const f32x4*)src)[lane + 64 * j]; }
;         while (row < NT) {
;             f32x4 v[4];
; #pragma unroll
;             for (int j = 0; j < 4; ++j) v[j] = vn[j];
;             const int nrow = row + stride;
;             if (nrow < NT) { const float* src = nrow < NL ? P.in[0] + (size_t)nrow * 1024 : P.in[2] + (size_t)(nrow - NL) * 1024;
; #pragma unroll
;                 for (int j = 0; j < 4; ++j) vn[j] = ((const f32x4*)src)[lane + 64 * j]; }
;             const int mr = row < NL ? (row >> 13) : 4;
;             norm_row_pre(v, P.in[6], mod + mr * 9216 + 0, mod + mr * 9216 + 1024, H + (size_t)row * 1024, lane);
;             if (row >= NL) {
; #pragma unroll
;                 for (int j = 0; j < 4; ++j) ((f32x4*)((float*)(P.ws + OFF_E) + (size_t)(row - NL) * 1024))[lane + 64 * j] = v[j];
;             }
;             row = nrow;
;         }
	v_pk_mul_f32 v[96:97], v[128:129], v[128:129]
	v_pk_fma_f32 v[96:97], v[130:131], v[130:131], v[96:97]
	v_pk_fma_f32 v[96:97], v[132:133], v[132:133], v[96:97]
	v_pk_fma_f32 v[96:97], v[134:135], v[134:135], v[96:97]
	v_pk_fma_f32 v[96:97], v[136:137], v[136:137], v[96:97]
	v_pk_fma_f32 v[96:97], v[138:139], v[138:139], v[96:97]
	v_pk_fma_f32 v[96:97], v[140:141], v[140:141], v[96:97]
	v_pk_fma_f32 v[96:97], v[142:143], v[142:143], v[96:97]
	v_add_f32_e32 v96, v96, v97
	s_nop 1
	v_add_f32_dpp v97, v96, v96 quad_perm:[1,0,3,2] row_mask:0xf bank_mask:0xf
	s_nop 1
	v_add_f32_dpp v96, v97, v97 quad_perm:[2,3,0,1] row_mask:0xf bank_mask:0xf
	s_nop 1
	v_add_f32_dpp v97, v96, v96 row_half_mirror row_mask:0xf bank_mask:0xf
	s_nop 1
	v_add_f32_dpp v96, v97, v97 row_mirror row_mask:0xf bank_mask:0xf
	s_nop 1
	v_readlane_b32 s16, v96, 0
	v_readlane_b32 s17, v96, 16
	v_readlane_b32 s18, v96, 32
	v_readlane_b32 s19, v96, 48
	s_nop 1
	v_mov_b32_e32 v96, s16
	v_add_f32_e32 v96, s17, v96
	v_add_f32_e32 v96, s18, v96
	v_add_f32_e32 v96, s19, v96
	v_mov_b32_e32 v98, 0x358637bd
	v_fmamk_f32 v96, v96, 0x3a800000, v98
	v_rsq_f32_e32 v96, v96
	s_nop 0
	v_pk_mul_f32 v[128:129], v[128:129], v[96:97] op_sel_hi:[1,0]
	v_pk_mul_f32 v[130:131], v[130:131], v[96:97] op_sel_hi:[1,0]
	v_pk_mul_f32 v[132:133], v[132:133], v[96:97] op_sel_hi:[1,0]
	v_pk_mul_f32 v[134:135], v[134:135], v[96:97] op_sel_hi:[1,0]
	v_pk_mul_f32 v[136:137], v[136:137], v[96:97] op_sel_hi:[1,0]
	v_pk_mul_f32 v[138:139], v[138:139], v[96:97] op_sel_hi:[1,0]
	v_pk_mul_f32 v[140:141], v[140:141], v[96:97] op_sel_hi:[1,0]
	v_pk_mul_f32 v[142:143], v[142:143], v[96:97] op_sel_hi:[1,0]
	v_pk_mul_f32 v[128:129], v[48:49], v[128:129]
	v_pk_mul_f32 v[130:131], v[50:51], v[130:131]
	v_pk_mul_f32 v[132:133], v[52:53], v[132:133]
	v_pk_mul_f32 v[134:135], v[54:55], v[134:135]
	v_pk_mul_f32 v[136:137], v[56:57], v[136:137]
	v_pk_mul_f32 v[138:139], v[58:59], v[138:139]
	v_pk_mul_f32 v[140:141], v[60:61], v[140:141]
	v_pk_mul_f32 v[142:143], v[62:63], v[142:143]
	v_pk_fma_f32 v[128:129], v[64:65], v[128:129], v[80:81]
	v_pk_fma_f32 v[130:131], v[66:67], v[130:131], v[82:83]
	v_pk_fma_f32 v[132:133], v[68:69], v[132:133], v[84:85]
	v_pk_fma_f32 v[134:135], v[70:71], v[134:135], v[86:87]
	v_pk_fma_f32 v[136:137], v[72:73], v[136:137], v[88:89]
	v_pk_fma_f32 v[138:139], v[74:75], v[138:139], v[90:91]
	v_pk_fma_f32 v[140:141], v[76:77], v[140:141], v[92:93]
	v_pk_fma_f32 v[142:143], v[78:79], v[142:143], v[94:95]
	v_cvt_pk_bf16_f32 v100, v128, v129
	v_cvt_pk_bf16_f32 v101, v130, v131
	v_cvt_pk_bf16_f32 v102, v132, v133
	v_cvt_pk_bf16_f32 v103, v134, v135
	v_cvt_pk_bf16_f32 v104, v136, v137
	v_cvt_pk_bf16_f32 v105, v138, v139
	v_cvt_pk_bf16_f32 v106, v140, v141
	v_cvt_pk_bf16_f32 v107, v142, v143
	s_add_u32 s8, s8, 0x400000
	s_addc_u32 s9, s9, 0
	global_store_dwordx2 v33, v[100:101], s[8:9]
	global_store_dwordx2 v33, v[102:103], s[8:9] offset:512
	global_store_dwordx2 v33, v[104:105], s[8:9] offset:1024
	global_store_dwordx2 v33, v[106:107], s[8:9] offset:1536
	s_add_u32 s6, s6, 0x800000
	s_addc_u32 s7, s7, 0
	global_load_dwordx4 v[128:131], v32, s[6:7]
	global_load_dwordx4 v[132:135], v32, s[6:7] offset:1024
	global_load_dwordx4 v[136:139], v32, s[6:7] offset:2048
	global_load_dwordx4 v[140:143], v32, s[6:7] offset:3072
	s_waitcnt vmcnt(24)
	v_pk_mul_f32 v[96:97], v[144:145], v[144:145]
	v_pk_fma_f32 v[96:97], v[146:147], v[146:147], v[96:97]
	v_pk_fma_f32 v[96:97], v[148:149], v[148:149], v[96:97]
	v_pk_fma_f32 v[96:97], v[150:151], v[150:151], v[96:97]
	v_pk_fma_f32 v[96:97], v[152:153], v[152:153], v[96:97]
	v_pk_fma_f32 v[96:97], v[154:155], v[154:155], v[96:97]
	v_pk_fma_f32 v[96:97], v[156:157], v[156:157], v[96:97]
	v_pk_fma_f32 v[96:97], v[158:159], v[158:159], v[96:97]
	v_add_f32_e32 v96, v96, v97
	s_nop 1
	v_add_f32_dpp v97, v96, v96 quad_perm:[1,0,3,2] row_mask:0xf bank_mask:0xf
	s_nop 1
	v_add_f32_dpp v96, v97, v97 quad_perm:[2,3,0,1] row_mask:0xf bank_mask:0xf
	s_nop 1
	v_add_f32_dpp v97, v96, v96 row_half_mirror row_mask:0xf bank_mask:0xf
	s_nop 1
	v_add_f32_dpp v96, v97, v97 row_mirror row_mask:0xf bank_mask:0xf
	s_nop 1
	v_readlane_b32 s16, v96, 0
	v_readlane_b32 s17, v96, 16
	v_readlane_b32 s18, v96, 32
	v_readlane_b32 s19, v96, 48
	s_nop 1
	v_mov_b32_e32 v96, s16
	v_add_f32_e32 v96, s17, v96
	v_add_f32_e32 v96, s18, v96
	v_add_f32_e32 v96, s19, v96
	v_mov_b32_e32 v98, 0x358637bd
	v_fmamk_f32 v96, v96, 0x3a800000, v98
	v_rsq_f32_e32 v96, v96
	s_nop 0
	v_pk_mul_f32 v[144:145], v[144:145], v[96:97] op_sel_hi:[1,0]
	v_pk_mul_f32 v[146:147], v[146:147], v[96:97] op_sel_hi:[1,0]
	v_pk_mul_f32 v[148:149], v[148:149], v[96:97] op_sel_hi:[1,0]
	v_pk_mul_f32 v[150:151], v[150:151], v[96:97] op_sel_hi:[1,0]
	v_pk_mul_f32 v[152:153], v[152:153], v[96:97] op_sel_hi:[1,0]
	v_pk_mul_f32 v[154:155], v[154:155], v[96:97] op_sel_hi:[1,0]
	v_pk_mul_f32 v[156:157], v[156:157], v[96:97] op_sel_hi:[1,0]
	v_pk_mul_f32 v[158:159], v[158:159], v[96:97] op_sel_hi:[1,0]
	v_pk_mul_f32 v[144:145], v[48:49], v[144:145]
	v_pk_mul_f32 v[146:147], v[50:51], v[146:147]
	v_pk_mul_f32 v[148:149], v[52:53], v[148:149]
	v_pk_mul_f32 v[150:151], v[54:55], v[150:151]
	v_pk_mul_f32 v[152:153], v[56:57], v[152:153]
	v_pk_mul_f32 v[154:155], v[58:59], v[154:155]
	v_pk_mul_f32 v[156:157], v[60:61], v[156:157]
	v_pk_mul_f32 v[158:159], v[62:63], v[158:159]
	v_pk_fma_f32 v[144:145], v[64:65], v[144:145], v[80:81]
	v_pk_fma_f32 v[146:147], v[66:67], v[146:147], v[82:83]
	v_pk_fma_f32 v[148:149], v[68:69], v[148:149], v[84:85]
	v_pk_fma_f32 v[150:151], v[70:71], v[150:151], v[86:87]
	v_pk_fma_f32 v[152:153], v[72:73], v[152:153], v[88:89]
	v_pk_fma_f32 v[154:155], v[74:75], v[154:155], v[90:91]
	v_pk_fma_f32 v[156:157], v[76:77], v[156:157], v[92:93]
	v_pk_fma_f32 v[158:159], v[78:79], v[158:159], v[94:95]
	v_cvt_pk_bf16_f32 v100, v144, v145
	v_cvt_pk_bf16_f32 v101, v146, v147
	v_cvt_pk_bf16_f32 v102, v148, v149
	v_cvt_pk_bf16_f32 v103, v150, v151
	v_cvt_pk_bf16_f32 v104, v152, v153
	v_cvt_pk_bf16_f32 v105, v154, v155
	v_cvt_pk_bf16_f32 v106, v156, v157
	v_cvt_pk_bf16_f32 v107, v158, v159
	s_add_u32 s8, s8, 0x400000
	s_addc_u32 s9, s9, 0
	global_store_dwordx2 v33, v[100:101], s[8:9]
	global_store_dwordx2 v33, v[102:103], s[8:9] offset:512
	global_store_dwordx2 v33, v[104:105], s[8:9] offset:1024
	global_store_dwordx2 v33, v[106:107], s[8:9] offset:1536
	s_add_u32 s6, s6, 0x800000
	s_addc_u32 s7, s7, 0
	global_load_dwordx4 v[144:147], v32, s[6:7]
	global_load_dwordx4 v[148:151], v32, s[6:7] offset:1024
	global_load_dwordx4 v[152:155], v32, s[6:7] offset:2048
	global_load_dwordx4 v[156:159], v32, s[6:7] offset:3072
	s_waitcnt vmcnt(16)
; __device__ __forceinline__ void store_bf4(bf16_t* p, f32x4 v) { uint2 o; o.x = pk2(v[0], v[1]); o.y = pk2(v[2], v[3]); *(uint2*)p = o; }
; __device__ __forceinline__ void norm_row_pre(const f32x4 (&v)[4], const float* __restrict__ g, const float* __restrict__ shift, const float* __restrict__ scale, bf16_t* __restrict__ dst, int lane) {
;     float ss = 0.f;
; #pragma unroll
;     for (int j = 0; j < 4; ++j) ss += v[j][0] * v[j][0] + v[j][1] * v[j][1] + v[j][2] * v[j][2] + v[j][3] * v[j][3];
;     ss = wave_sum(ss);
;     const float rstd = rsqrtf(ss * (1.f / 1024.f) + 1e-6f);
; #pragma unroll
;     for (int j = 0; j < 4; ++j) {
;         const int c4 = lane + 64 * j;
;         const f32x4 g4 = ((const f32x4*)g)[c4], sh = ((const f32x4*)shift)[c4], sc = ((const f32x4*)scale)[c4];
;         f32x4 h = (v[j] * rstd) * g4; h = h * (sc + 1.f) + sh;
;         store_bf4(dst + c4 * 4, h);
;     }
; }
; __device__ __forceinline__ void phase1(const Params& P) {
;     ...
;         const int stride = gridDim.x * 8;
;         int row = blockIdx.x * 8 + w;
;         f32x4 vn[4];
;         if (row < NT) { const float* src = row < NL ? P.in[0] + (size_t)row * 1024 : P.in[2] + (size_t)(row - NL) * 1024;
; #pragma unroll
;             for (int j = 0; j < 4; ++j) vn[j] = ((const f32x4*)src)[lane + 64 * j]; }
;         while (row < NT) {
;             f32x4 v[4];
; #pragma unroll
;             for (int j = 0; j < 4; ++j) v[j] = vn[j];
;             const int nrow = row + stride;
;             if (nrow < NT) { const float* src = nrow < NL ? P.in[0] + (size_t)nrow * 1024 : P.in[2] + (size_t)(nrow - NL) * 1024;
; #pragma unroll
;                 for (int j = 0; j < 4; ++j) vn[j] = ((const f32x4*)src)[lane + 64 * j]; }
;             const int mr = row < NL ? (row >> 13) : 4;
;             norm_row_pre(v, P.in[6], mod + mr * 9216 + 0, mod + mr * 9216 + 1024, H + (size_t)row * 1024, lane);
;             if (row >= NL) {
; #pragma unroll
;                 for (int j = 0; j < 4; ++j) ((f32x4*)((float*)(P.ws + OFF_E) + (size_t)(row - NL) * 1024))[lane + 64 * j] = v[j];
;             }
;             row = nrow;
;         }
	v_pk_add_f32 v[176:177], v[176:177], 1.0 op_sel_hi:[1,0]
	v_pk_add_f32 v[178:179], v[178:179], 1.0 op_sel_hi:[1,0]
	v_pk_add_f32 v[180:181], v[180:181], 1.0 op_sel_hi:[1,0]
	v_pk_add_f32 v[182:183], v[182:183], 1.0 op_sel_hi:[1,0]
	v_pk_add_f32 v[184:185], v[184:185], 1.0 op_sel_hi:[1,0]
	v_pk_add_f32 v[186:187], v[186:187], 1.0 op_sel_hi:[1,0]
	v_pk_add_f32 v[188:189], v[188:189], 1.0 op_sel_hi:[1,0]
	v_pk_add_f32 v[190:191], v[190:191], 1.0 op_sel_hi:[1,0]
	v_pk_mul_f32 v[96:97], v[112:113], v[112:113]
	v_pk_fma_f32 v[96:97], v[114:115], v[114:115], v[96:97]
	v_pk_fma_f32 v[96:97], v[116:117], v[116:117], v[96:97]
	v_pk_fma_f32 v[96:97], v[118:119], v[118:119], v[96:97]
	v_pk_fma_f32 v[96:97], v[120:121], v[120:121], v[96:97]
	v_pk_fma_f32 v[96:97], v[122:123], v[122:123], v[96:97]
	v_pk_fma_f32 v[96:97], v[124:125], v[124:125], v[96:97]
	v_pk_fma_f32 v[96:97], v[126:127], v[126:127], v[96:97]
	v_add_f32_e32 v96, v96, v97
	s_nop 1
	v_add_f32_dpp v97, v96, v96 quad_perm:[1,0,3,2] row_mask:0xf bank_mask:0xf
	s_nop 1
	v_add_f32_dpp v96, v97, v97 quad_perm:[2,3,0,1] row_mask:0xf bank_mask:0xf
	s_nop 1
	v_add_f32_dpp v97, v96, v96 row_half_mirror row_mask:0xf bank_mask:0xf
	s_nop 1
	v_add_f32_dpp v96, v97, v97 row_mirror row_mask:0xf bank_mask:0xf
	s_nop 1
	v_readlane_b32 s16, v96, 0
	v_readlane_b32 s17, v96, 16
	v_readlane_b32 s18, v96, 32
	v_readlane_b32 s19, v96, 48
	s_nop 1
	v_mov_b32_e32 v96, s16
	v_add_f32_e32 v96, s17, v96
	v_add_f32_e32 v96, s18, v96
	v_add_f32_e32 v96, s19, v96
	v_mov_b32_e32 v98, 0x358637bd
	v_fmamk_f32 v96, v96, 0x3a800000, v98
	v_rsq_f32_e32 v96, v96
	s_nop 0
	v_pk_mul_f32 v[112:113], v[112:113], v[96:97] op_sel_hi:[1,0]
	v_pk_mul_f32 v[114:115], v[114:115], v[96:97] op_sel_hi:[1,0]
	v_pk_mul_f32 v[116:117], v[116:117], v[96:97] op_sel_hi:[1,0]
	v_pk_mul_f32 v[118:119], v[118:119], v[96:97] op_sel_hi:[1,0]
	v_pk_mul_f32 v[120:121], v[120:121], v[96:97] op_sel_hi:[1,0]
	v_pk_mul_f32 v[122:123], v[122:123], v[96:97] op_sel_hi:[1,0]
	v_pk_mul_f32 v[124:125], v[124:125], v[96:97] op_sel_hi:[1,0]
	v_pk_mul_f32 v[126:127], v[126:127], v[96:97] op_sel_hi:[1,0]
	v_pk_mul_f32 v[112:113], v[48:49], v[112:113]
	v_pk_mul_f32 v[114:115], v[50:51], v[114:115]
	v_pk_mul_f32 v[116:117], v[52:53], v[116:117]
	v_pk_mul_f32 v[118:119], v[54:55], v[118:119]
	v_pk_mul_f32 v[120:121], v[56:57], v[120:121]
	v_pk_mul_f32 v[122:123], v[58:59], v[122:123]
	v_pk_mul_f32 v[124:125], v[60:61], v[124:125]
	v_pk_mul_f32 v[126:127], v[62:63], v[126:127]
	v_pk_fma_f32 v[112:113], v[176:177], v[112:113], v[192:193]
	v_pk_fma_f32 v[114:115], v[178:179], v[114:115], v[194:195]
	v_pk_fma_f32 v[116:117], v[180:181], v[116:117], v[196:197]
	v_pk_fma_f32 v[118:119], v[182:183], v[118:119], v[198:199]
	v_pk_fma_f32 v[120:121], v[184:185], v[120:121], v[200:201]
	v_pk_fma_f32 v[122:123], v[186:187], v[122:123], v[202:203]
	v_pk_fma_f32 v[124:125], v[188:189], v[124:125], v[204:205]
	v_pk_fma_f32 v[126:127], v[190:191], v[126:127], v[206:207]
	v_cvt_pk_bf16_f32 v100, v112, v113
	v_cvt_pk_bf16_f32 v101, v114, v115
	v_cvt_pk_bf16_f32 v102, v116, v117
	v_cvt_pk_bf16_f32 v103, v118, v119
	v_cvt_pk_bf16_f32 v104, v120, v121
	v_cvt_pk_bf16_f32 v105, v122, v123
	v_cvt_pk_bf16_f32 v106, v124, v125
	v_cvt_pk_bf16_f32 v107, v126, v127
	s_add_u32 s8, s8, 0x400000
	s_addc_u32 s9, s9, 0
	global_store_dwordx2 v33, v[100:101], s[8:9]
	global_store_dwordx2 v33, v[102:103], s[8:9] offset:512
	global_store_dwordx2 v33, v[104:105], s[8:9] offset:1024
	global_store_dwordx2 v33, v[106:107], s[8:9] offset:1536
	s_add_u32 s6, s6, 0x800000
	s_addc_u32 s7, s7, 0
	global_load_dwordx4 v[112:115], v32, s[6:7]
	global_load_dwordx4 v[116:119], v32, s[6:7] offset:1024
	global_load_dwordx4 v[120:123], v32, s[6:7] offset:2048
	global_load_dwordx4 v[124:127], v32, s[6:7] offset:3072
	s_waitcnt vmcnt(16)
	v_pk_mul_f32 v[96:97], v[128:129], v[128:129]
	v_pk_fma_f32 v[96:97], v[130:131], v[130:131], v[96:97]
	v_pk_fma_f32 v[96:97], v[132:133], v[132:133], v[96:97]
	v_pk_fma_f32 v[96:97], v[134:135], v[134:135], v[96:97]
	v_pk_fma_f32 v[96:97], v[136:137], v[136:137], v[96:97]
	v_pk_fma_f32 v[96:97], v[138:139], v[138:139], v[96:97]
	v_pk_fma_f32 v[96:97], v[140:141], v[140:141], v[96:97]
	v_pk_fma_f32 v[96:97], v[142:143], v[142:143], v[96:97]
	v_add_f32_e32 v96, v96, v97
	s_nop 1
	v_add_f32_dpp v97, v96, v96 quad_perm:[1,0,3,2] row_mask:0xf bank_mask:0xf
	s_nop 1
	v_add_f32_dpp v96, v97, v97 quad_perm:[2,3,0,1] row_mask:0xf bank_mask:0xf
	s_nop 1
	v_add_f32_dpp v97, v96, v96 row_half_mirror row_mask:0xf bank_mask:0xf
	s_nop 1
	v_add_f32_dpp v96, v97, v97 row_mirror row_mask:0xf bank_mask:0xf
	s_nop 1
	v_readlane_b32 s16, v96, 0
	v_readlane_b32 s17, v96, 16
	v_readlane_b32 s18, v96, 32
	v_readlane_b32 s19, v96, 48
	s_nop 1
	v_mov_b32_e32 v96, s16
	v_add_f32_e32 v96, s17, v96
	v_add_f32_e32 v96, s18, v96
	v_add_f32_e32 v96, s19, v96
	v_mov_b32_e32 v98, 0x358637bd
	v_fmamk_f32 v96, v96, 0x3a800000, v98
	v_rsq_f32_e32 v96, v96
	s_nop 0
	v_pk_mul_f32 v[128:129], v[128:129], v[96:97] op_sel_hi:[1,0]
	v_pk_mul_f32 v[130:131], v[130:131], v[96:97] op_sel_hi:[1,0]
	v_pk_mul_f32 v[132:133], v[132:133], v[96:97] op_sel_hi:[1,0]
	v_pk_mul_f32 v[134:135], v[134:135], v[96:97] op_sel_hi:[1,0]
	v_pk_mul_f32 v[136:137], v[136:137], v[96:97] op_sel_hi:[1,0]
	v_pk_mul_f32 v[138:139], v[138:139], v[96:97] op_sel_hi:[1,0]
	v_pk_mul_f32 v[140:141], v[140:141], v[96:97] op_sel_hi:[1,0]
	v_pk_mul_f32 v[142:143], v[142:143], v[96:97] op_sel_hi:[1,0]
	v_pk_mul_f32 v[128:129], v[48:49], v[128:129]
	v_pk_mul_f32 v[130:131], v[50:51], v[130:131]
	v_pk_mul_f32 v[132:133], v[52:53], v[132:133]
; __device__ __forceinline__ void store_bf4(bf16_t* p, f32x4 v) { uint2 o; o.x = pk2(v[0], v[1]); o.y = pk2(v[2], v[3]); *(uint2*)p = o; }
; __device__ __forceinline__ void norm_row_pre(const f32x4 (&v)[4], const float* __restrict__ g, const float* __restrict__ shift, const float* __restrict__ scale, bf16_t* __restrict__ dst, int lane) {
;     float ss = 0.f;
; #pragma unroll
;     for (int j = 0; j < 4; ++j) ss += v[j][0] * v[j][0] + v[j][1] * v[j][1] + v[j][2] * v[j][2] + v[j][3] * v[j][3];
;     ss = wave_sum(ss);
;     const float rstd = rsqrtf(ss * (1.f / 1024.f) + 1e-6f);
; #pragma unroll
;     for (int j = 0; j < 4; ++j) {
;         const int c4 = lane + 64 * j;
;         const f32x4 g4 = ((const f32x4*)g)[c4], sh = ((const f32x4*)shift)[c4], sc = ((const f32x4*)scale)[c4];
;         f32x4 h = (v[j] * rstd) * g4; h = h * (sc + 1.f) + sh;
;         store_bf4(dst + c4 * 4, h);
;     }
; }
; __device__ __forceinline__ void phase1(const Params& P) {
;     ...
;         const int stride = gridDim.x * 8;
;         int row = blockIdx.x * 8 + w;
;         f32x4 vn[4];
;         if (row < NT) { const float* src = row < NL ? P.in[0] + (size_t)row * 1024 : P.in[2] + (size_t)(row - NL) * 1024;
; #pragma unroll
;             for (int j = 0; j < 4; ++j) vn[j] = ((const f32x4*)src)[lane + 64 * j]; }
;         while (row < NT) {
;             f32x4 v[4];
; #pragma unroll
;             for (int j = 0; j < 4; ++j) v[j] = vn[j];
;             const int nrow = row + stride;
;             if (nrow < NT) { const float* src = nrow < NL ? P.in[0] + (size_t)nrow * 1024 : P.in[2] + (size_t)(nrow - NL) * 1024;
; #pragma unroll
;                 for (int j = 0; j < 4; ++j) vn[j] = ((const f32x4*)src)[lane + 64 * j]; }
;             const int mr = row < NL ? (row >> 13) : 4;
;             norm_row_pre(v, P.in[6], mod + mr * 9216 + 0, mod + mr * 9216 + 1024, H + (size_t)row * 1024, lane);
;             if (row >= NL) {
; #pragma unroll
;                 for (int j = 0; j < 4; ++j) ((f32x4*)((float*)(P.ws + OFF_E) + (size_t)(row - NL) * 1024))[lane + 64 * j] = v[j];
;             }
;             row = nrow;
;         }
	v_pk_mul_f32 v[134:135], v[54:55], v[134:135]
	v_pk_mul_f32 v[136:137], v[56:57], v[136:137]
	v_pk_mul_f32 v[138:139], v[58:59], v[138:139]
	v_pk_mul_f32 v[140:141], v[60:61], v[140:141]
	v_pk_mul_f32 v[142:143], v[62:63], v[142:143]
	v_pk_fma_f32 v[128:129], v[176:177], v[128:129], v[192:193]
	v_pk_fma_f32 v[130:131], v[178:179], v[130:131], v[194:195]
	v_pk_fma_f32 v[132:133], v[180:181], v[132:133], v[196:197]
	v_pk_fma_f32 v[134:135], v[182:183], v[134:135], v[198:199]
	v_pk_fma_f32 v[136:137], v[184:185], v[136:137], v[200:201]
	v_pk_fma_f32 v[138:139], v[186:187], v[138:139], v[202:203]
	v_pk_fma_f32 v[140:141], v[188:189], v[140:141], v[204:205]
	v_pk_fma_f32 v[142:143], v[190:191], v[142:143], v[206:207]
	v_cvt_pk_bf16_f32 v100, v128, v129
	v_cvt_pk_bf16_f32 v101, v130, v131
	v_cvt_pk_bf16_f32 v102, v132, v133
	v_cvt_pk_bf16_f32 v103, v134, v135
	v_cvt_pk_bf16_f32 v104, v136, v137
	v_cvt_pk_bf16_f32 v105, v138, v139
	v_cvt_pk_bf16_f32 v106, v140, v141
	v_cvt_pk_bf16_f32 v107, v142, v143
	s_add_u32 s8, s8, 0x400000
	s_addc_u32 s9, s9, 0
	global_store_dwordx2 v33, v[100:101], s[8:9]
	global_store_dwordx2 v33, v[102:103], s[8:9] offset:512
	global_store_dwordx2 v33, v[104:105], s[8:9] offset:1024
	global_store_dwordx2 v33, v[106:107], s[8:9] offset:1536
	s_lshl_b32 s10, s20, 12
	s_add_u32 s6, s40, s10
	s_addc_u32 s7, s41, 0
	global_load_dwordx4 v[128:131], v32, s[6:7]
	global_load_dwordx4 v[132:135], v32, s[6:7] offset:1024
	global_load_dwordx4 v[136:139], v32, s[6:7] offset:2048
	global_load_dwordx4 v[140:143], v32, s[6:7] offset:3072
	s_mov_b32 s10, 147456
	s_add_u32 s12, s2, s10
	s_addc_u32 s13, s3, 0
	s_add_u32 s14, s12, 0x1000
	s_addc_u32 s15, s13, 0
	global_load_dwordx4 v[80:83], v32, s[12:13]
	global_load_dwordx4 v[84:87], v32, s[12:13] offset:1024
	global_load_dwordx4 v[88:91], v32, s[12:13] offset:2048
	global_load_dwordx4 v[92:95], v32, s[12:13] offset:3072
	global_load_dwordx4 v[64:67], v32, s[14:15]
	global_load_dwordx4 v[68:71], v32, s[14:15] offset:1024
	global_load_dwordx4 v[72:75], v32, s[14:15] offset:2048
	global_load_dwordx4 v[76:79], v32, s[14:15] offset:3072
	s_waitcnt vmcnt(24)
	v_pk_mul_f32 v[96:97], v[144:145], v[144:145]
	v_pk_fma_f32 v[96:97], v[146:147], v[146:147], v[96:97]
	v_pk_fma_f32 v[96:97], v[148:149], v[148:149], v[96:97]
	v_pk_fma_f32 v[96:97], v[150:151], v[150:151], v[96:97]
	v_pk_fma_f32 v[96:97], v[152:153], v[152:153], v[96:97]
	v_pk_fma_f32 v[96:97], v[154:155], v[154:155], v[96:97]
	v_pk_fma_f32 v[96:97], v[156:157], v[156:157], v[96:97]
	v_pk_fma_f32 v[96:97], v[158:159], v[158:159], v[96:97]
	v_add_f32_e32 v96, v96, v97
	s_nop 1
	v_add_f32_dpp v97, v96, v96 quad_perm:[1,0,3,2] row_mask:0xf bank_mask:0xf
	s_nop 1
	v_add_f32_dpp v96, v97, v97 quad_perm:[2,3,0,1] row_mask:0xf bank_mask:0xf
	s_nop 1
	v_add_f32_dpp v97, v96, v96 row_half_mirror row_mask:0xf bank_mask:0xf
	s_nop 1
	v_add_f32_dpp v96, v97, v97 row_mirror row_mask:0xf bank_mask:0xf
	s_nop 1
	v_readlane_b32 s16, v96, 0
	v_readlane_b32 s17, v96, 16
	v_readlane_b32 s18, v96, 32
	v_readlane_b32 s19, v96, 48
	s_nop 1
	v_mov_b32_e32 v96, s16
	v_add_f32_e32 v96, s17, v96
	v_add_f32_e32 v96, s18, v96
	v_add_f32_e32 v96, s19, v96
	v_mov_b32_e32 v98, 0x358637bd
	v_fmamk_f32 v96, v96, 0x3a800000, v98
	v_rsq_f32_e32 v96, v96
	s_nop 0
	v_pk_mul_f32 v[144:145], v[144:145], v[96:97] op_sel_hi:[1,0]
	v_pk_mul_f32 v[146:147], v[146:147], v[96:97] op_sel_hi:[1,0]
	v_pk_mul_f32 v[148:149], v[148:149], v[96:97] op_sel_hi:[1,0]
	v_pk_mul_f32 v[150:151], v[150:151], v[96:97] op_sel_hi:[1,0]
	v_pk_mul_f32 v[152:153], v[152:153], v[96:97] op_sel_hi:[1,0]
	v_pk_mul_f32 v[154:155], v[154:155], v[96:97] op_sel_hi:[1,0]
	v_pk_mul_f32 v[156:157], v[156:157], v[96:97] op_sel_hi:[1,0]
	v_pk_mul_f32 v[158:159], v[158:159], v[96:97] op_sel_hi:[1,0]
	v_pk_mul_f32 v[144:145], v[48:49], v[144:145]
	v_pk_mul_f32 v[146:147], v[50:51], v[146:147]
	v_pk_mul_f32 v[148:149], v[52:53], v[148:149]
	v_pk_mul_f32 v[150:151], v[54:55], v[150:151]
	v_pk_mul_f32 v[152:153], v[56:57], v[152:153]
	v_pk_mul_f32 v[154:155], v[58:59], v[154:155]
	v_pk_mul_f32 v[156:157], v[60:61], v[156:157]
	v_pk_mul_f32 v[158:159], v[62:63], v[158:159]
	v_pk_fma_f32 v[144:145], v[176:177], v[144:145], v[192:193]
	v_pk_fma_f32 v[146:147], v[178:179], v[146:147], v[194:195]
	v_pk_fma_f32 v[148:149], v[180:181], v[148:149], v[196:197]
	v_pk_fma_f32 v[150:151], v[182:183], v[150:151], v[198:199]
	v_pk_fma_f32 v[152:153], v[184:185], v[152:153], v[200:201]
	v_pk_fma_f32 v[154:155], v[186:187], v[154:155], v[202:203]
	v_pk_fma_f32 v[156:157], v[188:189], v[156:157], v[204:205]
	v_pk_fma_f32 v[158:159], v[190:191], v[158:159], v[206:207]
	v_cvt_pk_bf16_f32 v100, v144, v145
	v_cvt_pk_bf16_f32 v101, v146, v147
	v_cvt_pk_bf16_f32 v102, v148, v149
	v_cvt_pk_bf16_f32 v103, v150, v151
	v_cvt_pk_bf16_f32 v104, v152, v153
	v_cvt_pk_bf16_f32 v105, v154, v155
	v_cvt_pk_bf16_f32 v106, v156, v157
	v_cvt_pk_bf16_f32 v107, v158, v159
	s_add_u32 s8, s8, 0x400000
	s_addc_u32 s9, s9, 0
	global_store_dwordx2 v33, v[100:101], s[8:9]
	global_store_dwordx2 v33, v[102:103], s[8:9] offset:512
	global_store_dwordx2 v33, v[104:105], s[8:9] offset:1024
	global_store_dwordx2 v33, v[106:107], s[8:9] offset:1536
	s_waitcnt vmcnt(20)
; __device__ __forceinline__ void store_bf4(bf16_t* p, f32x4 v) { uint2 o; o.x = pk2(v[0], v[1]); o.y = pk2(v[2], v[3]); *(uint2*)p = o; }
; __device__ __forceinline__ void norm_row_pre(const f32x4 (&v)[4], const float* __restrict__ g, const float* __restrict__ shift, const float* __restrict__ scale, bf16_t* __restrict__ dst, int lane) {
;     float ss = 0.f;
; #pragma unroll
;     for (int j = 0; j < 4; ++j) ss += v[j][0] * v[j][0] + v[j][1] * v[j][1] + v[j][2] * v[j][2] + v[j][3] * v[j][3];
;     ss = wave_sum(ss);
;     const float rstd = rsqrtf(ss * (1.f / 1024.f) + 1e-6f);
; #pragma unroll
;     for (int j = 0; j < 4; ++j) {
;         const int c4 = lane + 64 * j;
;         const f32x4 g4 = ((const f32x4*)g)[c4], sh = ((const f32x4*)shift)[c4], sc = ((const f32x4*)scale)[c4];
;         f32x4 h = (v[j] * rstd) * g4; h = h * (sc + 1.f) + sh;
;         store_bf4(dst + c4 * 4, h);
;     }
; }
; __device__ __forceinline__ void phase1(const Params& P) {
;     ...
;         const int stride = gridDim.x * 8;
;         int row = blockIdx.x * 8 + w;
;         f32x4 vn[4];
;         if (row < NT) { const float* src = row < NL ? P.in[0] + (size_t)row * 1024 : P.in[2] + (size_t)(row - NL) * 1024;
; #pragma unroll
;             for (int j = 0; j < 4; ++j) vn[j] = ((const f32x4*)src)[lane + 64 * j]; }
;         while (row < NT) {
;             f32x4 v[4];
; #pragma unroll
;             for (int j = 0; j < 4; ++j) v[j] = vn[j];
;             const int nrow = row + stride;
;             if (nrow < NT) { const float* src = nrow < NL ? P.in[0] + (size_t)nrow * 1024 : P.in[2] + (size_t)(nrow - NL) * 1024;
; #pragma unroll
;                 for (int j = 0; j < 4; ++j) vn[j] = ((const f32x4*)src)[lane + 64 * j]; }
;             const int mr = row < NL ? (row >> 13) : 4;
;             norm_row_pre(v, P.in[6], mod + mr * 9216 + 0, mod + mr * 9216 + 1024, H + (size_t)row * 1024, lane);
;             if (row >= NL) {
; #pragma unroll
;                 for (int j = 0; j < 4; ++j) ((f32x4*)((float*)(P.ws + OFF_E) + (size_t)(row - NL) * 1024))[lane + 64 * j] = v[j];
;             }
;             row = nrow;
;         }
	v_pk_mul_f32 v[96:97], v[112:113], v[112:113]
	v_pk_fma_f32 v[96:97], v[114:115], v[114:115], v[96:97]
	v_pk_fma_f32 v[96:97], v[116:117], v[116:117], v[96:97]
	v_pk_fma_f32 v[96:97], v[118:119], v[118:119], v[96:97]
	v_pk_fma_f32 v[96:97], v[120:121], v[120:121], v[96:97]
	v_pk_fma_f32 v[96:97], v[122:123], v[122:123], v[96:97]
	v_pk_fma_f32 v[96:97], v[124:125], v[124:125], v[96:97]
	v_pk_fma_f32 v[96:97], v[126:127], v[126:127], v[96:97]
	v_add_f32_e32 v96, v96, v97
	s_nop 1
	v_add_f32_dpp v97, v96, v96 quad_perm:[1,0,3,2] row_mask:0xf bank_mask:0xf
	s_nop 1
	v_add_f32_dpp v96, v97, v97 quad_perm:[2,3,0,1] row_mask:0xf bank_mask:0xf
	s_nop 1
	v_add_f32_dpp v97, v96, v96 row_half_mirror row_mask:0xf bank_mask:0xf
	s_nop 1
	v_add_f32_dpp v96, v97, v97 row_mirror row_mask:0xf bank_mask:0xf
	s_nop 1
	v_readlane_b32 s16, v96, 0
	v_readlane_b32 s17, v96, 16
	v_readlane_b32 s18, v96, 32
	v_readlane_b32 s19, v96, 48
	s_nop 1
	v_mov_b32_e32 v96, s16
	v_add_f32_e32 v96, s17, v96
	v_add_f32_e32 v96, s18, v96
	v_add_f32_e32 v96, s19, v96
	v_mov_b32_e32 v98, 0x358637bd
	v_fmamk_f32 v96, v96, 0x3a800000, v98
	v_rsq_f32_e32 v96, v96
	s_nop 0
	v_pk_mul_f32 v[112:113], v[112:113], v[96:97] op_sel_hi:[1,0]
	v_pk_mul_f32 v[114:115], v[114:115], v[96:97] op_sel_hi:[1,0]
	v_pk_mul_f32 v[116:117], v[116:117], v[96:97] op_sel_hi:[1,0]
	v_pk_mul_f32 v[118:119], v[118:119], v[96:97] op_sel_hi:[1,0]
	v_pk_mul_f32 v[120:121], v[120:121], v[96:97] op_sel_hi:[1,0]
	v_pk_mul_f32 v[122:123], v[122:123], v[96:97] op_sel_hi:[1,0]
	v_pk_mul_f32 v[124:125], v[124:125], v[96:97] op_sel_hi:[1,0]
	v_pk_mul_f32 v[126:127], v[126:127], v[96:97] op_sel_hi:[1,0]
	v_pk_mul_f32 v[112:113], v[48:49], v[112:113]
	v_pk_mul_f32 v[114:115], v[50:51], v[114:115]
	v_pk_mul_f32 v[116:117], v[52:53], v[116:117]
	v_pk_mul_f32 v[118:119], v[54:55], v[118:119]
	v_pk_mul_f32 v[120:121], v[56:57], v[120:121]
	v_pk_mul_f32 v[122:123], v[58:59], v[122:123]
	v_pk_mul_f32 v[124:125], v[60:61], v[124:125]
	v_pk_mul_f32 v[126:127], v[62:63], v[126:127]
	v_pk_fma_f32 v[112:113], v[176:177], v[112:113], v[192:193]
	v_pk_fma_f32 v[114:115], v[178:179], v[114:115], v[194:195]
	v_pk_fma_f32 v[116:117], v[180:181], v[116:117], v[196:197]
	v_pk_fma_f32 v[118:119], v[182:183], v[118:119], v[198:199]
	v_pk_fma_f32 v[120:121], v[184:185], v[120:121], v[200:201]
	v_pk_fma_f32 v[122:123], v[186:187], v[122:123], v[202:203]
	v_pk_fma_f32 v[124:125], v[188:189], v[124:125], v[204:205]
	v_pk_fma_f32 v[126:127], v[190:191], v[126:127], v[206:207]
	v_cvt_pk_bf16_f32 v100, v112, v113
	v_cvt_pk_bf16_f32 v101, v114, v115
	v_cvt_pk_bf16_f32 v102, v116, v117
	v_cvt_pk_bf16_f32 v103, v118, v119
	v_cvt_pk_bf16_f32 v104, v120, v121
	v_cvt_pk_bf16_f32 v105, v122, v123
	v_cvt_pk_bf16_f32 v106, v124, v125
	v_cvt_pk_bf16_f32 v107, v126, v127
	s_add_u32 s8, s8, 0x400000
	s_addc_u32 s9, s9, 0
	global_store_dwordx2 v33, v[100:101], s[8:9]
	global_store_dwordx2 v33, v[102:103], s[8:9] offset:512
	global_store_dwordx2 v33, v[104:105], s[8:9] offset:1024
	global_store_dwordx2 v33, v[106:107], s[8:9] offset:1536
	s_waitcnt vmcnt(8)
; __device__ __forceinline__ void store_bf4(bf16_t* p, f32x4 v) { uint2 o; o.x = pk2(v[0], v[1]); o.y = pk2(v[2], v[3]); *(uint2*)p = o; }
; __device__ __forceinline__ void norm_row_pre(const f32x4 (&v)[4], const float* __restrict__ g, const float* __restrict__ shift, const float* __restrict__ scale, bf16_t* __restrict__ dst, int lane) {
;     float ss = 0.f;
; #pragma unroll
;     for (int j = 0; j < 4; ++j) ss += v[j][0] * v[j][0] + v[j][1] * v[j][1] + v[j][2] * v[j][2] + v[j][3] * v[j][3];
;     ss = wave_sum(ss);
;     const float rstd = rsqrtf(ss * (1.f / 1024.f) + 1e-6f);
; #pragma unroll
;     for (int j = 0; j < 4; ++j) {
;         const int c4 = lane + 64 * j;
;         const f32x4 g4 = ((const f32x4*)g)[c4], sh = ((const f32x4*)shift)[c4], sc = ((const f32x4*)scale)[c4];
;         f32x4 h = (v[j] * rstd) * g4; h = h * (sc + 1.f) + sh;
;         store_bf4(dst + c4 * 4, h);
;     }
; }
; __device__ __forceinline__ void phase1(const Params& P) {
;     ...
;             if (nrow < NT) { const float* src = nrow < NL ? P.in[0] + (size_t)nrow * 1024 : P.in[2] + (size_t)(nrow - NL) * 1024;
; #pragma unroll
;                 for (int j = 0; j < 4; ++j) vn[j] = ((const f32x4*)src)[lane + 64 * j]; }
;             const int mr = row < NL ? (row >> 13) : 4;
;             norm_row_pre(v, P.in[6], mod + mr * 9216 + 0, mod + mr * 9216 + 1024, H + (size_t)row * 1024, lane);
;             if (row >= NL) {
; #pragma unroll
;                 for (int j = 0; j < 4; ++j) ((f32x4*)((float*)(P.ws + OFF_E) + (size_t)(row - NL) * 1024))[lane + 64 * j] = v[j];
;             }
;             row = nrow;
;         }
	v_pk_add_f32 v[64:65], v[64:65], 1.0 op_sel_hi:[1,0]
	v_pk_add_f32 v[66:67], v[66:67], 1.0 op_sel_hi:[1,0]
	v_pk_add_f32 v[68:69], v[68:69], 1.0 op_sel_hi:[1,0]
	v_pk_add_f32 v[70:71], v[70:71], 1.0 op_sel_hi:[1,0]
	v_pk_add_f32 v[72:73], v[72:73], 1.0 op_sel_hi:[1,0]
	v_pk_add_f32 v[74:75], v[74:75], 1.0 op_sel_hi:[1,0]
	v_pk_add_f32 v[76:77], v[76:77], 1.0 op_sel_hi:[1,0]
	v_pk_add_f32 v[78:79], v[78:79], 1.0 op_sel_hi:[1,0]
	v_pk_mul_f32 v[96:97], v[128:129], v[128:129]
	v_pk_fma_f32 v[96:97], v[130:131], v[130:131], v[96:97]
	v_pk_fma_f32 v[96:97], v[132:133], v[132:133], v[96:97]
	v_pk_fma_f32 v[96:97], v[134:135], v[134:135], v[96:97]
	v_pk_fma_f32 v[96:97], v[136:137], v[136:137], v[96:97]
	v_pk_fma_f32 v[96:97], v[138:139], v[138:139], v[96:97]
	v_pk_fma_f32 v[96:97], v[140:141], v[140:141], v[96:97]
	v_pk_fma_f32 v[96:97], v[142:143], v[142:143], v[96:97]
	v_add_f32_e32 v96, v96, v97
	s_nop 1
	v_add_f32_dpp v97, v96, v96 quad_perm:[1,0,3,2] row_mask:0xf bank_mask:0xf
	s_nop 1
	v_add_f32_dpp v96, v97, v97 quad_perm:[2,3,0,1] row_mask:0xf bank_mask:0xf
	s_nop 1
	v_add_f32_dpp v97, v96, v96 row_half_mirror row_mask:0xf bank_mask:0xf
	s_nop 1
	v_add_f32_dpp v96, v97, v97 row_mirror row_mask:0xf bank_mask:0xf
	s_nop 1
	v_readlane_b32 s16, v96, 0
	v_readlane_b32 s17, v96, 16
	v_readlane_b32 s18, v96, 32
	v_readlane_b32 s19, v96, 48
	s_nop 1
	v_mov_b32_e32 v96, s16
	v_add_f32_e32 v96, s17, v96
	v_add_f32_e32 v96, s18, v96
	v_add_f32_e32 v96, s19, v96
	v_mov_b32_e32 v98, 0x358637bd
	v_fmamk_f32 v96, v96, 0x3a800000, v98
	v_rsq_f32_e32 v96, v96
	s_lshl_b32 s10, s20, 12
	s_add_u32 s12, s68, s10
	s_addc_u32 s13, s69, 0
	s_add_u32 s12, s12, 0x1ce3d000
	s_addc_u32 s13, s13, 0
	global_store_dwordx4 v32, v[128:131], s[12:13]
	global_store_dwordx4 v32, v[132:135], s[12:13] offset:1024
	global_store_dwordx4 v32, v[136:139], s[12:13] offset:2048
	global_store_dwordx4 v32, v[140:143], s[12:13] offset:3072
	v_pk_mul_f32 v[128:129], v[128:129], v[96:97] op_sel_hi:[1,0]
	v_pk_mul_f32 v[130:131], v[130:131], v[96:97] op_sel_hi:[1,0]
	v_pk_mul_f32 v[132:133], v[132:133], v[96:97] op_sel_hi:[1,0]
	v_pk_mul_f32 v[134:135], v[134:135], v[96:97] op_sel_hi:[1,0]
	v_pk_mul_f32 v[136:137], v[136:137], v[96:97] op_sel_hi:[1,0]
	v_pk_mul_f32 v[138:139], v[138:139], v[96:97] op_sel_hi:[1,0]
	v_pk_mul_f32 v[140:141], v[140:141], v[96:97] op_sel_hi:[1,0]
	v_pk_mul_f32 v[142:143], v[142:143], v[96:97] op_sel_hi:[1,0]
	v_pk_mul_f32 v[128:129], v[48:49], v[128:129]
	v_pk_mul_f32 v[130:131], v[50:51], v[130:131]
	v_pk_mul_f32 v[132:133], v[52:53], v[132:133]
	v_pk_mul_f32 v[134:135], v[54:55], v[134:135]
	v_pk_mul_f32 v[136:137], v[56:57], v[136:137]
	v_pk_mul_f32 v[138:139], v[58:59], v[138:139]
	v_pk_mul_f32 v[140:141], v[60:61], v[140:141]
	v_pk_mul_f32 v[142:143], v[62:63], v[142:143]
	v_pk_fma_f32 v[128:129], v[64:65], v[128:129], v[80:81]
	v_pk_fma_f32 v[130:131], v[66:67], v[130:131], v[82:83]
	v_pk_fma_f32 v[132:133], v[68:69], v[132:133], v[84:85]
	v_pk_fma_f32 v[134:135], v[70:71], v[134:135], v[86:87]
	v_pk_fma_f32 v[136:137], v[72:73], v[136:137], v[88:89]
	v_pk_fma_f32 v[138:139], v[74:75], v[138:139], v[90:91]
	v_pk_fma_f32 v[140:141], v[76:77], v[140:141], v[92:93]
	v_pk_fma_f32 v[142:143], v[78:79], v[142:143], v[94:95]
	v_cvt_pk_bf16_f32 v100, v128, v129
	v_cvt_pk_bf16_f32 v101, v130, v131
	v_cvt_pk_bf16_f32 v102, v132, v133
	v_cvt_pk_bf16_f32 v103, v134, v135
	v_cvt_pk_bf16_f32 v104, v136, v137
	v_cvt_pk_bf16_f32 v105, v138, v139
	v_cvt_pk_bf16_f32 v106, v140, v141
	v_cvt_pk_bf16_f32 v107, v142, v143
	s_add_u32 s10, s20, 0x8000
	s_lshl_b32 s11, s10, 11
	s_lshr_b32 s10, s10, 21
	s_add_u32 s8, s68, s11
	s_addc_u32 s9, s69, s10
	s_add_u32 s8, s8, 0x52bd000
	s_addc_u32 s9, s9, 0
	global_store_dwordx2 v33, v[100:101], s[8:9]
	global_store_dwordx2 v33, v[102:103], s[8:9] offset:512
	global_store_dwordx2 v33, v[104:105], s[8:9] offset:1024
	global_store_dwordx2 v33, v[106:107], s[8:9] offset:1536
	s_branch .Lp1n_done
	s_nop 0
	s_nop 0
	s_nop 0
	s_nop 0
	s_nop 0
	s_nop 0
	s_nop 0
	s_nop 0
	s_nop 0
	s_nop 0
	s_nop 0

; __device__ __forceinline__ float bflo(unsigned u) { return __uint_as_float(u << 16); }
; __device__ __forceinline__ float bfhi(unsigned u) { return __uint_as_float(u & 0xffff0000u); }
; __device__ __forceinline__ float wave_sum(float v) {
; #pragma unroll
;     for (int o = 1; o < 64; o <<= 1) v += __shfl_xor(v, o);
;     return v;
; }
; __device__ __forceinline__ void phase1(const Params& P) {
;     ...
;     for (int r0 = blockIdx.x * 32 + w * 4; r0 < 4352 + 5632; r0 += gridDim.x * 32) {
;         const bool first = r0 < 4352;
;         const bf16_t* wt = first ? (const bf16_t*)(P.ws + OFF_WIN) + (size_t)r0 * 1024 : (const bf16_t*)(P.ws + OFF_WGU2) + (size_t)(r0 - 4352) * 1024;
;         const float* sh = mod + (first ? 3 : 6) * 1024 + lane * 16;
;         uint4 wq[4][2];
; #pragma unroll
;         for (int i = 0; i < 4; ++i) { wq[i][0] = *(const uint4*)(wt + (size_t)i * 1024 + lane * 16); wq[i][1] = *(const uint4*)(wt + (size_t)i * 1024 + lane * 16 + 8); }
;         f32x4 s4[5][4];
; #pragma unroll
;         for (int mr = 0; mr < 5; ++mr)
; #pragma unroll
;             for (int q = 0; q < 4; ++q) s4[mr][q] = *(const f32x4*)(sh + mr * 9216 + q * 4);
;         float* BW = (float*)(P.ws + OFF_BW);
; #pragma unroll
;         for (int i = 0; i < 4; ++i) {
;             const uint4 w0 = wq[i][0], w1 = wq[i][1];
;             const float wv[16] = {bflo(w0.x), bfhi(w0.x), bflo(w0.y), bfhi(w0.y), bflo(w0.z), bfhi(w0.z), bflo(w0.w), bfhi(w0.w),
;                                   bflo(w1.x), bfhi(w1.x), bflo(w1.y), bfhi(w1.y), bflo(w1.z), bfhi(w1.z), bflo(w1.w), bfhi(w1.w)};
;             const int r = r0 + i;
; #pragma unroll
;             for (int mr = 0; mr < 5; ++mr) {
;                 float a = 0.f;
; #pragma unroll
;                 for (int q = 0; q < 4; ++q) a += s4[mr][q][0] * wv[q * 4] + s4[mr][q][1] * wv[q * 4 + 1] + s4[mr][q][2] * wv[q * 4 + 2] + s4[mr][q][3] * wv[q * 4 + 3];
;                 a = wave_sum(a);
;                 if (lane == 0) { if (first) BW[mr * 4352 + r] = a; else BW[5 * 4352 + mr * 5632 + (r - 4352)] = a; }
;             }
;         }
;     }
.LBB0_142:
	v_add_u32_e32 v0, 0xffffef00, v104
	v_ashrrev_i32_e32 v105, 31, v104
	v_cmp_gt_i32_e64 s[4:5], s34, v104
	v_cmp_lt_i32_e64 s[6:7], s31, v104
	s_waitcnt lgkmcnt(0)
	v_cndmask_b32_e64 v1, 0, v105, s[4:5]
	v_cndmask_b32_e64 v0, v0, v104, s[4:5]
	v_cndmask_b32_e64 v106, v120, v121, s[4:5]
	v_lshl_add_u64 v[2:3], s[68:69], 0, v[106:107]
	v_lshlrev_b64 v[0:1], 11, v[0:1]
	v_lshl_add_u64 v[0:1], v[2:3], 0, v[0:1]
	v_lshl_add_u64 v[0:1], v[0:1], 0, v[110:111]
	global_load_dwordx4 v[148:151], v[0:1], off
	global_load_dwordx4 v[164:167], v[0:1], off offset:16
	v_cndmask_b32_e64 v106, v122, v123, s[4:5]
	v_lshl_add_u64 v[2:3], v[108:109], 0, v[106:107]
	global_load_dwordx4 v[56:59], v[2:3], off
	global_load_dwordx4 v[48:51], v[2:3], off offset:16
	global_load_dwordx4 v[40:43], v[2:3], off offset:32
	global_load_dwordx4 v[36:39], v[2:3], off offset:48
	v_add_co_u32_e32 v6, vcc, s38, v2
	v_lshl_add_u64 v[4:5], v[2:3], 0, s[18:19]
	s_nop 0
	v_addc_co_u32_e32 v7, vcc, 0, v3, vcc
	v_add_co_u32_e32 v10, vcc, s39, v2
	v_lshl_add_u64 v[8:9], v[2:3], 0, s[20:21]
	s_nop 0
	v_addc_co_u32_e32 v11, vcc, 0, v3, vcc
	v_add_co_u32_e32 v14, vcc, s40, v2
	v_lshl_add_u64 v[12:13], v[2:3], 0, s[22:23]
	s_nop 0
	v_addc_co_u32_e32 v15, vcc, 0, v3, vcc
	v_lshl_add_u64 v[80:81], v[2:3], 0, s[24:25]
	v_add_co_u32_e32 v2, vcc, s41, v2
	v_lshl_add_u64 v[82:83], v[0:1], 0, s[14:15]
	s_nop 0
	v_addc_co_u32_e32 v3, vcc, 0, v3, vcc
	v_add_co_u32_e32 v84, vcc, s35, v0
	global_load_dwordx4 v[96:99], v[0:1], off offset:2064
	global_load_dwordx4 v[100:103], v[0:1], off offset:2048
	v_addc_co_u32_e32 v85, vcc, 0, v1, vcc
	v_lshl_add_u64 v[112:113], v[0:1], 0, s[16:17]
	global_load_dwordx4 v[76:79], v[6:7], off
	global_load_dwordx4 v[64:67], v[4:5], off offset:48
	global_load_dwordx4 v[68:71], v[4:5], off offset:32
	global_load_dwordx4 v[72:75], v[4:5], off offset:16
	global_load_dwordx4 v[60:63], v[10:11], off
	global_load_dwordx4 v[32:35], v[8:9], off offset:48
	global_load_dwordx4 v[44:47], v[8:9], off offset:32
	global_load_dwordx4 v[52:55], v[8:9], off offset:16
	global_load_dwordx4 v[28:31], v[14:15], off
	global_load_dwordx4 v[16:19], v[12:13], off offset:48
	global_load_dwordx4 v[20:23], v[12:13], off offset:32
	global_load_dwordx4 v[24:27], v[12:13], off offset:16
	s_nop 0
	global_load_dwordx4 v[12:15], v[2:3], off
	s_nop 0
	global_load_dwordx4 v[0:3], v[80:81], off offset:48
	global_load_dwordx4 v[4:7], v[80:81], off offset:32
	global_load_dwordx4 v[8:11], v[80:81], off offset:16
	global_load_dwordx4 v[92:95], v[84:85], off
	global_load_dwordx4 v[88:91], v[82:83], off offset:16
	s_nop 0
	global_load_dwordx4 v[84:87], v[84:85], off offset:2048
	s_nop 0
	global_load_dwordx4 v[80:83], v[112:113], off offset:16
	s_waitcnt vmcnt(27)
	v_and_b32_e32 v162, 0xffff0000, v148
	v_lshlrev_b32_e32 v160, 16, v148
	v_and_b32_e32 v159, 0xffff0000, v150
	s_waitcnt vmcnt(25)
	v_mul_f32_e32 v106, v57, v162
	v_lshlrev_b32_e32 v161, 16, v149
	v_lshlrev_b32_e32 v156, 16, v150
	v_and_b32_e32 v155, 0xffff0000, v164
	s_waitcnt vmcnt(24)
	v_mul_f32_e32 v112, v49, v159
	v_fmac_f32_e32 v106, v56, v160
	v_and_b32_e32 v158, 0xffff0000, v149
	v_lshlrev_b32_e32 v157, 16, v151
	v_and_b32_e32 v154, 0xffff0000, v151
	v_lshlrev_b32_e32 v152, 16, v164
	v_and_b32_e32 v151, 0xffff0000, v166
	s_waitcnt vmcnt(23)
	v_mul_f32_e32 v163, v41, v155
	v_fmac_f32_e32 v112, v48, v156
	v_fmac_f32_e32 v106, v58, v161
	v_lshlrev_b32_e32 v153, 16, v165
	v_lshlrev_b32_e32 v148, 16, v166
	s_waitcnt vmcnt(22)
	v_mul_f32_e32 v164, v37, v151
	v_fmac_f32_e32 v163, v40, v152
	v_fmac_f32_e32 v112, v50, v157
	v_fmac_f32_e32 v106, v59, v158
	v_and_b32_e32 v150, 0xffff0000, v165
	v_lshlrev_b32_e32 v149, 16, v167
	v_fmac_f32_e32 v164, v36, v148
	v_fmac_f32_e32 v163, v42, v153
	v_fmac_f32_e32 v112, v51, v154
	v_add_f32_e32 v106, 0, v106
	v_and_b32_e32 v113, 0xffff0000, v167
	v_fmac_f32_e32 v164, v38, v149
	v_fmac_f32_e32 v163, v43, v150
	v_add_f32_e32 v106, v106, v112
	v_fmac_f32_e32 v164, v39, v113
	v_add_f32_e32 v106, v106, v163
	v_add_f32_e32 v106, v106, v164
	s_nop 1
	v_add_f32_dpp v112, v106, v106 quad_perm:[1,0,3,2] row_mask:0xf bank_mask:0xf
	s_nop 1
	v_add_f32_dpp v106, v112, v112 quad_perm:[2,3,0,1] row_mask:0xf bank_mask:0xf
	s_nop 1
	v_add_f32_dpp v112, v106, v106 row_half_mirror row_mask:0xf bank_mask:0xf
	s_nop 1
	v_add_f32_dpp v106, v112, v112 row_mirror row_mask:0xf bank_mask:0xf
	s_nop 1
	v_readlane_b32 s98, v106, 0
	v_readlane_b32 s99, v106, 16
	v_readlane_b32 s100, v106, 32
	v_readlane_b32 s101, v106, 48
	s_nop 1
	v_mov_b32_e32 v106, s98
	v_add_f32_e32 v106, s99, v106
	v_add_f32_e32 v106, s100, v106
	v_add_f32_e32 v106, s101, v106
	v_mov_b32_e32 v163, 0
	v_add_u32_e32 v112, 0x4400, v104
	s_and_saveexec_b64 s[26:27], s[2:3]
	s_cbranch_execz .LBB0_144
	v_cndmask_b32_e64 v165, 0, v105, s[4:5]
	v_cndmask_b32_e64 v164, v112, v104, s[4:5]
	v_lshl_add_u64 v[164:165], v[164:165], 2, s[10:11]
	s_waitcnt lgkmcnt(0)
	v_add_f32_e32 v106, v106, v163
	global_store_dword v[164:165], v106, off
; __device__ __forceinline__ float bflo(unsigned u) { return __uint_as_float(u << 16); }
; __device__ __forceinline__ float bfhi(unsigned u) { return __uint_as_float(u & 0xffff0000u); }
; __device__ __forceinline__ float wave_sum(float v) {
; #pragma unroll
;     for (int o = 1; o < 64; o <<= 1) v += __shfl_xor(v, o);
;     return v;
; }
; __device__ __forceinline__ void phase1(const Params& P) {
;     ...
;         for (int i = 0; i < 4; ++i) {
;             const uint4 w0 = wq[i][0], w1 = wq[i][1];
;             const float wv[16] = {bflo(w0.x), bfhi(w0.x), bflo(w0.y), bfhi(w0.y), bflo(w0.z), bfhi(w0.z), bflo(w0.w), bfhi(w0.w),
;                                   bflo(w1.x), bfhi(w1.x), bflo(w1.y), bfhi(w1.y), bflo(w1.z), bfhi(w1.z), bflo(w1.w), bfhi(w1.w)};
;             const int r = r0 + i;
; #pragma unroll
;             for (int mr = 0; mr < 5; ++mr) {
;                 float a = 0.f;
; #pragma unroll
;                 for (int q = 0; q < 4; ++q) a += s4[mr][q][0] * wv[q * 4] + s4[mr][q][1] * wv[q * 4 + 1] + s4[mr][q][2] * wv[q * 4 + 2] + s4[mr][q][3] * wv[q * 4 + 3];
;                 a = wave_sum(a);
;                 if (lane == 0) { if (first) BW[mr * 4352 + r] = a; else BW[5 * 4352 + mr * 5632 + (r - 4352)] = a; }
;             }
.LBB0_144:
	s_or_b64 exec, exec, s[26:27]
	s_waitcnt vmcnt(19)
	v_mul_f32_e32 v106, v77, v162
	v_fmac_f32_e32 v106, v76, v160
	s_waitcnt vmcnt(16) lgkmcnt(0)
	v_mul_f32_e32 v163, v73, v159
	v_fmac_f32_e32 v106, v78, v161
	v_fmac_f32_e32 v163, v72, v156
	v_fmac_f32_e32 v106, v79, v158
	v_fmac_f32_e32 v163, v74, v157
	v_add_f32_e32 v106, 0, v106
	v_fmac_f32_e32 v163, v75, v154
	v_add_f32_e32 v106, v106, v163
	v_mul_f32_e32 v163, v69, v155
	v_fmac_f32_e32 v163, v68, v152
	v_fmac_f32_e32 v163, v70, v153
	v_fmac_f32_e32 v163, v71, v150
	v_add_f32_e32 v106, v106, v163
	v_mul_f32_e32 v163, v65, v151
	v_fmac_f32_e32 v163, v64, v148
	v_fmac_f32_e32 v163, v66, v149
	v_fmac_f32_e32 v163, v67, v113
	v_add_f32_e32 v106, v106, v163
	s_nop 1
	v_add_f32_dpp v163, v106, v106 quad_perm:[1,0,3,2] row_mask:0xf bank_mask:0xf
	s_nop 1
	v_add_f32_dpp v106, v163, v163 quad_perm:[2,3,0,1] row_mask:0xf bank_mask:0xf
	s_nop 1
	v_add_f32_dpp v163, v106, v106 row_half_mirror row_mask:0xf bank_mask:0xf
	s_nop 1
	v_add_f32_dpp v106, v163, v163 row_mirror row_mask:0xf bank_mask:0xf
	s_nop 1
	v_readlane_b32 s98, v106, 0
	v_readlane_b32 s99, v106, 16
	v_readlane_b32 s100, v106, 32
	v_readlane_b32 s101, v106, 48
	s_nop 1
	v_mov_b32_e32 v163, s98
	v_add_f32_e32 v163, s99, v163
	v_add_f32_e32 v163, s100, v163
	v_add_f32_e32 v163, s101, v163
	v_mov_b32_e32 v164, 0
	s_and_saveexec_b64 s[26:27], s[2:3]
	s_cbranch_execz .LBB0_146
	v_lshl_add_u64 v[166:167], v[104:105], 2, s[10:11]
	v_cndmask_b32_e64 v106, v124, v125, s[4:5]
	v_lshl_add_u64 v[166:167], v[166:167], 0, v[106:107]
	s_waitcnt lgkmcnt(0)
	v_add_f32_e32 v106, v163, v164
	global_store_dword v[166:167], v106, off
.LBB0_146:
	s_or_b64 exec, exec, s[26:27]
	s_waitcnt vmcnt(15)
	v_mul_f32_e32 v106, v61, v162
	v_fmac_f32_e32 v106, v60, v160
	s_waitcnt vmcnt(12)
	v_mul_f32_e32 v163, v53, v159
	v_fmac_f32_e32 v106, v62, v161
	v_fmac_f32_e32 v163, v52, v156
	v_fmac_f32_e32 v106, v63, v158
	v_fmac_f32_e32 v163, v54, v157
	v_add_f32_e32 v106, 0, v106
	v_fmac_f32_e32 v163, v55, v154
	v_add_f32_e32 v106, v106, v163
	v_mul_f32_e32 v163, v45, v155
	v_fmac_f32_e32 v163, v44, v152
	v_fmac_f32_e32 v163, v46, v153
	v_fmac_f32_e32 v163, v47, v150
	v_add_f32_e32 v106, v106, v163
	v_mul_f32_e32 v163, v33, v151
	v_fmac_f32_e32 v163, v32, v148
	v_fmac_f32_e32 v163, v34, v149
	v_fmac_f32_e32 v163, v35, v113
	v_add_f32_e32 v106, v106, v163
	s_nop 1
	v_add_f32_dpp v163, v106, v106 quad_perm:[1,0,3,2] row_mask:0xf bank_mask:0xf
	s_nop 1
	v_add_f32_dpp v106, v163, v163 quad_perm:[2,3,0,1] row_mask:0xf bank_mask:0xf
	s_nop 1
	v_add_f32_dpp v163, v106, v106 row_half_mirror row_mask:0xf bank_mask:0xf
	s_nop 1
	v_add_f32_dpp v106, v163, v163 row_mirror row_mask:0xf bank_mask:0xf
	s_nop 1
	v_readlane_b32 s98, v106, 0
	v_readlane_b32 s99, v106, 16
	v_readlane_b32 s100, v106, 32
	v_readlane_b32 s101, v106, 48
	s_nop 1
	v_mov_b32_e32 v163, s98
	v_add_f32_e32 v163, s99, v163
	v_add_f32_e32 v163, s100, v163
	v_add_f32_e32 v163, s101, v163
	v_mov_b32_e32 v164, 0
	s_and_saveexec_b64 s[26:27], s[2:3]
	s_cbranch_execz .LBB0_148
	v_lshl_add_u64 v[166:167], v[104:105], 2, s[10:11]
	v_cndmask_b32_e64 v106, v126, v127, s[4:5]
	v_lshl_add_u64 v[166:167], v[166:167], 0, v[106:107]
	s_waitcnt lgkmcnt(0)
	v_add_f32_e32 v106, v163, v164
	global_store_dword v[166:167], v106, off
.LBB0_148:
	s_or_b64 exec, exec, s[26:27]
	s_waitcnt vmcnt(11)
	v_mul_f32_e32 v106, v29, v162
	v_fmac_f32_e32 v106, v28, v160
	s_waitcnt vmcnt(8)
	v_mul_f32_e32 v163, v25, v159
	v_fmac_f32_e32 v106, v30, v161
	v_fmac_f32_e32 v163, v24, v156
	v_fmac_f32_e32 v106, v31, v158
	v_fmac_f32_e32 v163, v26, v157
	v_add_f32_e32 v106, 0, v106
	v_fmac_f32_e32 v163, v27, v154
	v_add_f32_e32 v106, v106, v163
	v_mul_f32_e32 v163, v21, v155
	v_fmac_f32_e32 v163, v20, v152
	v_fmac_f32_e32 v163, v22, v153
	v_fmac_f32_e32 v163, v23, v150
	v_add_f32_e32 v106, v106, v163
	v_mul_f32_e32 v163, v17, v151
	v_fmac_f32_e32 v163, v16, v148
	v_fmac_f32_e32 v163, v18, v149
	v_fmac_f32_e32 v163, v19, v113
	v_add_f32_e32 v106, v106, v163
	s_nop 1
	v_add_f32_dpp v163, v106, v106 quad_perm:[1,0,3,2] row_mask:0xf bank_mask:0xf
	s_nop 1
	v_add_f32_dpp v106, v163, v163 quad_perm:[2,3,0,1] row_mask:0xf bank_mask:0xf
	s_nop 1
	v_add_f32_dpp v163, v106, v106 row_half_mirror row_mask:0xf bank_mask:0xf
	s_nop 1
	v_add_f32_dpp v106, v163, v163 row_mirror row_mask:0xf bank_mask:0xf
	s_nop 1
	v_readlane_b32 s98, v106, 0
	v_readlane_b32 s99, v106, 16
	v_readlane_b32 s100, v106, 32
	v_readlane_b32 s101, v106, 48
	s_nop 1
	v_mov_b32_e32 v163, s98
	v_add_f32_e32 v163, s99, v163
	v_add_f32_e32 v163, s100, v163
	v_add_f32_e32 v163, s101, v163
	v_mov_b32_e32 v164, 0
	s_and_saveexec_b64 s[26:27], s[2:3]
	s_cbranch_execz .LBB0_150
	v_lshl_add_u64 v[166:167], v[104:105], 2, s[10:11]
	v_cndmask_b32_e64 v106, v128, v129, s[4:5]
	v_lshl_add_u64 v[166:167], v[166:167], 0, v[106:107]
	s_waitcnt lgkmcnt(0)
	v_add_f32_e32 v106, v163, v164
	global_store_dword v[166:167], v106, off
.LBB0_150:
	s_or_b64 exec, exec, s[26:27]
	s_waitcnt vmcnt(7)
	v_mul_f32_e32 v106, v13, v162
	v_fmac_f32_e32 v106, v12, v160
	v_fmac_f32_e32 v106, v14, v161
	v_fmac_f32_e32 v106, v15, v158
	s_waitcnt vmcnt(4)
	v_mul_f32_e32 v158, v9, v159
	v_fmac_f32_e32 v158, v8, v156
	v_fmac_f32_e32 v158, v10, v157
	v_fmac_f32_e32 v158, v11, v154
	v_mul_f32_e32 v154, v5, v155
	v_fmac_f32_e32 v154, v4, v152
	v_fmac_f32_e32 v154, v6, v153
	v_fmac_f32_e32 v154, v7, v150
	v_mul_f32_e32 v150, v1, v151
	v_add_f32_e32 v106, 0, v106
	v_fmac_f32_e32 v150, v0, v148
	v_add_f32_e32 v106, v106, v158
	v_fmac_f32_e32 v150, v2, v149
	v_add_f32_e32 v106, v106, v154
	v_fmac_f32_e32 v150, v3, v113
	v_add_f32_e32 v106, v106, v150
	s_nop 1
	v_add_f32_dpp v113, v106, v106 quad_perm:[1,0,3,2] row_mask:0xf bank_mask:0xf
	s_nop 1
	v_add_f32_dpp v106, v113, v113 quad_perm:[2,3,0,1] row_mask:0xf bank_mask:0xf
	s_nop 1
	v_add_f32_dpp v113, v106, v106 row_half_mirror row_mask:0xf bank_mask:0xf
	s_nop 1
	v_add_f32_dpp v106, v113, v113 row_mirror row_mask:0xf bank_mask:0xf
	s_nop 1
	v_readlane_b32 s98, v106, 0
	v_readlane_b32 s99, v106, 16
	v_readlane_b32 s100, v106, 32
	v_readlane_b32 s101, v106, 48
	s_nop 1
	v_mov_b32_e32 v106, s98
	v_add_f32_e32 v106, s99, v106
	v_add_f32_e32 v106, s100, v106
	v_add_f32_e32 v106, s101, v106
	v_mov_b32_e32 v113, 0
	s_and_saveexec_b64 s[26:27], s[2:3]
	s_cbranch_execz .LBB0_155
	s_waitcnt lgkmcnt(0)
	v_add_f32_e32 v106, v106, v113
	s_and_saveexec_b64 s[28:29], s[6:7]
	s_xor_b64 s[28:29], exec, s[28:29]
	s_cbranch_execz .LBB0_153
	v_lshl_add_u64 v[112:113], v[104:105], 2, s[10:11]
	v_add_co_u32_e32 v112, vcc, 0x27000, v112
	s_nop 1
	v_addc_co_u32_e32 v113, vcc, 0, v113, vcc
	global_store_dword v[112:113], v106, off

; __device__ __forceinline__ float bflo(unsigned u) { return __uint_as_float(u << 16); }
; __device__ __forceinline__ float bfhi(unsigned u) { return __uint_as_float(u & 0xffff0000u); }
; __device__ __forceinline__ float wave_sum(float v) {
; #pragma unroll
;     for (int o = 1; o < 64; o <<= 1) v += __shfl_xor(v, o);
;     return v;
; }
; __device__ __forceinline__ void phase1(const Params& P) {
;     ...
;         for (int i = 0; i < 4; ++i) {
;             const uint4 w0 = wq[i][0], w1 = wq[i][1];
;             const float wv[16] = {bflo(w0.x), bfhi(w0.x), bflo(w0.y), bfhi(w0.y), bflo(w0.z), bfhi(w0.z), bflo(w0.w), bfhi(w0.w),
;                                   bflo(w1.x), bfhi(w1.x), bflo(w1.y), bfhi(w1.y), bflo(w1.z), bfhi(w1.z), bflo(w1.w), bfhi(w1.w)};
;             const int r = r0 + i;
; #pragma unroll
;             for (int mr = 0; mr < 5; ++mr) {
;                 float a = 0.f;
; #pragma unroll
;                 for (int q = 0; q < 4; ++q) a += s4[mr][q][0] * wv[q * 4] + s4[mr][q][1] * wv[q * 4 + 1] + s4[mr][q][2] * wv[q * 4 + 2] + s4[mr][q][3] * wv[q * 4 + 3];
;                 a = wave_sum(a);
;                 if (lane == 0) { if (first) BW[mr * 4352 + r] = a; else BW[5 * 4352 + mr * 5632 + (r - 4352)] = a; }
;             }
.LBB0_155:
	s_or_b64 exec, exec, s[26:27]
	v_and_b32_e32 v155, 0xffff0000, v100
	v_lshlrev_b32_e32 v153, 16, v100
	v_and_b32_e32 v152, 0xffff0000, v102
	v_lshlrev_b32_e32 v150, 16, v103
	s_waitcnt lgkmcnt(0)
	v_and_b32_e32 v113, 0xffff0000, v103
	v_lshlrev_b32_e32 v103, 16, v96
	v_and_b32_e32 v148, 0xffff0000, v96
	v_mul_f32_e32 v96, v57, v155
	v_lshlrev_b32_e32 v154, 16, v101
	v_and_b32_e32 v151, 0xffff0000, v101
	v_lshlrev_b32_e32 v149, 16, v102
	v_lshlrev_b32_e32 v112, 16, v97
	v_and_b32_e32 v101, 0xffff0000, v97
	v_lshlrev_b32_e32 v100, 16, v98
	v_and_b32_e32 v102, 0xffff0000, v98
	v_lshlrev_b32_e32 v98, 16, v99
	v_and_b32_e32 v97, 0xffff0000, v99
	v_fmac_f32_e32 v96, v56, v153
	v_mul_f32_e32 v99, v49, v152
	v_fmac_f32_e32 v96, v58, v154
	v_fmac_f32_e32 v99, v48, v149
	v_fmac_f32_e32 v96, v59, v151
	v_fmac_f32_e32 v99, v50, v150
	v_add_f32_e32 v96, 0, v96
	v_fmac_f32_e32 v99, v51, v113
	v_add_f32_e32 v96, v96, v99
	v_mul_f32_e32 v99, v41, v148
	v_fmac_f32_e32 v99, v40, v103
	v_fmac_f32_e32 v99, v42, v112
	v_fmac_f32_e32 v99, v43, v101
	v_add_f32_e32 v96, v96, v99
	v_mul_f32_e32 v99, v37, v102
	v_fmac_f32_e32 v99, v36, v100
	v_fmac_f32_e32 v99, v38, v98
	v_fmac_f32_e32 v99, v39, v97
	v_add_f32_e32 v96, v96, v99
	s_nop 1
	v_add_f32_dpp v99, v96, v96 quad_perm:[1,0,3,2] row_mask:0xf bank_mask:0xf
	s_nop 1
	v_add_f32_dpp v96, v99, v99 quad_perm:[2,3,0,1] row_mask:0xf bank_mask:0xf
	s_nop 1
	v_add_f32_dpp v99, v96, v96 row_half_mirror row_mask:0xf bank_mask:0xf
	s_nop 1
	v_add_f32_dpp v96, v99, v99 row_mirror row_mask:0xf bank_mask:0xf
	s_nop 1
	v_readlane_b32 s98, v96, 0
	v_readlane_b32 s99, v96, 16
	v_readlane_b32 s100, v96, 32
	v_readlane_b32 s101, v96, 48
	s_nop 1
	v_mov_b32_e32 v99, s98
	v_add_f32_e32 v99, s99, v99
	v_add_f32_e32 v99, s100, v99
	v_add_f32_e32 v99, s101, v99
	v_mov_b32_e32 v106, 0
	v_add_u32_e32 v96, 0x4401, v104
	s_and_saveexec_b64 s[26:27], s[2:3]
	s_cbranch_execz .LBB0_157
	v_add_u32_e32 v156, 1, v104
	v_ashrrev_i32_e32 v157, 31, v156
	v_cndmask_b32_e64 v157, 0, v157, s[4:5]
	v_cndmask_b32_e64 v156, v96, v156, s[4:5]
	v_lshl_add_u64 v[156:157], v[156:157], 2, s[10:11]
	s_waitcnt lgkmcnt(0)
	v_add_f32_e32 v99, v99, v106
	global_store_dword v[156:157], v99, off
.LBB0_157:
	s_or_b64 exec, exec, s[26:27]
	v_mul_f32_e32 v99, v77, v155
	v_fmac_f32_e32 v99, v76, v153
	s_waitcnt lgkmcnt(0)
	v_mul_f32_e32 v106, v73, v152
	v_fmac_f32_e32 v99, v78, v154
	v_fmac_f32_e32 v106, v72, v149
	v_fmac_f32_e32 v99, v79, v151
	v_fmac_f32_e32 v106, v74, v150
	v_add_f32_e32 v99, 0, v99
	v_fmac_f32_e32 v106, v75, v113
	v_add_f32_e32 v99, v99, v106
	v_mul_f32_e32 v106, v69, v148
	v_fmac_f32_e32 v106, v68, v103
	v_fmac_f32_e32 v106, v70, v112
	v_fmac_f32_e32 v106, v71, v101
	v_add_f32_e32 v99, v99, v106
	v_mul_f32_e32 v106, v65, v102
	v_fmac_f32_e32 v106, v64, v100
	v_fmac_f32_e32 v106, v66, v98
	v_fmac_f32_e32 v106, v67, v97
	v_add_f32_e32 v99, v99, v106
	s_nop 1
	v_add_f32_dpp v106, v99, v99 quad_perm:[1,0,3,2] row_mask:0xf bank_mask:0xf
	s_nop 1
	v_add_f32_dpp v99, v106, v106 quad_perm:[2,3,0,1] row_mask:0xf bank_mask:0xf
	s_nop 1
	v_add_f32_dpp v106, v99, v99 row_half_mirror row_mask:0xf bank_mask:0xf
	s_nop 1
	v_add_f32_dpp v99, v106, v106 row_mirror row_mask:0xf bank_mask:0xf
	s_nop 1
	v_readlane_b32 s98, v99, 0
	v_readlane_b32 s99, v99, 16
	v_readlane_b32 s100, v99, 32
	v_readlane_b32 s101, v99, 48
	s_nop 1
	v_mov_b32_e32 v99, s98
	v_add_f32_e32 v99, s99, v99
	v_add_f32_e32 v99, s100, v99
	v_add_f32_e32 v99, s101, v99
	v_mov_b32_e32 v156, 0
	s_and_saveexec_b64 s[26:27], s[2:3]
	s_cbranch_execz .LBB0_159
	v_lshl_add_u64 v[158:159], v[104:105], 2, s[10:11]
	v_cndmask_b32_e64 v106, v130, v131, s[4:5]
	v_lshl_add_u64 v[158:159], v[158:159], 0, v[106:107]
	s_waitcnt lgkmcnt(0)
	v_add_f32_e32 v99, v99, v156
	global_store_dword v[158:159], v99, off
; __device__ __forceinline__ float bflo(unsigned u) { return __uint_as_float(u << 16); }
; __device__ __forceinline__ float bfhi(unsigned u) { return __uint_as_float(u & 0xffff0000u); }
; __device__ __forceinline__ float wave_sum(float v) {
; #pragma unroll
;     for (int o = 1; o < 64; o <<= 1) v += __shfl_xor(v, o);
;     return v;
; }
; __device__ __forceinline__ void phase1(const Params& P) {
;     ...
;         for (int i = 0; i < 4; ++i) {
;             const uint4 w0 = wq[i][0], w1 = wq[i][1];
;             const float wv[16] = {bflo(w0.x), bfhi(w0.x), bflo(w0.y), bfhi(w0.y), bflo(w0.z), bfhi(w0.z), bflo(w0.w), bfhi(w0.w),
;                                   bflo(w1.x), bfhi(w1.x), bflo(w1.y), bfhi(w1.y), bflo(w1.z), bfhi(w1.z), bflo(w1.w), bfhi(w1.w)};
;             const int r = r0 + i;
; #pragma unroll
;             for (int mr = 0; mr < 5; ++mr) {
;                 float a = 0.f;
; #pragma unroll
;                 for (int q = 0; q < 4; ++q) a += s4[mr][q][0] * wv[q * 4] + s4[mr][q][1] * wv[q * 4 + 1] + s4[mr][q][2] * wv[q * 4 + 2] + s4[mr][q][3] * wv[q * 4 + 3];
;                 a = wave_sum(a);
;                 if (lane == 0) { if (first) BW[mr * 4352 + r] = a; else BW[5 * 4352 + mr * 5632 + (r - 4352)] = a; }
;             }
.LBB0_159:
	s_or_b64 exec, exec, s[26:27]
	v_mul_f32_e32 v99, v61, v155
	v_fmac_f32_e32 v99, v60, v153
	v_mul_f32_e32 v106, v53, v152
	v_fmac_f32_e32 v99, v62, v154
	v_fmac_f32_e32 v106, v52, v149
	v_fmac_f32_e32 v99, v63, v151
	v_fmac_f32_e32 v106, v54, v150
	v_add_f32_e32 v99, 0, v99
	v_fmac_f32_e32 v106, v55, v113
	v_add_f32_e32 v99, v99, v106
	v_mul_f32_e32 v106, v45, v148
	v_fmac_f32_e32 v106, v44, v103
	v_fmac_f32_e32 v106, v46, v112
	v_fmac_f32_e32 v106, v47, v101
	v_add_f32_e32 v99, v99, v106
	v_mul_f32_e32 v106, v33, v102
	v_fmac_f32_e32 v106, v32, v100
	v_fmac_f32_e32 v106, v34, v98
	v_fmac_f32_e32 v106, v35, v97
	v_add_f32_e32 v99, v99, v106
	s_nop 1
	v_add_f32_dpp v106, v99, v99 quad_perm:[1,0,3,2] row_mask:0xf bank_mask:0xf
	s_nop 1
	v_add_f32_dpp v99, v106, v106 quad_perm:[2,3,0,1] row_mask:0xf bank_mask:0xf
	s_nop 1
	v_add_f32_dpp v106, v99, v99 row_half_mirror row_mask:0xf bank_mask:0xf
	s_nop 1
	v_add_f32_dpp v99, v106, v106 row_mirror row_mask:0xf bank_mask:0xf
	s_nop 1
	v_readlane_b32 s98, v99, 0
	v_readlane_b32 s99, v99, 16
	v_readlane_b32 s100, v99, 32
	v_readlane_b32 s101, v99, 48
	s_nop 1
	v_mov_b32_e32 v99, s98
	v_add_f32_e32 v99, s99, v99
	v_add_f32_e32 v99, s100, v99
	v_add_f32_e32 v99, s101, v99
	v_mov_b32_e32 v156, 0
	s_and_saveexec_b64 s[26:27], s[2:3]
	s_cbranch_execz .LBB0_161
	v_lshl_add_u64 v[158:159], v[104:105], 2, s[10:11]
	v_cndmask_b32_e64 v106, v132, v133, s[4:5]
	v_lshl_add_u64 v[158:159], v[158:159], 0, v[106:107]
	s_waitcnt lgkmcnt(0)
	v_add_f32_e32 v99, v99, v156
	global_store_dword v[158:159], v99, off
.LBB0_161:
	s_or_b64 exec, exec, s[26:27]
	v_mul_f32_e32 v99, v29, v155
	v_fmac_f32_e32 v99, v28, v153
	v_mul_f32_e32 v106, v25, v152
	v_fmac_f32_e32 v99, v30, v154
	v_fmac_f32_e32 v106, v24, v149
	v_fmac_f32_e32 v99, v31, v151
	v_fmac_f32_e32 v106, v26, v150
	v_add_f32_e32 v99, 0, v99
	v_fmac_f32_e32 v106, v27, v113
	v_add_f32_e32 v99, v99, v106
	v_mul_f32_e32 v106, v21, v148
	v_fmac_f32_e32 v106, v20, v103
	v_fmac_f32_e32 v106, v22, v112
	v_fmac_f32_e32 v106, v23, v101
	v_add_f32_e32 v99, v99, v106
	v_mul_f32_e32 v106, v17, v102
	v_fmac_f32_e32 v106, v16, v100
	v_fmac_f32_e32 v106, v18, v98
	v_fmac_f32_e32 v106, v19, v97
	v_add_f32_e32 v99, v99, v106
	s_nop 1
	v_add_f32_dpp v106, v99, v99 quad_perm:[1,0,3,2] row_mask:0xf bank_mask:0xf
	s_nop 1
	v_add_f32_dpp v99, v106, v106 quad_perm:[2,3,0,1] row_mask:0xf bank_mask:0xf
	s_nop 1
	v_add_f32_dpp v106, v99, v99 row_half_mirror row_mask:0xf bank_mask:0xf
	s_nop 1
	v_add_f32_dpp v99, v106, v106 row_mirror row_mask:0xf bank_mask:0xf
	s_nop 1
	v_readlane_b32 s98, v99, 0
	v_readlane_b32 s99, v99, 16
	v_readlane_b32 s100, v99, 32
	v_readlane_b32 s101, v99, 48
	s_nop 1
	v_mov_b32_e32 v99, s98
	v_add_f32_e32 v99, s99, v99
	v_add_f32_e32 v99, s100, v99
	v_add_f32_e32 v99, s101, v99
	v_mov_b32_e32 v156, 0
	s_and_saveexec_b64 s[26:27], s[2:3]
	s_cbranch_execz .LBB0_163
	v_lshl_add_u64 v[158:159], v[104:105], 2, s[10:11]
	v_cndmask_b32_e64 v106, v134, v135, s[4:5]
	v_lshl_add_u64 v[158:159], v[158:159], 0, v[106:107]
	s_waitcnt lgkmcnt(0)
	v_add_f32_e32 v99, v99, v156
	global_store_dword v[158:159], v99, off
.LBB0_163:
	s_or_b64 exec, exec, s[26:27]
	v_mul_f32_e32 v99, v13, v155
	v_fmac_f32_e32 v99, v12, v153
	v_mul_f32_e32 v106, v9, v152
	v_fmac_f32_e32 v99, v14, v154
	v_fmac_f32_e32 v106, v8, v149
	v_fmac_f32_e32 v99, v15, v151
	v_fmac_f32_e32 v106, v10, v150
	v_add_f32_e32 v99, 0, v99
	v_fmac_f32_e32 v106, v11, v113
	v_add_f32_e32 v99, v99, v106
	v_mul_f32_e32 v106, v5, v148
	v_fmac_f32_e32 v106, v4, v103
	v_fmac_f32_e32 v106, v6, v112
	v_fmac_f32_e32 v106, v7, v101
	v_mul_f32_e32 v101, v1, v102
	v_fmac_f32_e32 v101, v0, v100
	v_fmac_f32_e32 v101, v2, v98
	v_add_f32_e32 v99, v99, v106
	v_fmac_f32_e32 v101, v3, v97
	v_add_f32_e32 v97, v99, v101
	s_nop 1
	v_add_f32_dpp v98, v97, v97 quad_perm:[1,0,3,2] row_mask:0xf bank_mask:0xf
	s_nop 1
	v_add_f32_dpp v97, v98, v98 quad_perm:[2,3,0,1] row_mask:0xf bank_mask:0xf
	s_nop 1
	v_add_f32_dpp v98, v97, v97 row_half_mirror row_mask:0xf bank_mask:0xf
	s_nop 1
	v_add_f32_dpp v97, v98, v98 row_mirror row_mask:0xf bank_mask:0xf
	s_nop 1
	v_readlane_b32 s98, v97, 0
	v_readlane_b32 s99, v97, 16
	v_readlane_b32 s100, v97, 32
	v_readlane_b32 s101, v97, 48
	s_nop 1
	v_mov_b32_e32 v97, s98
	v_add_f32_e32 v97, s99, v97
	v_add_f32_e32 v97, s100, v97
	v_add_f32_e32 v97, s101, v97
	v_mov_b32_e32 v98, 0
	s_and_saveexec_b64 s[26:27], s[2:3]
	s_cbranch_execz .LBB0_168
	s_waitcnt lgkmcnt(0)
	v_add_f32_e32 v98, v97, v98
	s_and_saveexec_b64 s[28:29], s[6:7]
	s_xor_b64 s[28:29], exec, s[28:29]
	s_cbranch_execz .LBB0_166
	v_lshl_add_u64 v[96:97], v[104:105], 2, s[10:11]
	v_add_co_u32_e32 v96, vcc, 0x27000, v96
	s_nop 1
	v_addc_co_u32_e32 v97, vcc, 0, v97, vcc
	global_store_dword v[96:97], v98, off offset:4

; __device__ __forceinline__ float bflo(unsigned u) { return __uint_as_float(u << 16); }
; __device__ __forceinline__ float bfhi(unsigned u) { return __uint_as_float(u & 0xffff0000u); }
; __device__ __forceinline__ float wave_sum(float v) {
; #pragma unroll
;     for (int o = 1; o < 64; o <<= 1) v += __shfl_xor(v, o);
;     return v;
; }
; __device__ __forceinline__ void phase1(const Params& P) {
;     ...
;         for (int i = 0; i < 4; ++i) {
;             const uint4 w0 = wq[i][0], w1 = wq[i][1];
;             const float wv[16] = {bflo(w0.x), bfhi(w0.x), bflo(w0.y), bfhi(w0.y), bflo(w0.z), bfhi(w0.z), bflo(w0.w), bfhi(w0.w),
;                                   bflo(w1.x), bfhi(w1.x), bflo(w1.y), bfhi(w1.y), bflo(w1.z), bfhi(w1.z), bflo(w1.w), bfhi(w1.w)};
;             const int r = r0 + i;
; #pragma unroll
;             for (int mr = 0; mr < 5; ++mr) {
;                 float a = 0.f;
; #pragma unroll
;                 for (int q = 0; q < 4; ++q) a += s4[mr][q][0] * wv[q * 4] + s4[mr][q][1] * wv[q * 4 + 1] + s4[mr][q][2] * wv[q * 4 + 2] + s4[mr][q][3] * wv[q * 4 + 3];
;                 a = wave_sum(a);
;                 if (lane == 0) { if (first) BW[mr * 4352 + r] = a; else BW[5 * 4352 + mr * 5632 + (r - 4352)] = a; }
;             }
.LBB0_168:
	s_or_b64 exec, exec, s[26:27]
	s_waitcnt vmcnt(3)
	v_and_b32_e32 v113, 0xffff0000, v92
	v_lshlrev_b32_e32 v103, 16, v92
	v_and_b32_e32 v102, 0xffff0000, v94
	v_lshlrev_b32_e32 v100, 16, v95
	v_and_b32_e32 v97, 0xffff0000, v95
	s_waitcnt vmcnt(2)
	v_lshlrev_b32_e32 v95, 16, v88
	s_waitcnt lgkmcnt(0)
	v_and_b32_e32 v98, 0xffff0000, v88
	v_mul_f32_e32 v88, v57, v113
	v_lshlrev_b32_e32 v112, 16, v93
	v_and_b32_e32 v101, 0xffff0000, v93
	v_lshlrev_b32_e32 v99, 16, v94
	v_lshlrev_b32_e32 v96, 16, v89
	v_and_b32_e32 v93, 0xffff0000, v89
	v_lshlrev_b32_e32 v92, 16, v90
	v_and_b32_e32 v94, 0xffff0000, v90
	v_lshlrev_b32_e32 v90, 16, v91
	v_and_b32_e32 v89, 0xffff0000, v91
	v_fmac_f32_e32 v88, v56, v103
	v_mul_f32_e32 v91, v49, v102
	v_fmac_f32_e32 v88, v58, v112
	v_fmac_f32_e32 v91, v48, v99
	v_fmac_f32_e32 v88, v59, v101
	v_fmac_f32_e32 v91, v50, v100
	v_add_f32_e32 v88, 0, v88
	v_fmac_f32_e32 v91, v51, v97
	v_add_f32_e32 v88, v88, v91
	v_mul_f32_e32 v91, v41, v98
	v_fmac_f32_e32 v91, v40, v95
	v_fmac_f32_e32 v91, v42, v96
	v_fmac_f32_e32 v91, v43, v93
	v_add_f32_e32 v88, v88, v91
	v_mul_f32_e32 v91, v37, v94
	v_fmac_f32_e32 v91, v36, v92
	v_fmac_f32_e32 v91, v38, v90
	v_fmac_f32_e32 v91, v39, v89
	v_add_f32_e32 v88, v88, v91
	s_nop 1
	v_add_f32_dpp v91, v88, v88 quad_perm:[1,0,3,2] row_mask:0xf bank_mask:0xf
	s_nop 1
	v_add_f32_dpp v88, v91, v91 quad_perm:[2,3,0,1] row_mask:0xf bank_mask:0xf
	s_nop 1
	v_add_f32_dpp v91, v88, v88 row_half_mirror row_mask:0xf bank_mask:0xf
	s_nop 1
	v_add_f32_dpp v88, v91, v91 row_mirror row_mask:0xf bank_mask:0xf
	s_nop 1
	v_readlane_b32 s98, v88, 0
	v_readlane_b32 s99, v88, 16
	v_readlane_b32 s100, v88, 32
	v_readlane_b32 s101, v88, 48
	s_nop 1
	v_mov_b32_e32 v91, s98
	v_add_f32_e32 v91, s99, v91
	v_add_f32_e32 v91, s100, v91
	v_add_f32_e32 v91, s101, v91
	v_mov_b32_e32 v106, 0
	v_add_u32_e32 v88, 0x4402, v104
	s_and_saveexec_b64 s[26:27], s[2:3]
	s_cbranch_execz .LBB0_170
	v_add_u32_e32 v148, 2, v104
	v_ashrrev_i32_e32 v149, 31, v148
	v_cndmask_b32_e64 v149, 0, v149, s[4:5]
	v_cndmask_b32_e64 v148, v88, v148, s[4:5]
	v_lshl_add_u64 v[148:149], v[148:149], 2, s[10:11]
	s_waitcnt lgkmcnt(0)
	v_add_f32_e32 v91, v91, v106
	global_store_dword v[148:149], v91, off
.LBB0_170:
	s_or_b64 exec, exec, s[26:27]
	v_mul_f32_e32 v91, v77, v113
	v_fmac_f32_e32 v91, v76, v103
	s_waitcnt lgkmcnt(0)
	v_mul_f32_e32 v106, v73, v102
	v_fmac_f32_e32 v91, v78, v112
	v_fmac_f32_e32 v106, v72, v99
	v_fmac_f32_e32 v91, v79, v101
	v_fmac_f32_e32 v106, v74, v100
	v_add_f32_e32 v91, 0, v91
	v_fmac_f32_e32 v106, v75, v97
	v_add_f32_e32 v91, v91, v106
	v_mul_f32_e32 v106, v69, v98
	v_fmac_f32_e32 v106, v68, v95
	v_fmac_f32_e32 v106, v70, v96
	v_fmac_f32_e32 v106, v71, v93
	v_add_f32_e32 v91, v91, v106
	v_mul_f32_e32 v106, v65, v94
	v_fmac_f32_e32 v106, v64, v92
	v_fmac_f32_e32 v106, v66, v90
	v_fmac_f32_e32 v106, v67, v89
	v_add_f32_e32 v91, v91, v106
	s_nop 1
	v_add_f32_dpp v106, v91, v91 quad_perm:[1,0,3,2] row_mask:0xf bank_mask:0xf
	s_nop 1
	v_add_f32_dpp v91, v106, v106 quad_perm:[2,3,0,1] row_mask:0xf bank_mask:0xf
	s_nop 1
	v_add_f32_dpp v106, v91, v91 row_half_mirror row_mask:0xf bank_mask:0xf
	s_nop 1
	v_add_f32_dpp v91, v106, v106 row_mirror row_mask:0xf bank_mask:0xf
	s_nop 1
	v_readlane_b32 s98, v91, 0
	v_readlane_b32 s99, v91, 16
	v_readlane_b32 s100, v91, 32
	v_readlane_b32 s101, v91, 48
	s_nop 1
	v_mov_b32_e32 v91, s98
	v_add_f32_e32 v91, s99, v91
	v_add_f32_e32 v91, s100, v91
	v_add_f32_e32 v91, s101, v91
	v_mov_b32_e32 v148, 0
	s_and_saveexec_b64 s[26:27], s[2:3]
	s_cbranch_execz .LBB0_172
	v_lshl_add_u64 v[150:151], v[104:105], 2, s[10:11]
	v_cndmask_b32_e64 v106, v136, v137, s[4:5]
	v_lshl_add_u64 v[150:151], v[150:151], 0, v[106:107]
	s_waitcnt lgkmcnt(0)
	v_add_f32_e32 v91, v91, v148
	global_store_dword v[150:151], v91, off
; __device__ __forceinline__ float bflo(unsigned u) { return __uint_as_float(u << 16); }
; __device__ __forceinline__ float bfhi(unsigned u) { return __uint_as_float(u & 0xffff0000u); }
; __device__ __forceinline__ float wave_sum(float v) {
; #pragma unroll
;     for (int o = 1; o < 64; o <<= 1) v += __shfl_xor(v, o);
;     return v;
; }
; __device__ __forceinline__ void phase1(const Params& P) {
;     ...
;         for (int i = 0; i < 4; ++i) {
;             const uint4 w0 = wq[i][0], w1 = wq[i][1];
;             const float wv[16] = {bflo(w0.x), bfhi(w0.x), bflo(w0.y), bfhi(w0.y), bflo(w0.z), bfhi(w0.z), bflo(w0.w), bfhi(w0.w),
;                                   bflo(w1.x), bfhi(w1.x), bflo(w1.y), bfhi(w1.y), bflo(w1.z), bfhi(w1.z), bflo(w1.w), bfhi(w1.w)};
;             const int r = r0 + i;
; #pragma unroll
;             for (int mr = 0; mr < 5; ++mr) {
;                 float a = 0.f;
; #pragma unroll
;                 for (int q = 0; q < 4; ++q) a += s4[mr][q][0] * wv[q * 4] + s4[mr][q][1] * wv[q * 4 + 1] + s4[mr][q][2] * wv[q * 4 + 2] + s4[mr][q][3] * wv[q * 4 + 3];
;                 a = wave_sum(a);
;                 if (lane == 0) { if (first) BW[mr * 4352 + r] = a; else BW[5 * 4352 + mr * 5632 + (r - 4352)] = a; }
;             }
.LBB0_172:
	s_or_b64 exec, exec, s[26:27]
	v_mul_f32_e32 v91, v61, v113
	v_fmac_f32_e32 v91, v60, v103
	v_mul_f32_e32 v106, v53, v102
	v_fmac_f32_e32 v91, v62, v112
	v_fmac_f32_e32 v106, v52, v99
	v_fmac_f32_e32 v91, v63, v101
	v_fmac_f32_e32 v106, v54, v100
	v_add_f32_e32 v91, 0, v91
	v_fmac_f32_e32 v106, v55, v97
	v_add_f32_e32 v91, v91, v106
	v_mul_f32_e32 v106, v45, v98
	v_fmac_f32_e32 v106, v44, v95
	v_fmac_f32_e32 v106, v46, v96
	v_fmac_f32_e32 v106, v47, v93
	v_add_f32_e32 v91, v91, v106
	v_mul_f32_e32 v106, v33, v94
	v_fmac_f32_e32 v106, v32, v92
	v_fmac_f32_e32 v106, v34, v90
	v_fmac_f32_e32 v106, v35, v89
	v_add_f32_e32 v91, v91, v106
	s_nop 1
	v_add_f32_dpp v106, v91, v91 quad_perm:[1,0,3,2] row_mask:0xf bank_mask:0xf
	s_nop 1
	v_add_f32_dpp v91, v106, v106 quad_perm:[2,3,0,1] row_mask:0xf bank_mask:0xf
	s_nop 1
	v_add_f32_dpp v106, v91, v91 row_half_mirror row_mask:0xf bank_mask:0xf
	s_nop 1
	v_add_f32_dpp v91, v106, v106 row_mirror row_mask:0xf bank_mask:0xf
	s_nop 1
	v_readlane_b32 s98, v91, 0
	v_readlane_b32 s99, v91, 16
	v_readlane_b32 s100, v91, 32
	v_readlane_b32 s101, v91, 48
	s_nop 1
	v_mov_b32_e32 v91, s98
	v_add_f32_e32 v91, s99, v91
	v_add_f32_e32 v91, s100, v91
	v_add_f32_e32 v91, s101, v91
	v_mov_b32_e32 v148, 0
	s_and_saveexec_b64 s[26:27], s[2:3]
	s_cbranch_execz .LBB0_174
	v_lshl_add_u64 v[150:151], v[104:105], 2, s[10:11]
	v_cndmask_b32_e64 v106, v138, v139, s[4:5]
	v_lshl_add_u64 v[150:151], v[150:151], 0, v[106:107]
	s_waitcnt lgkmcnt(0)
	v_add_f32_e32 v91, v91, v148
	global_store_dword v[150:151], v91, off
.LBB0_174:
	s_or_b64 exec, exec, s[26:27]
	v_mul_f32_e32 v91, v29, v113
	v_fmac_f32_e32 v91, v28, v103
	v_mul_f32_e32 v106, v25, v102
	v_fmac_f32_e32 v91, v30, v112
	v_fmac_f32_e32 v106, v24, v99
	v_fmac_f32_e32 v91, v31, v101
	v_fmac_f32_e32 v106, v26, v100
	v_add_f32_e32 v91, 0, v91
	v_fmac_f32_e32 v106, v27, v97
	v_add_f32_e32 v91, v91, v106
	v_mul_f32_e32 v106, v21, v98
	v_fmac_f32_e32 v106, v20, v95
	v_fmac_f32_e32 v106, v22, v96
	v_fmac_f32_e32 v106, v23, v93
	v_add_f32_e32 v91, v91, v106
	v_mul_f32_e32 v106, v17, v94
	v_fmac_f32_e32 v106, v16, v92
	v_fmac_f32_e32 v106, v18, v90
	v_fmac_f32_e32 v106, v19, v89
	v_add_f32_e32 v91, v91, v106
	s_nop 1
	v_add_f32_dpp v106, v91, v91 quad_perm:[1,0,3,2] row_mask:0xf bank_mask:0xf
	s_nop 1
	v_add_f32_dpp v91, v106, v106 quad_perm:[2,3,0,1] row_mask:0xf bank_mask:0xf
	s_nop 1
	v_add_f32_dpp v106, v91, v91 row_half_mirror row_mask:0xf bank_mask:0xf
	s_nop 1
	v_add_f32_dpp v91, v106, v106 row_mirror row_mask:0xf bank_mask:0xf
	s_nop 1
	v_readlane_b32 s98, v91, 0
	v_readlane_b32 s99, v91, 16
	v_readlane_b32 s100, v91, 32
	v_readlane_b32 s101, v91, 48
	s_nop 1
	v_mov_b32_e32 v91, s98
	v_add_f32_e32 v91, s99, v91
	v_add_f32_e32 v91, s100, v91
	v_add_f32_e32 v91, s101, v91
	v_mov_b32_e32 v148, 0
	s_and_saveexec_b64 s[26:27], s[2:3]
	s_cbranch_execz .LBB0_176
	v_lshl_add_u64 v[150:151], v[104:105], 2, s[10:11]
	v_cndmask_b32_e64 v106, v140, v141, s[4:5]
	v_lshl_add_u64 v[150:151], v[150:151], 0, v[106:107]
	s_waitcnt lgkmcnt(0)
	v_add_f32_e32 v91, v91, v148
	global_store_dword v[150:151], v91, off
.LBB0_176:
	s_or_b64 exec, exec, s[26:27]
	v_mul_f32_e32 v91, v13, v113
	v_fmac_f32_e32 v91, v12, v103
	v_fmac_f32_e32 v91, v14, v112
	v_fmac_f32_e32 v91, v15, v101
	v_mul_f32_e32 v101, v9, v102
	v_fmac_f32_e32 v101, v8, v99
	v_fmac_f32_e32 v101, v10, v100
	v_fmac_f32_e32 v101, v11, v97
	v_mul_f32_e32 v97, v5, v98
	v_fmac_f32_e32 v97, v4, v95
	v_fmac_f32_e32 v97, v6, v96
	v_fmac_f32_e32 v97, v7, v93
	v_mul_f32_e32 v93, v1, v94
	v_add_f32_e32 v91, 0, v91
	v_fmac_f32_e32 v93, v0, v92
	v_add_f32_e32 v91, v91, v101
	v_fmac_f32_e32 v93, v2, v90
	v_add_f32_e32 v91, v91, v97
	v_fmac_f32_e32 v93, v3, v89
	v_add_f32_e32 v89, v91, v93
	s_nop 1
	v_add_f32_dpp v90, v89, v89 quad_perm:[1,0,3,2] row_mask:0xf bank_mask:0xf
	s_nop 1
	v_add_f32_dpp v89, v90, v90 quad_perm:[2,3,0,1] row_mask:0xf bank_mask:0xf
	s_nop 1
	v_add_f32_dpp v90, v89, v89 row_half_mirror row_mask:0xf bank_mask:0xf
	s_nop 1
	v_add_f32_dpp v89, v90, v90 row_mirror row_mask:0xf bank_mask:0xf
	s_nop 1
	v_readlane_b32 s98, v89, 0
	v_readlane_b32 s99, v89, 16
	v_readlane_b32 s100, v89, 32
	v_readlane_b32 s101, v89, 48
	s_nop 1
	v_mov_b32_e32 v89, s98
	v_add_f32_e32 v89, s99, v89
	v_add_f32_e32 v89, s100, v89
	v_add_f32_e32 v89, s101, v89
	v_mov_b32_e32 v90, 0
	s_and_saveexec_b64 s[26:27], s[2:3]
	s_cbranch_execz .LBB0_181
	s_waitcnt lgkmcnt(0)
	v_add_f32_e32 v90, v89, v90
	s_and_saveexec_b64 s[28:29], s[6:7]
	s_xor_b64 s[28:29], exec, s[28:29]
	s_cbranch_execz .LBB0_179
	v_lshl_add_u64 v[88:89], v[104:105], 2, s[10:11]
	v_add_co_u32_e32 v88, vcc, 0x27000, v88
	s_nop 1
	v_addc_co_u32_e32 v89, vcc, 0, v89, vcc
	global_store_dword v[88:89], v90, off offset:8

; __device__ __forceinline__ float bflo(unsigned u) { return __uint_as_float(u << 16); }
; __device__ __forceinline__ float bfhi(unsigned u) { return __uint_as_float(u & 0xffff0000u); }
; __device__ __forceinline__ float wave_sum(float v) {
; #pragma unroll
;     for (int o = 1; o < 64; o <<= 1) v += __shfl_xor(v, o);
;     return v;
; }
; __device__ __forceinline__ void phase1(const Params& P) {
;     ...
;         for (int i = 0; i < 4; ++i) {
;             const uint4 w0 = wq[i][0], w1 = wq[i][1];
;             const float wv[16] = {bflo(w0.x), bfhi(w0.x), bflo(w0.y), bfhi(w0.y), bflo(w0.z), bfhi(w0.z), bflo(w0.w), bfhi(w0.w),
;                                   bflo(w1.x), bfhi(w1.x), bflo(w1.y), bfhi(w1.y), bflo(w1.z), bfhi(w1.z), bflo(w1.w), bfhi(w1.w)};
;             const int r = r0 + i;
; #pragma unroll
;             for (int mr = 0; mr < 5; ++mr) {
;                 float a = 0.f;
; #pragma unroll
;                 for (int q = 0; q < 4; ++q) a += s4[mr][q][0] * wv[q * 4] + s4[mr][q][1] * wv[q * 4 + 1] + s4[mr][q][2] * wv[q * 4 + 2] + s4[mr][q][3] * wv[q * 4 + 3];
;                 a = wave_sum(a);
;                 if (lane == 0) { if (first) BW[mr * 4352 + r] = a; else BW[5 * 4352 + mr * 5632 + (r - 4352)] = a; }
;             }
.LBB0_181:
	s_or_b64 exec, exec, s[26:27]
	s_waitcnt vmcnt(1)
	v_and_b32_e32 v96, 0xffff0000, v84
	v_lshlrev_b32_e32 v94, 16, v84
	v_and_b32_e32 v93, 0xffff0000, v86
	v_mul_f32_e32 v57, v57, v96
	v_lshlrev_b32_e32 v95, 16, v85
	s_waitcnt lgkmcnt(0)
	v_lshlrev_b32_e32 v90, 16, v86
	s_waitcnt vmcnt(0)
	v_and_b32_e32 v89, 0xffff0000, v80
	v_fmac_f32_e32 v57, v56, v94
	v_mul_f32_e32 v49, v49, v93
	v_and_b32_e32 v92, 0xffff0000, v85
	v_lshlrev_b32_e32 v91, 16, v87
	v_lshlrev_b32_e32 v86, 16, v80
	v_and_b32_e32 v85, 0xffff0000, v82
	v_fmac_f32_e32 v57, v58, v95
	v_fmac_f32_e32 v49, v48, v90
	v_mul_f32_e32 v41, v41, v89
	v_and_b32_e32 v88, 0xffff0000, v87
	v_lshlrev_b32_e32 v87, 16, v81
	v_and_b32_e32 v84, 0xffff0000, v81
	v_lshlrev_b32_e32 v81, 16, v82
	v_fmac_f32_e32 v57, v59, v92
	v_fmac_f32_e32 v49, v50, v91
	v_fmac_f32_e32 v41, v40, v86
	v_mul_f32_e32 v37, v37, v85
	v_lshlrev_b32_e32 v82, 16, v83
	v_add_f32_e32 v56, 0, v57
	v_fmac_f32_e32 v49, v51, v88
	v_fmac_f32_e32 v41, v42, v87
	v_fmac_f32_e32 v37, v36, v81
	v_and_b32_e32 v80, 0xffff0000, v83
	v_add_f32_e32 v48, v56, v49
	v_fmac_f32_e32 v41, v43, v84
	v_fmac_f32_e32 v37, v38, v82
	v_add_f32_e32 v40, v48, v41
	v_fmac_f32_e32 v37, v39, v80
	v_add_f32_e32 v36, v40, v37
	s_nop 1
	v_add_f32_dpp v37, v36, v36 quad_perm:[1,0,3,2] row_mask:0xf bank_mask:0xf
	s_nop 1
	v_add_f32_dpp v36, v37, v37 quad_perm:[2,3,0,1] row_mask:0xf bank_mask:0xf
	s_nop 1
	v_add_f32_dpp v37, v36, v36 row_half_mirror row_mask:0xf bank_mask:0xf
	s_nop 1
	v_add_f32_dpp v36, v37, v37 row_mirror row_mask:0xf bank_mask:0xf
	s_nop 1
	v_readlane_b32 s98, v36, 0
	v_readlane_b32 s99, v36, 16
	v_readlane_b32 s100, v36, 32
	v_readlane_b32 s101, v36, 48
	s_nop 1
	v_mov_b32_e32 v37, s98
	v_add_f32_e32 v37, s99, v37
	v_add_f32_e32 v37, s100, v37
	v_add_f32_e32 v37, s101, v37
	v_mov_b32_e32 v38, 0
	v_add_u32_e32 v36, 0x4403, v104
	s_and_saveexec_b64 s[26:27], s[2:3]
	s_cbranch_execz .LBB0_183
	v_add_u32_e32 v39, 3, v104
	v_ashrrev_i32_e32 v40, 31, v39
	v_cndmask_b32_e64 v41, 0, v40, s[4:5]
	v_cndmask_b32_e64 v40, v36, v39, s[4:5]
	v_lshl_add_u64 v[40:41], v[40:41], 2, s[10:11]
	s_waitcnt lgkmcnt(0)
	v_add_f32_e32 v37, v37, v38
	global_store_dword v[40:41], v37, off
.LBB0_183:
	s_or_b64 exec, exec, s[26:27]
	v_mul_f32_e32 v37, v77, v96
	v_fmac_f32_e32 v37, v76, v94
	s_waitcnt lgkmcnt(0)
	v_mul_f32_e32 v38, v73, v93
	v_fmac_f32_e32 v37, v78, v95
	v_fmac_f32_e32 v38, v72, v90
	v_fmac_f32_e32 v37, v79, v92
	v_fmac_f32_e32 v38, v74, v91
	v_add_f32_e32 v37, 0, v37
	v_fmac_f32_e32 v38, v75, v88
	v_add_f32_e32 v37, v37, v38
	v_mul_f32_e32 v38, v69, v89
	v_fmac_f32_e32 v38, v68, v86
	v_fmac_f32_e32 v38, v70, v87
	v_fmac_f32_e32 v38, v71, v84
	v_add_f32_e32 v37, v37, v38
	v_mul_f32_e32 v38, v65, v85
	v_fmac_f32_e32 v38, v64, v81
	v_fmac_f32_e32 v38, v66, v82
	v_fmac_f32_e32 v38, v67, v80
	v_add_f32_e32 v37, v37, v38
	s_nop 1
	v_add_f32_dpp v38, v37, v37 quad_perm:[1,0,3,2] row_mask:0xf bank_mask:0xf
	s_nop 1
	v_add_f32_dpp v37, v38, v38 quad_perm:[2,3,0,1] row_mask:0xf bank_mask:0xf
	s_nop 1
	v_add_f32_dpp v38, v37, v37 row_half_mirror row_mask:0xf bank_mask:0xf
	s_nop 1
	v_add_f32_dpp v37, v38, v38 row_mirror row_mask:0xf bank_mask:0xf
	s_nop 1
	v_readlane_b32 s98, v37, 0
	v_readlane_b32 s99, v37, 16
	v_readlane_b32 s100, v37, 32
	v_readlane_b32 s101, v37, 48
	s_nop 1
	v_mov_b32_e32 v37, s98
	v_add_f32_e32 v37, s99, v37
	v_add_f32_e32 v37, s100, v37
	v_add_f32_e32 v37, s101, v37
	v_mov_b32_e32 v38, 0
	s_and_saveexec_b64 s[26:27], s[2:3]
	s_cbranch_execz .LBB0_185
	v_lshl_add_u64 v[40:41], v[104:105], 2, s[10:11]
	v_cndmask_b32_e64 v106, v142, v143, s[4:5]
	v_lshl_add_u64 v[40:41], v[40:41], 0, v[106:107]
	s_waitcnt lgkmcnt(0)
	v_add_f32_e32 v37, v37, v38
	global_store_dword v[40:41], v37, off
.LBB0_185:
	s_or_b64 exec, exec, s[26:27]
	v_mul_f32_e32 v37, v61, v96
	v_fmac_f32_e32 v37, v60, v94
	s_waitcnt lgkmcnt(0)
	v_mul_f32_e32 v38, v53, v93
	v_fmac_f32_e32 v37, v62, v95
	v_fmac_f32_e32 v38, v52, v90
	v_fmac_f32_e32 v37, v63, v92
	v_fmac_f32_e32 v38, v54, v91
	v_add_f32_e32 v37, 0, v37
	v_fmac_f32_e32 v38, v55, v88
	v_add_f32_e32 v37, v37, v38
	v_mul_f32_e32 v38, v45, v89
	v_fmac_f32_e32 v38, v44, v86
	v_mul_f32_e32 v33, v33, v85
	v_fmac_f32_e32 v38, v46, v87
	v_fmac_f32_e32 v33, v32, v81
	v_fmac_f32_e32 v38, v47, v84
	v_fmac_f32_e32 v33, v34, v82
	v_add_f32_e32 v37, v37, v38
	v_fmac_f32_e32 v33, v35, v80
	v_add_f32_e32 v32, v37, v33
	s_nop 1
	v_add_f32_dpp v33, v32, v32 quad_perm:[1,0,3,2] row_mask:0xf bank_mask:0xf
	s_nop 1
	v_add_f32_dpp v32, v33, v33 quad_perm:[2,3,0,1] row_mask:0xf bank_mask:0xf
	s_nop 1
	v_add_f32_dpp v33, v32, v32 row_half_mirror row_mask:0xf bank_mask:0xf
	s_nop 1
	v_add_f32_dpp v32, v33, v33 row_mirror row_mask:0xf bank_mask:0xf
	s_nop 1
	v_readlane_b32 s98, v32, 0
	v_readlane_b32 s99, v32, 16
	v_readlane_b32 s100, v32, 32
	v_readlane_b32 s101, v32, 48
	s_nop 1
	v_mov_b32_e32 v32, s98
	v_add_f32_e32 v32, s99, v32
	v_add_f32_e32 v32, s100, v32
	v_add_f32_e32 v32, s101, v32
	v_mov_b32_e32 v33, 0
	s_and_saveexec_b64 s[26:27], s[2:3]
	s_cbranch_execz .LBB0_187
	v_lshl_add_u64 v[34:35], v[104:105], 2, s[10:11]
	v_cndmask_b32_e64 v106, v144, v145, s[4:5]
	v_lshl_add_u64 v[34:35], v[34:35], 0, v[106:107]
	s_waitcnt lgkmcnt(0)
	v_add_f32_e32 v32, v32, v33
	global_store_dword v[34:35], v32, off
; __device__ __forceinline__ void phase1(const Params& P) {
;     ...
;     for (int r0 = blockIdx.x * 32 + w * 4; r0 < 4352 + 5632; r0 += gridDim.x * 32) {
;         const bool first = r0 < 4352;
;         const bf16_t* wt = first ? (const bf16_t*)(P.ws + OFF_WIN) + (size_t)r0 * 1024 : (const bf16_t*)(P.ws + OFF_WGU2) + (size_t)(r0 - 4352) * 1024;
;         const float* sh = mod + (first ? 3 : 6) * 1024 + lane * 16;
;         uint4 wq[4][2];
; #pragma unroll
;         for (int i = 0; i < 4; ++i) { wq[i][0] = *(const uint4*)(wt + (size_t)i * 1024 + lane * 16); wq[i][1] = *(const uint4*)(wt + (size_t)i * 1024 + lane * 16 + 8); }
;         f32x4 s4[5][4];
; #pragma unroll
;         for (int mr = 0; mr < 5; ++mr)
; #pragma unroll
;             for (int q = 0; q < 4; ++q) s4[mr][q] = *(const f32x4*)(sh + mr * 9216 + q * 4);
;         float* BW = (float*)(P.ws + OFF_BW);
; #pragma unroll
;         for (int i = 0; i < 4; ++i) {
;             const uint4 w0 = wq[i][0], w1 = wq[i][1];
;             const float wv[16] = {bflo(w0.x), bfhi(w0.x), bflo(w0.y), bfhi(w0.y), bflo(w0.z), bfhi(w0.z), bflo(w0.w), bfhi(w0.w),
;                                   bflo(w1.x), bfhi(w1.x), bflo(w1.y), bfhi(w1.y), bflo(w1.z), bfhi(w1.z), bflo(w1.w), bfhi(w1.w)};
;             const int r = r0 + i;
; #pragma unroll
;             for (int mr = 0; mr < 5; ++mr) {
;                 float a = 0.f;
; #pragma unroll
;                 for (int q = 0; q < 4; ++q) a += s4[mr][q][0] * wv[q * 4] + s4[mr][q][1] * wv[q * 4 + 1] + s4[mr][q][2] * wv[q * 4 + 2] + s4[mr][q][3] * wv[q * 4 + 3];
;                 a = wave_sum(a);
;                 if (lane == 0) { if (first) BW[mr * 4352 + r] = a; else BW[5 * 4352 + mr * 5632 + (r - 4352)] = a; }
;             }
;         }
;     }
;     ...
;         constexpr int N = 2 * 32 * 32 * 256;
;         int e0 = gtid;
;         for (; e0 + 3 * gsz < N; e0 += 4 * gsz) {
;             float sacc[4] = {0.f, 0.f, 0.f, 0.f};
; #pragma unroll 2
;             for (int p = 0; p < 64; ++p) {
; #pragma unroll
;                 for (int q = 0; q < 4; ++q) {
;                     const int e = e0 + q * gsz;
;                     const int cp = e & 15, c = (e >> 4) & 15, tau = (e >> 8) & 31, dg = e >> 13;
;                     const float2 C = make_float2(P.in[17][(dg * 16 + c) * 64 + p], P.in[18][(dg * 16 + c) * 64 + p]);
.LBB0_187:
	s_or_b64 exec, exec, s[26:27]
	v_mul_f32_e32 v29, v29, v96
	v_fmac_f32_e32 v29, v28, v94
	v_mul_f32_e32 v25, v25, v93
	v_fmac_f32_e32 v29, v30, v95
	v_fmac_f32_e32 v25, v24, v90
	v_mul_f32_e32 v21, v21, v89
	v_fmac_f32_e32 v29, v31, v92
	v_fmac_f32_e32 v25, v26, v91
	v_fmac_f32_e32 v21, v20, v86
	v_mul_f32_e32 v17, v17, v85
	v_add_f32_e32 v28, 0, v29
	v_fmac_f32_e32 v25, v27, v88
	v_fmac_f32_e32 v21, v22, v87
	v_fmac_f32_e32 v17, v16, v81
	v_add_f32_e32 v24, v28, v25
	v_fmac_f32_e32 v21, v23, v84
	v_fmac_f32_e32 v17, v18, v82
	v_add_f32_e32 v20, v24, v21
	v_fmac_f32_e32 v17, v19, v80
	v_add_f32_e32 v16, v20, v17
	s_nop 1
	v_add_f32_dpp v17, v16, v16 quad_perm:[1,0,3,2] row_mask:0xf bank_mask:0xf
	s_nop 1
	v_add_f32_dpp v16, v17, v17 quad_perm:[2,3,0,1] row_mask:0xf bank_mask:0xf
	s_nop 1
	v_add_f32_dpp v17, v16, v16 row_half_mirror row_mask:0xf bank_mask:0xf
	s_nop 1
	v_add_f32_dpp v16, v17, v17 row_mirror row_mask:0xf bank_mask:0xf
	s_nop 1
	v_readlane_b32 s98, v16, 0
	v_readlane_b32 s99, v16, 16
	v_readlane_b32 s100, v16, 32
	v_readlane_b32 s101, v16, 48
	s_nop 1
	v_mov_b32_e32 v16, s98
	v_add_f32_e32 v16, s99, v16
	v_add_f32_e32 v16, s100, v16
	v_add_f32_e32 v16, s101, v16
	v_mov_b32_e32 v17, 0
	s_and_saveexec_b64 s[26:27], s[2:3]
	s_cbranch_execz .LBB0_189
	v_lshl_add_u64 v[18:19], v[104:105], 2, s[10:11]
	v_cndmask_b32_e64 v106, v146, v147, s[4:5]
	v_lshl_add_u64 v[18:19], v[18:19], 0, v[106:107]
	s_waitcnt lgkmcnt(0)
	v_add_f32_e32 v16, v16, v17
	global_store_dword v[18:19], v16, off
.LBB0_189:
	s_or_b64 exec, exec, s[26:27]
	v_mul_f32_e32 v13, v13, v96
	v_fmac_f32_e32 v13, v12, v94
	v_mul_f32_e32 v9, v9, v93
	v_fmac_f32_e32 v13, v14, v95
	v_fmac_f32_e32 v9, v8, v90
	v_mul_f32_e32 v5, v5, v89
	v_fmac_f32_e32 v13, v15, v92
	v_fmac_f32_e32 v9, v10, v91
	v_fmac_f32_e32 v5, v4, v86
	v_mul_f32_e32 v1, v1, v85
	v_add_f32_e32 v12, 0, v13
	v_fmac_f32_e32 v9, v11, v88
	v_fmac_f32_e32 v5, v6, v87
	v_fmac_f32_e32 v1, v0, v81
	v_add_f32_e32 v8, v12, v9
	v_fmac_f32_e32 v5, v7, v84
	v_fmac_f32_e32 v1, v2, v82
	v_add_f32_e32 v4, v8, v5
	v_fmac_f32_e32 v1, v3, v80
	v_add_f32_e32 v0, v4, v1
	s_nop 1
	v_add_f32_dpp v1, v0, v0 quad_perm:[1,0,3,2] row_mask:0xf bank_mask:0xf
	s_nop 1
	v_add_f32_dpp v0, v1, v1 quad_perm:[2,3,0,1] row_mask:0xf bank_mask:0xf
	s_nop 1
	v_add_f32_dpp v1, v0, v0 row_half_mirror row_mask:0xf bank_mask:0xf
	s_nop 1
	v_add_f32_dpp v0, v1, v1 row_mirror row_mask:0xf bank_mask:0xf
	s_nop 1
	v_readlane_b32 s98, v0, 0
	v_readlane_b32 s99, v0, 16
	v_readlane_b32 s100, v0, 32
	v_readlane_b32 s101, v0, 48
	s_nop 1
	v_mov_b32_e32 v0, s98
	v_add_f32_e32 v0, s99, v0
	v_add_f32_e32 v0, s100, v0
	v_add_f32_e32 v0, s101, v0
	v_mov_b32_e32 v1, 0
	s_and_saveexec_b64 s[4:5], s[2:3]
	s_cbranch_execz .LBB0_141
	s_waitcnt lgkmcnt(0)
	v_add_f32_e32 v0, v0, v1
	s_and_saveexec_b64 s[26:27], s[6:7]
	s_xor_b64 s[6:7], exec, s[26:27]
	s_cbranch_execz .LBB0_192
	v_lshl_add_u64 v[2:3], v[104:105], 2, s[10:11]
	v_add_co_u32_e32 v2, vcc, 0x27000, v2
	s_nop 1
	v_addc_co_u32_e32 v3, vcc, 0, v3, vcc
	global_store_dword v[2:3], v0, off offset:12
.LBB0_192:
	s_andn2_saveexec_b64 s[6:7], s[6:7]
	s_cbranch_execz .LBB0_141
	v_ashrrev_i32_e32 v37, 31, v36
	v_lshl_add_u64 v[2:3], v[36:37], 2, s[10:11]
	global_store_dword v[2:3], v0, off
	s_branch .LBB0_141
	s_nop 0
	s_nop 0
	s_nop 0
	s_nop 0
	s_nop 0
	s_nop 0
	s_nop 0
	s_nop 0
	s_nop 0
	s_nop 0
	s_nop 0
	s_nop 0
.LBB0_194:
	s_or_b64 exec, exec, s[0:1]
	s_lshl_b32 s12, s33, 9
	v_add_u32_e32 v68, s12, v168
	s_lshl_b32 s10, s90, 9
	s_mul_i32 s22, s90, 0x600
	s_add_u32 s0, s68, 0x4e00000
	v_add_u32_e32 v69, s22, v68
	s_mov_b32 s2, 0x80000
	s_addc_u32 s1, s69, 0
	v_cmp_gt_i32_e32 vcc, s2, v69
	v_mov_b32_e32 v0, v68
	s_and_saveexec_b64 s[2:3], vcc
	s_cbranch_execz .LBB0_200
	v_readfirstlane_b32 s4, v171
	v_readlane_b32 s38, v251, 23
	v_readlane_b32 s39, v251, 24
	v_readlane_b32 s40, v251, 25
	v_readlane_b32 s41, v251, 26
	v_lshrrev_b32_e32 v126, 2, v170
	v_and_b32_e32 v127, 3, v170
	v_mov_b32_e32 v128, 0
	v_lshlrev_b32_e32 v126, 8, v126
	v_lshlrev_b32_e32 v127, 5, v127
	v_mov_b32_e32 v118, 0
	v_mov_b32_e32 v119, 0
	v_mov_b32_e32 v120, 0
	v_mov_b32_e32 v121, 0
	v_mov_b32_e32 v122, 0
	v_mov_b32_e32 v123, 0
	v_mov_b32_e32 v124, 0
	v_mov_b32_e32 v125, 0
	s_lshl_b32 s5, s33, 3
	s_add_u32 s4, s4, s5
	s_lshr_b32 s5, s4, 5
	s_and_b32 s6, s4, 31
	s_lshl_b32 s7, s5, 12
	s_add_u32 s12, s38, s7
	s_addc_u32 s13, s39, 0
	s_add_u32 s14, s40, s7
	s_addc_u32 s15, s41, 0
	s_mul_i32 s7, s5, 33
	s_add_u32 s7, s7, s6
	s_lshl_b32 s7, s7, 9
	s_add_u32 s16, s68, s7
	s_addc_u32 s17, s69, 0
	s_add_u32 s16, s16, 0x5000000
	s_addc_u32 s17, s17, 0
	s_lshl_b32 s7, s5, 13
	s_add_u32 s18, s68, s7
	s_addc_u32 s19, s69, 0
	s_add_u32 s18, s18, 0x5108000
	s_addc_u32 s19, s19, 0
	global_load_dwordx4 v[0:3], v126, s[12:13]
	global_load_dwordx4 v[4:7], v126, s[14:15]
	global_load_dwordx4 v[8:11], v128, s[16:17]
	global_load_dwordx4 v[12:15], v128, s[16:17] offset:16
	global_load_dwordx4 v[16:19], v127, s[18:19]
	global_load_dwordx4 v[20:23], v127, s[18:19] offset:16
	global_load_dwordx4 v[24:27], v127, s[18:19] offset:128
	global_load_dwordx4 v[28:31], v127, s[18:19] offset:144
	global_load_dwordx4 v[32:35], v127, s[18:19] offset:256
	global_load_dwordx4 v[36:39], v127, s[18:19] offset:272
	global_load_dwordx4 v[40:43], v127, s[18:19] offset:384
	global_load_dwordx4 v[44:47], v127, s[18:19] offset:400
	s_add_u32 s18, s18, 0x200
	s_addc_u32 s19, s19, 0
	global_load_dwordx4 v[70:73], v126, s[12:13] offset:16
	global_load_dwordx4 v[74:77], v126, s[14:15] offset:16
	global_load_dwordx4 v[78:81], v128, s[16:17] offset:32
	global_load_dwordx4 v[82:85], v128, s[16:17] offset:48
	global_load_dwordx4 v[86:89], v127, s[18:19]
	global_load_dwordx4 v[90:93], v127, s[18:19] offset:16
	global_load_dwordx4 v[94:97], v127, s[18:19] offset:128
	global_load_dwordx4 v[98:101], v127, s[18:19] offset:144
	global_load_dwordx4 v[102:105], v127, s[18:19] offset:256
	global_load_dwordx4 v[106:109], v127, s[18:19] offset:272
	global_load_dwordx4 v[110:113], v127, s[18:19] offset:384
	global_load_dwordx4 v[114:117], v127, s[18:19] offset:400
	s_add_u32 s18, s18, 0x200
	s_addc_u32 s19, s19, 0
	s_waitcnt vmcnt(12)
; __device__ __forceinline__ float2 cmul(float2 a, float2 b) { return make_float2(a.x * b.x - a.y * b.y, a.x * b.y + a.y * b.x); }
; __device__ __forceinline__ void phase1(const Params& P) {
;     ...
;             for (int p = 0; p < 64; ++p) {
; #pragma unroll
;                 for (int q = 0; q < 4; ++q) {
;                     const int e = e0 + q * gsz;
;                     const int cp = e & 15, c = (e >> 4) & 15, tau = (e >> 8) & 31, dg = e >> 13;
;                     const float2 C = make_float2(P.in[17][(dg * 16 + c) * 64 + p], P.in[18][(dg * 16 + c) * 64 + p]);
;                     const float2 z = cmul(LP[(dg * 33 + tau) * 64 + p], BB[(dg * 64 + p) * 16 + cp]);
;                     sacc[q] += C.x * z.x - C.y * z.y;
;                 }
	v_pk_mul_f32 v[130:131], v[16:17], v[8:9] op_sel_hi:[1,0]
	v_pk_fma_f32 v[132:133], v[16:17], v[8:9], v[130:131] op_sel:[1,1,0] op_sel_hi:[0,1,1] neg_lo:[0,1,0]
	v_fmac_f32_e32 v118, v132, v0
	v_fmac_f32_e32 v122, v133, v4
	v_pk_mul_f32 v[134:135], v[18:19], v[8:9] op_sel_hi:[1,0]
	v_pk_fma_f32 v[136:137], v[18:19], v[8:9], v[134:135] op_sel:[1,1,0] op_sel_hi:[0,1,1] neg_lo:[0,1,0]
	v_fmac_f32_e32 v119, v136, v0
	v_fmac_f32_e32 v123, v137, v4
	v_pk_mul_f32 v[130:131], v[20:21], v[8:9] op_sel_hi:[1,0]
	v_pk_fma_f32 v[132:133], v[20:21], v[8:9], v[130:131] op_sel:[1,1,0] op_sel_hi:[0,1,1] neg_lo:[0,1,0]
	v_fmac_f32_e32 v120, v132, v0
	v_fmac_f32_e32 v124, v133, v4
	v_pk_mul_f32 v[134:135], v[22:23], v[8:9] op_sel_hi:[1,0]
	v_pk_fma_f32 v[136:137], v[22:23], v[8:9], v[134:135] op_sel:[1,1,0] op_sel_hi:[0,1,1] neg_lo:[0,1,0]
	v_fmac_f32_e32 v121, v136, v0
	v_fmac_f32_e32 v125, v137, v4
	v_pk_mul_f32 v[130:131], v[24:25], v[10:11] op_sel_hi:[1,0]
	v_pk_fma_f32 v[132:133], v[24:25], v[10:11], v[130:131] op_sel:[1,1,0] op_sel_hi:[0,1,1] neg_lo:[0,1,0]
	v_fmac_f32_e32 v118, v132, v1
	v_fmac_f32_e32 v122, v133, v5
	v_pk_mul_f32 v[134:135], v[26:27], v[10:11] op_sel_hi:[1,0]
	v_pk_fma_f32 v[136:137], v[26:27], v[10:11], v[134:135] op_sel:[1,1,0] op_sel_hi:[0,1,1] neg_lo:[0,1,0]
	v_fmac_f32_e32 v119, v136, v1
	v_fmac_f32_e32 v123, v137, v5
	v_pk_mul_f32 v[130:131], v[28:29], v[10:11] op_sel_hi:[1,0]
	v_pk_fma_f32 v[132:133], v[28:29], v[10:11], v[130:131] op_sel:[1,1,0] op_sel_hi:[0,1,1] neg_lo:[0,1,0]
	v_fmac_f32_e32 v120, v132, v1
	v_fmac_f32_e32 v124, v133, v5
	v_pk_mul_f32 v[134:135], v[30:31], v[10:11] op_sel_hi:[1,0]
	v_pk_fma_f32 v[136:137], v[30:31], v[10:11], v[134:135] op_sel:[1,1,0] op_sel_hi:[0,1,1] neg_lo:[0,1,0]
	v_fmac_f32_e32 v121, v136, v1
	v_fmac_f32_e32 v125, v137, v5
	v_pk_mul_f32 v[130:131], v[32:33], v[12:13] op_sel_hi:[1,0]
	v_pk_fma_f32 v[132:133], v[32:33], v[12:13], v[130:131] op_sel:[1,1,0] op_sel_hi:[0,1,1] neg_lo:[0,1,0]
	v_fmac_f32_e32 v118, v132, v2
	v_fmac_f32_e32 v122, v133, v6
	v_pk_mul_f32 v[134:135], v[34:35], v[12:13] op_sel_hi:[1,0]
	v_pk_fma_f32 v[136:137], v[34:35], v[12:13], v[134:135] op_sel:[1,1,0] op_sel_hi:[0,1,1] neg_lo:[0,1,0]
	v_fmac_f32_e32 v119, v136, v2
	v_fmac_f32_e32 v123, v137, v6
	v_pk_mul_f32 v[130:131], v[36:37], v[12:13] op_sel_hi:[1,0]
	v_pk_fma_f32 v[132:133], v[36:37], v[12:13], v[130:131] op_sel:[1,1,0] op_sel_hi:[0,1,1] neg_lo:[0,1,0]
	v_fmac_f32_e32 v120, v132, v2
	v_fmac_f32_e32 v124, v133, v6
	v_pk_mul_f32 v[134:135], v[38:39], v[12:13] op_sel_hi:[1,0]
	v_pk_fma_f32 v[136:137], v[38:39], v[12:13], v[134:135] op_sel:[1,1,0] op_sel_hi:[0,1,1] neg_lo:[0,1,0]
	v_fmac_f32_e32 v121, v136, v2
	v_fmac_f32_e32 v125, v137, v6
	v_pk_mul_f32 v[130:131], v[40:41], v[14:15] op_sel_hi:[1,0]
	v_pk_fma_f32 v[132:133], v[40:41], v[14:15], v[130:131] op_sel:[1,1,0] op_sel_hi:[0,1,1] neg_lo:[0,1,0]
	v_fmac_f32_e32 v118, v132, v3
	v_fmac_f32_e32 v122, v133, v7
	v_pk_mul_f32 v[134:135], v[42:43], v[14:15] op_sel_hi:[1,0]
	v_pk_fma_f32 v[136:137], v[42:43], v[14:15], v[134:135] op_sel:[1,1,0] op_sel_hi:[0,1,1] neg_lo:[0,1,0]
	v_fmac_f32_e32 v119, v136, v3
	v_fmac_f32_e32 v123, v137, v7
	v_pk_mul_f32 v[130:131], v[44:45], v[14:15] op_sel_hi:[1,0]
	v_pk_fma_f32 v[132:133], v[44:45], v[14:15], v[130:131] op_sel:[1,1,0] op_sel_hi:[0,1,1] neg_lo:[0,1,0]
	v_fmac_f32_e32 v120, v132, v3
	v_fmac_f32_e32 v124, v133, v7
	v_pk_mul_f32 v[134:135], v[46:47], v[14:15] op_sel_hi:[1,0]
	v_pk_fma_f32 v[136:137], v[46:47], v[14:15], v[134:135] op_sel:[1,1,0] op_sel_hi:[0,1,1] neg_lo:[0,1,0]
	v_fmac_f32_e32 v121, v136, v3
	v_fmac_f32_e32 v125, v137, v7
	global_load_dwordx4 v[0:3], v126, s[12:13] offset:32
	global_load_dwordx4 v[4:7], v126, s[14:15] offset:32
	global_load_dwordx4 v[8:11], v128, s[16:17] offset:64
	global_load_dwordx4 v[12:15], v128, s[16:17] offset:80
	global_load_dwordx4 v[16:19], v127, s[18:19]
	global_load_dwordx4 v[20:23], v127, s[18:19] offset:16
	global_load_dwordx4 v[24:27], v127, s[18:19] offset:128
	global_load_dwordx4 v[28:31], v127, s[18:19] offset:144
	global_load_dwordx4 v[32:35], v127, s[18:19] offset:256
	global_load_dwordx4 v[36:39], v127, s[18:19] offset:272
	global_load_dwordx4 v[40:43], v127, s[18:19] offset:384
	global_load_dwordx4 v[44:47], v127, s[18:19] offset:400
	s_add_u32 s18, s18, 0x200
	s_addc_u32 s19, s19, 0
	s_waitcnt vmcnt(12)
; __device__ __forceinline__ float2 cmul(float2 a, float2 b) { return make_float2(a.x * b.x - a.y * b.y, a.x * b.y + a.y * b.x); }
; __device__ __forceinline__ void phase1(const Params& P) {
;     ...
;             for (int p = 0; p < 64; ++p) {
; #pragma unroll
;                 for (int q = 0; q < 4; ++q) {
;                     const int e = e0 + q * gsz;
;                     const int cp = e & 15, c = (e >> 4) & 15, tau = (e >> 8) & 31, dg = e >> 13;
;                     const float2 C = make_float2(P.in[17][(dg * 16 + c) * 64 + p], P.in[18][(dg * 16 + c) * 64 + p]);
;                     const float2 z = cmul(LP[(dg * 33 + tau) * 64 + p], BB[(dg * 64 + p) * 16 + cp]);
;                     sacc[q] += C.x * z.x - C.y * z.y;
;                 }
	v_pk_mul_f32 v[130:131], v[86:87], v[78:79] op_sel_hi:[1,0]
	v_pk_fma_f32 v[132:133], v[86:87], v[78:79], v[130:131] op_sel:[1,1,0] op_sel_hi:[0,1,1] neg_lo:[0,1,0]
	v_fmac_f32_e32 v118, v132, v70
	v_fmac_f32_e32 v122, v133, v74
	v_pk_mul_f32 v[134:135], v[88:89], v[78:79] op_sel_hi:[1,0]
	v_pk_fma_f32 v[136:137], v[88:89], v[78:79], v[134:135] op_sel:[1,1,0] op_sel_hi:[0,1,1] neg_lo:[0,1,0]
	v_fmac_f32_e32 v119, v136, v70
	v_fmac_f32_e32 v123, v137, v74
	v_pk_mul_f32 v[130:131], v[90:91], v[78:79] op_sel_hi:[1,0]
	v_pk_fma_f32 v[132:133], v[90:91], v[78:79], v[130:131] op_sel:[1,1,0] op_sel_hi:[0,1,1] neg_lo:[0,1,0]
	v_fmac_f32_e32 v120, v132, v70
	v_fmac_f32_e32 v124, v133, v74
	v_pk_mul_f32 v[134:135], v[92:93], v[78:79] op_sel_hi:[1,0]
	v_pk_fma_f32 v[136:137], v[92:93], v[78:79], v[134:135] op_sel:[1,1,0] op_sel_hi:[0,1,1] neg_lo:[0,1,0]
	v_fmac_f32_e32 v121, v136, v70
	v_fmac_f32_e32 v125, v137, v74
	v_pk_mul_f32 v[130:131], v[94:95], v[80:81] op_sel_hi:[1,0]
	v_pk_fma_f32 v[132:133], v[94:95], v[80:81], v[130:131] op_sel:[1,1,0] op_sel_hi:[0,1,1] neg_lo:[0,1,0]
	v_fmac_f32_e32 v118, v132, v71
	v_fmac_f32_e32 v122, v133, v75
	v_pk_mul_f32 v[134:135], v[96:97], v[80:81] op_sel_hi:[1,0]
	v_pk_fma_f32 v[136:137], v[96:97], v[80:81], v[134:135] op_sel:[1,1,0] op_sel_hi:[0,1,1] neg_lo:[0,1,0]
	v_fmac_f32_e32 v119, v136, v71
	v_fmac_f32_e32 v123, v137, v75
	v_pk_mul_f32 v[130:131], v[98:99], v[80:81] op_sel_hi:[1,0]
	v_pk_fma_f32 v[132:133], v[98:99], v[80:81], v[130:131] op_sel:[1,1,0] op_sel_hi:[0,1,1] neg_lo:[0,1,0]
	v_fmac_f32_e32 v120, v132, v71
	v_fmac_f32_e32 v124, v133, v75
	v_pk_mul_f32 v[134:135], v[100:101], v[80:81] op_sel_hi:[1,0]
	v_pk_fma_f32 v[136:137], v[100:101], v[80:81], v[134:135] op_sel:[1,1,0] op_sel_hi:[0,1,1] neg_lo:[0,1,0]
	v_fmac_f32_e32 v121, v136, v71
	v_fmac_f32_e32 v125, v137, v75
	v_pk_mul_f32 v[130:131], v[102:103], v[82:83] op_sel_hi:[1,0]
	v_pk_fma_f32 v[132:133], v[102:103], v[82:83], v[130:131] op_sel:[1,1,0] op_sel_hi:[0,1,1] neg_lo:[0,1,0]
	v_fmac_f32_e32 v118, v132, v72
	v_fmac_f32_e32 v122, v133, v76
	v_pk_mul_f32 v[134:135], v[104:105], v[82:83] op_sel_hi:[1,0]
	v_pk_fma_f32 v[136:137], v[104:105], v[82:83], v[134:135] op_sel:[1,1,0] op_sel_hi:[0,1,1] neg_lo:[0,1,0]
	v_fmac_f32_e32 v119, v136, v72
	v_fmac_f32_e32 v123, v137, v76
	v_pk_mul_f32 v[130:131], v[106:107], v[82:83] op_sel_hi:[1,0]
	v_pk_fma_f32 v[132:133], v[106:107], v[82:83], v[130:131] op_sel:[1,1,0] op_sel_hi:[0,1,1] neg_lo:[0,1,0]
	v_fmac_f32_e32 v120, v132, v72
	v_fmac_f32_e32 v124, v133, v76
	v_pk_mul_f32 v[134:135], v[108:109], v[82:83] op_sel_hi:[1,0]
	v_pk_fma_f32 v[136:137], v[108:109], v[82:83], v[134:135] op_sel:[1,1,0] op_sel_hi:[0,1,1] neg_lo:[0,1,0]
	v_fmac_f32_e32 v121, v136, v72
	v_fmac_f32_e32 v125, v137, v76
	v_pk_mul_f32 v[130:131], v[110:111], v[84:85] op_sel_hi:[1,0]
	v_pk_fma_f32 v[132:133], v[110:111], v[84:85], v[130:131] op_sel:[1,1,0] op_sel_hi:[0,1,1] neg_lo:[0,1,0]
	v_fmac_f32_e32 v118, v132, v73
	v_fmac_f32_e32 v122, v133, v77
	v_pk_mul_f32 v[134:135], v[112:113], v[84:85] op_sel_hi:[1,0]
	v_pk_fma_f32 v[136:137], v[112:113], v[84:85], v[134:135] op_sel:[1,1,0] op_sel_hi:[0,1,1] neg_lo:[0,1,0]
	v_fmac_f32_e32 v119, v136, v73
	v_fmac_f32_e32 v123, v137, v77
	v_pk_mul_f32 v[130:131], v[114:115], v[84:85] op_sel_hi:[1,0]
	v_pk_fma_f32 v[132:133], v[114:115], v[84:85], v[130:131] op_sel:[1,1,0] op_sel_hi:[0,1,1] neg_lo:[0,1,0]
	v_fmac_f32_e32 v120, v132, v73
	v_fmac_f32_e32 v124, v133, v77
	v_pk_mul_f32 v[134:135], v[116:117], v[84:85] op_sel_hi:[1,0]
	v_pk_fma_f32 v[136:137], v[116:117], v[84:85], v[134:135] op_sel:[1,1,0] op_sel_hi:[0,1,1] neg_lo:[0,1,0]
	v_fmac_f32_e32 v121, v136, v73
	v_fmac_f32_e32 v125, v137, v77
	global_load_dwordx4 v[70:73], v126, s[12:13] offset:48
	global_load_dwordx4 v[74:77], v126, s[14:15] offset:48
	global_load_dwordx4 v[78:81], v128, s[16:17] offset:96
	global_load_dwordx4 v[82:85], v128, s[16:17] offset:112
	global_load_dwordx4 v[86:89], v127, s[18:19]
	global_load_dwordx4 v[90:93], v127, s[18:19] offset:16
	global_load_dwordx4 v[94:97], v127, s[18:19] offset:128
	global_load_dwordx4 v[98:101], v127, s[18:19] offset:144
	global_load_dwordx4 v[102:105], v127, s[18:19] offset:256
	global_load_dwordx4 v[106:109], v127, s[18:19] offset:272
	global_load_dwordx4 v[110:113], v127, s[18:19] offset:384
	global_load_dwordx4 v[114:117], v127, s[18:19] offset:400
	s_add_u32 s18, s18, 0x200
	s_addc_u32 s19, s19, 0
	s_waitcnt vmcnt(12)
; __device__ __forceinline__ float2 cmul(float2 a, float2 b) { return make_float2(a.x * b.x - a.y * b.y, a.x * b.y + a.y * b.x); }
; __device__ __forceinline__ void phase1(const Params& P) {
;     ...
;             for (int p = 0; p < 64; ++p) {
; #pragma unroll
;                 for (int q = 0; q < 4; ++q) {
;                     const int e = e0 + q * gsz;
;                     const int cp = e & 15, c = (e >> 4) & 15, tau = (e >> 8) & 31, dg = e >> 13;
;                     const float2 C = make_float2(P.in[17][(dg * 16 + c) * 64 + p], P.in[18][(dg * 16 + c) * 64 + p]);
;                     const float2 z = cmul(LP[(dg * 33 + tau) * 64 + p], BB[(dg * 64 + p) * 16 + cp]);
;                     sacc[q] += C.x * z.x - C.y * z.y;
;                 }
	v_pk_mul_f32 v[130:131], v[16:17], v[8:9] op_sel_hi:[1,0]
	v_pk_fma_f32 v[132:133], v[16:17], v[8:9], v[130:131] op_sel:[1,1,0] op_sel_hi:[0,1,1] neg_lo:[0,1,0]
	v_fmac_f32_e32 v118, v132, v0
	v_fmac_f32_e32 v122, v133, v4
	v_pk_mul_f32 v[134:135], v[18:19], v[8:9] op_sel_hi:[1,0]
	v_pk_fma_f32 v[136:137], v[18:19], v[8:9], v[134:135] op_sel:[1,1,0] op_sel_hi:[0,1,1] neg_lo:[0,1,0]
	v_fmac_f32_e32 v119, v136, v0
	v_fmac_f32_e32 v123, v137, v4
	v_pk_mul_f32 v[130:131], v[20:21], v[8:9] op_sel_hi:[1,0]
	v_pk_fma_f32 v[132:133], v[20:21], v[8:9], v[130:131] op_sel:[1,1,0] op_sel_hi:[0,1,1] neg_lo:[0,1,0]
	v_fmac_f32_e32 v120, v132, v0
	v_fmac_f32_e32 v124, v133, v4
	v_pk_mul_f32 v[134:135], v[22:23], v[8:9] op_sel_hi:[1,0]
	v_pk_fma_f32 v[136:137], v[22:23], v[8:9], v[134:135] op_sel:[1,1,0] op_sel_hi:[0,1,1] neg_lo:[0,1,0]
	v_fmac_f32_e32 v121, v136, v0
	v_fmac_f32_e32 v125, v137, v4
	v_pk_mul_f32 v[130:131], v[24:25], v[10:11] op_sel_hi:[1,0]
	v_pk_fma_f32 v[132:133], v[24:25], v[10:11], v[130:131] op_sel:[1,1,0] op_sel_hi:[0,1,1] neg_lo:[0,1,0]
	v_fmac_f32_e32 v118, v132, v1
	v_fmac_f32_e32 v122, v133, v5
	v_pk_mul_f32 v[134:135], v[26:27], v[10:11] op_sel_hi:[1,0]
	v_pk_fma_f32 v[136:137], v[26:27], v[10:11], v[134:135] op_sel:[1,1,0] op_sel_hi:[0,1,1] neg_lo:[0,1,0]
	v_fmac_f32_e32 v119, v136, v1
	v_fmac_f32_e32 v123, v137, v5
	v_pk_mul_f32 v[130:131], v[28:29], v[10:11] op_sel_hi:[1,0]
	v_pk_fma_f32 v[132:133], v[28:29], v[10:11], v[130:131] op_sel:[1,1,0] op_sel_hi:[0,1,1] neg_lo:[0,1,0]
	v_fmac_f32_e32 v120, v132, v1
	v_fmac_f32_e32 v124, v133, v5
	v_pk_mul_f32 v[134:135], v[30:31], v[10:11] op_sel_hi:[1,0]
	v_pk_fma_f32 v[136:137], v[30:31], v[10:11], v[134:135] op_sel:[1,1,0] op_sel_hi:[0,1,1] neg_lo:[0,1,0]
	v_fmac_f32_e32 v121, v136, v1
	v_fmac_f32_e32 v125, v137, v5
	v_pk_mul_f32 v[130:131], v[32:33], v[12:13] op_sel_hi:[1,0]
	v_pk_fma_f32 v[132:133], v[32:33], v[12:13], v[130:131] op_sel:[1,1,0] op_sel_hi:[0,1,1] neg_lo:[0,1,0]
	v_fmac_f32_e32 v118, v132, v2
	v_fmac_f32_e32 v122, v133, v6
	v_pk_mul_f32 v[134:135], v[34:35], v[12:13] op_sel_hi:[1,0]
	v_pk_fma_f32 v[136:137], v[34:35], v[12:13], v[134:135] op_sel:[1,1,0] op_sel_hi:[0,1,1] neg_lo:[0,1,0]
	v_fmac_f32_e32 v119, v136, v2
	v_fmac_f32_e32 v123, v137, v6
	v_pk_mul_f32 v[130:131], v[36:37], v[12:13] op_sel_hi:[1,0]
	v_pk_fma_f32 v[132:133], v[36:37], v[12:13], v[130:131] op_sel:[1,1,0] op_sel_hi:[0,1,1] neg_lo:[0,1,0]
	v_fmac_f32_e32 v120, v132, v2
	v_fmac_f32_e32 v124, v133, v6
	v_pk_mul_f32 v[134:135], v[38:39], v[12:13] op_sel_hi:[1,0]
	v_pk_fma_f32 v[136:137], v[38:39], v[12:13], v[134:135] op_sel:[1,1,0] op_sel_hi:[0,1,1] neg_lo:[0,1,0]
	v_fmac_f32_e32 v121, v136, v2
	v_fmac_f32_e32 v125, v137, v6
	v_pk_mul_f32 v[130:131], v[40:41], v[14:15] op_sel_hi:[1,0]
	v_pk_fma_f32 v[132:133], v[40:41], v[14:15], v[130:131] op_sel:[1,1,0] op_sel_hi:[0,1,1] neg_lo:[0,1,0]
	v_fmac_f32_e32 v118, v132, v3
	v_fmac_f32_e32 v122, v133, v7
	v_pk_mul_f32 v[134:135], v[42:43], v[14:15] op_sel_hi:[1,0]
	v_pk_fma_f32 v[136:137], v[42:43], v[14:15], v[134:135] op_sel:[1,1,0] op_sel_hi:[0,1,1] neg_lo:[0,1,0]
	v_fmac_f32_e32 v119, v136, v3
	v_fmac_f32_e32 v123, v137, v7
	v_pk_mul_f32 v[130:131], v[44:45], v[14:15] op_sel_hi:[1,0]
	v_pk_fma_f32 v[132:133], v[44:45], v[14:15], v[130:131] op_sel:[1,1,0] op_sel_hi:[0,1,1] neg_lo:[0,1,0]
	v_fmac_f32_e32 v120, v132, v3
	v_fmac_f32_e32 v124, v133, v7
	v_pk_mul_f32 v[134:135], v[46:47], v[14:15] op_sel_hi:[1,0]
	v_pk_fma_f32 v[136:137], v[46:47], v[14:15], v[134:135] op_sel:[1,1,0] op_sel_hi:[0,1,1] neg_lo:[0,1,0]
	v_fmac_f32_e32 v121, v136, v3
	v_fmac_f32_e32 v125, v137, v7
	global_load_dwordx4 v[0:3], v126, s[12:13] offset:64
	global_load_dwordx4 v[4:7], v126, s[14:15] offset:64
	global_load_dwordx4 v[8:11], v128, s[16:17] offset:128
	global_load_dwordx4 v[12:15], v128, s[16:17] offset:144
	global_load_dwordx4 v[16:19], v127, s[18:19]
	global_load_dwordx4 v[20:23], v127, s[18:19] offset:16
	global_load_dwordx4 v[24:27], v127, s[18:19] offset:128
	global_load_dwordx4 v[28:31], v127, s[18:19] offset:144
	global_load_dwordx4 v[32:35], v127, s[18:19] offset:256
	global_load_dwordx4 v[36:39], v127, s[18:19] offset:272
	global_load_dwordx4 v[40:43], v127, s[18:19] offset:384
	global_load_dwordx4 v[44:47], v127, s[18:19] offset:400
	s_add_u32 s18, s18, 0x200
	s_addc_u32 s19, s19, 0
	s_waitcnt vmcnt(12)
; __device__ __forceinline__ float2 cmul(float2 a, float2 b) { return make_float2(a.x * b.x - a.y * b.y, a.x * b.y + a.y * b.x); }
; __device__ __forceinline__ void phase1(const Params& P) {
;     ...
;             for (int p = 0; p < 64; ++p) {
; #pragma unroll
;                 for (int q = 0; q < 4; ++q) {
;                     const int e = e0 + q * gsz;
;                     const int cp = e & 15, c = (e >> 4) & 15, tau = (e >> 8) & 31, dg = e >> 13;
;                     const float2 C = make_float2(P.in[17][(dg * 16 + c) * 64 + p], P.in[18][(dg * 16 + c) * 64 + p]);
;                     const float2 z = cmul(LP[(dg * 33 + tau) * 64 + p], BB[(dg * 64 + p) * 16 + cp]);
;                     sacc[q] += C.x * z.x - C.y * z.y;
;                 }
;             }
	v_pk_mul_f32 v[130:131], v[86:87], v[78:79] op_sel_hi:[1,0]
	v_pk_fma_f32 v[132:133], v[86:87], v[78:79], v[130:131] op_sel:[1,1,0] op_sel_hi:[0,1,1] neg_lo:[0,1,0]
	v_fmac_f32_e32 v118, v132, v70
	v_fmac_f32_e32 v122, v133, v74
	v_pk_mul_f32 v[134:135], v[88:89], v[78:79] op_sel_hi:[1,0]
	v_pk_fma_f32 v[136:137], v[88:89], v[78:79], v[134:135] op_sel:[1,1,0] op_sel_hi:[0,1,1] neg_lo:[0,1,0]
	v_fmac_f32_e32 v119, v136, v70
	v_fmac_f32_e32 v123, v137, v74
	v_pk_mul_f32 v[130:131], v[90:91], v[78:79] op_sel_hi:[1,0]
	v_pk_fma_f32 v[132:133], v[90:91], v[78:79], v[130:131] op_sel:[1,1,0] op_sel_hi:[0,1,1] neg_lo:[0,1,0]
	v_fmac_f32_e32 v120, v132, v70
	v_fmac_f32_e32 v124, v133, v74
	v_pk_mul_f32 v[134:135], v[92:93], v[78:79] op_sel_hi:[1,0]
	v_pk_fma_f32 v[136:137], v[92:93], v[78:79], v[134:135] op_sel:[1,1,0] op_sel_hi:[0,1,1] neg_lo:[0,1,0]
	v_fmac_f32_e32 v121, v136, v70
	v_fmac_f32_e32 v125, v137, v74
	v_pk_mul_f32 v[130:131], v[94:95], v[80:81] op_sel_hi:[1,0]
	v_pk_fma_f32 v[132:133], v[94:95], v[80:81], v[130:131] op_sel:[1,1,0] op_sel_hi:[0,1,1] neg_lo:[0,1,0]
	v_fmac_f32_e32 v118, v132, v71
	v_fmac_f32_e32 v122, v133, v75
	v_pk_mul_f32 v[134:135], v[96:97], v[80:81] op_sel_hi:[1,0]
	v_pk_fma_f32 v[136:137], v[96:97], v[80:81], v[134:135] op_sel:[1,1,0] op_sel_hi:[0,1,1] neg_lo:[0,1,0]
	v_fmac_f32_e32 v119, v136, v71
	v_fmac_f32_e32 v123, v137, v75
	v_pk_mul_f32 v[130:131], v[98:99], v[80:81] op_sel_hi:[1,0]
	v_pk_fma_f32 v[132:133], v[98:99], v[80:81], v[130:131] op_sel:[1,1,0] op_sel_hi:[0,1,1] neg_lo:[0,1,0]
	v_fmac_f32_e32 v120, v132, v71
	v_fmac_f32_e32 v124, v133, v75
	v_pk_mul_f32 v[134:135], v[100:101], v[80:81] op_sel_hi:[1,0]
	v_pk_fma_f32 v[136:137], v[100:101], v[80:81], v[134:135] op_sel:[1,1,0] op_sel_hi:[0,1,1] neg_lo:[0,1,0]
	v_fmac_f32_e32 v121, v136, v71
	v_fmac_f32_e32 v125, v137, v75
	v_pk_mul_f32 v[130:131], v[102:103], v[82:83] op_sel_hi:[1,0]
	v_pk_fma_f32 v[132:133], v[102:103], v[82:83], v[130:131] op_sel:[1,1,0] op_sel_hi:[0,1,1] neg_lo:[0,1,0]
	v_fmac_f32_e32 v118, v132, v72
	v_fmac_f32_e32 v122, v133, v76
	v_pk_mul_f32 v[134:135], v[104:105], v[82:83] op_sel_hi:[1,0]
	v_pk_fma_f32 v[136:137], v[104:105], v[82:83], v[134:135] op_sel:[1,1,0] op_sel_hi:[0,1,1] neg_lo:[0,1,0]
	v_fmac_f32_e32 v119, v136, v72
	v_fmac_f32_e32 v123, v137, v76
	v_pk_mul_f32 v[130:131], v[106:107], v[82:83] op_sel_hi:[1,0]
	v_pk_fma_f32 v[132:133], v[106:107], v[82:83], v[130:131] op_sel:[1,1,0] op_sel_hi:[0,1,1] neg_lo:[0,1,0]
	v_fmac_f32_e32 v120, v132, v72
	v_fmac_f32_e32 v124, v133, v76
	v_pk_mul_f32 v[134:135], v[108:109], v[82:83] op_sel_hi:[1,0]
	v_pk_fma_f32 v[136:137], v[108:109], v[82:83], v[134:135] op_sel:[1,1,0] op_sel_hi:[0,1,1] neg_lo:[0,1,0]
	v_fmac_f32_e32 v121, v136, v72
	v_fmac_f32_e32 v125, v137, v76
	v_pk_mul_f32 v[130:131], v[110:111], v[84:85] op_sel_hi:[1,0]
	v_pk_fma_f32 v[132:133], v[110:111], v[84:85], v[130:131] op_sel:[1,1,0] op_sel_hi:[0,1,1] neg_lo:[0,1,0]
	v_fmac_f32_e32 v118, v132, v73
	v_fmac_f32_e32 v122, v133, v77
	v_pk_mul_f32 v[134:135], v[112:113], v[84:85] op_sel_hi:[1,0]
	v_pk_fma_f32 v[136:137], v[112:113], v[84:85], v[134:135] op_sel:[1,1,0] op_sel_hi:[0,1,1] neg_lo:[0,1,0]
	v_fmac_f32_e32 v119, v136, v73
	v_fmac_f32_e32 v123, v137, v77
	v_pk_mul_f32 v[130:131], v[114:115], v[84:85] op_sel_hi:[1,0]
	v_pk_fma_f32 v[132:133], v[114:115], v[84:85], v[130:131] op_sel:[1,1,0] op_sel_hi:[0,1,1] neg_lo:[0,1,0]
	v_fmac_f32_e32 v120, v132, v73
	v_fmac_f32_e32 v124, v133, v77
	v_pk_mul_f32 v[134:135], v[116:117], v[84:85] op_sel_hi:[1,0]
	v_pk_fma_f32 v[136:137], v[116:117], v[84:85], v[134:135] op_sel:[1,1,0] op_sel_hi:[0,1,1] neg_lo:[0,1,0]
	v_fmac_f32_e32 v121, v136, v73
	v_fmac_f32_e32 v125, v137, v77
	global_load_dwordx4 v[70:73], v126, s[12:13] offset:80
	global_load_dwordx4 v[74:77], v126, s[14:15] offset:80
	global_load_dwordx4 v[78:81], v128, s[16:17] offset:160
	global_load_dwordx4 v[82:85], v128, s[16:17] offset:176
	global_load_dwordx4 v[86:89], v127, s[18:19]
	global_load_dwordx4 v[90:93], v127, s[18:19] offset:16
	global_load_dwordx4 v[94:97], v127, s[18:19] offset:128
	global_load_dwordx4 v[98:101], v127, s[18:19] offset:144
	global_load_dwordx4 v[102:105], v127, s[18:19] offset:256
	global_load_dwordx4 v[106:109], v127, s[18:19] offset:272
	global_load_dwordx4 v[110:113], v127, s[18:19] offset:384
	global_load_dwordx4 v[114:117], v127, s[18:19] offset:400
	s_add_u32 s18, s18, 0x200
	s_addc_u32 s19, s19, 0
	s_waitcnt vmcnt(12)
; __device__ __forceinline__ float2 cmul(float2 a, float2 b) { return make_float2(a.x * b.x - a.y * b.y, a.x * b.y + a.y * b.x); }
; __device__ __forceinline__ void phase1(const Params& P) {
;     ...
;             for (int p = 0; p < 64; ++p) {
; #pragma unroll
;                 for (int q = 0; q < 4; ++q) {
;                     const int e = e0 + q * gsz;
;                     const int cp = e & 15, c = (e >> 4) & 15, tau = (e >> 8) & 31, dg = e >> 13;
;                     const float2 C = make_float2(P.in[17][(dg * 16 + c) * 64 + p], P.in[18][(dg * 16 + c) * 64 + p]);
;                     const float2 z = cmul(LP[(dg * 33 + tau) * 64 + p], BB[(dg * 64 + p) * 16 + cp]);
;                     sacc[q] += C.x * z.x - C.y * z.y;
;                 }
;             }
	v_pk_mul_f32 v[130:131], v[16:17], v[8:9] op_sel_hi:[1,0]
	v_pk_fma_f32 v[132:133], v[16:17], v[8:9], v[130:131] op_sel:[1,1,0] op_sel_hi:[0,1,1] neg_lo:[0,1,0]
	v_fmac_f32_e32 v118, v132, v0
	v_fmac_f32_e32 v122, v133, v4
	v_pk_mul_f32 v[134:135], v[18:19], v[8:9] op_sel_hi:[1,0]
	v_pk_fma_f32 v[136:137], v[18:19], v[8:9], v[134:135] op_sel:[1,1,0] op_sel_hi:[0,1,1] neg_lo:[0,1,0]
	v_fmac_f32_e32 v119, v136, v0
	v_fmac_f32_e32 v123, v137, v4
	v_pk_mul_f32 v[130:131], v[20:21], v[8:9] op_sel_hi:[1,0]
	v_pk_fma_f32 v[132:133], v[20:21], v[8:9], v[130:131] op_sel:[1,1,0] op_sel_hi:[0,1,1] neg_lo:[0,1,0]
	v_fmac_f32_e32 v120, v132, v0
	v_fmac_f32_e32 v124, v133, v4
	v_pk_mul_f32 v[134:135], v[22:23], v[8:9] op_sel_hi:[1,0]
	v_pk_fma_f32 v[136:137], v[22:23], v[8:9], v[134:135] op_sel:[1,1,0] op_sel_hi:[0,1,1] neg_lo:[0,1,0]
	v_fmac_f32_e32 v121, v136, v0
	v_fmac_f32_e32 v125, v137, v4
	v_pk_mul_f32 v[130:131], v[24:25], v[10:11] op_sel_hi:[1,0]
	v_pk_fma_f32 v[132:133], v[24:25], v[10:11], v[130:131] op_sel:[1,1,0] op_sel_hi:[0,1,1] neg_lo:[0,1,0]
	v_fmac_f32_e32 v118, v132, v1
	v_fmac_f32_e32 v122, v133, v5
	v_pk_mul_f32 v[134:135], v[26:27], v[10:11] op_sel_hi:[1,0]
	v_pk_fma_f32 v[136:137], v[26:27], v[10:11], v[134:135] op_sel:[1,1,0] op_sel_hi:[0,1,1] neg_lo:[0,1,0]
	v_fmac_f32_e32 v119, v136, v1
	v_fmac_f32_e32 v123, v137, v5
	v_pk_mul_f32 v[130:131], v[28:29], v[10:11] op_sel_hi:[1,0]
	v_pk_fma_f32 v[132:133], v[28:29], v[10:11], v[130:131] op_sel:[1,1,0] op_sel_hi:[0,1,1] neg_lo:[0,1,0]
	v_fmac_f32_e32 v120, v132, v1
	v_fmac_f32_e32 v124, v133, v5
	v_pk_mul_f32 v[134:135], v[30:31], v[10:11] op_sel_hi:[1,0]
	v_pk_fma_f32 v[136:137], v[30:31], v[10:11], v[134:135] op_sel:[1,1,0] op_sel_hi:[0,1,1] neg_lo:[0,1,0]
	v_fmac_f32_e32 v121, v136, v1
	v_fmac_f32_e32 v125, v137, v5
	v_pk_mul_f32 v[130:131], v[32:33], v[12:13] op_sel_hi:[1,0]
	v_pk_fma_f32 v[132:133], v[32:33], v[12:13], v[130:131] op_sel:[1,1,0] op_sel_hi:[0,1,1] neg_lo:[0,1,0]
	v_fmac_f32_e32 v118, v132, v2
	v_fmac_f32_e32 v122, v133, v6
	v_pk_mul_f32 v[134:135], v[34:35], v[12:13] op_sel_hi:[1,0]
	v_pk_fma_f32 v[136:137], v[34:35], v[12:13], v[134:135] op_sel:[1,1,0] op_sel_hi:[0,1,1] neg_lo:[0,1,0]
	v_fmac_f32_e32 v119, v136, v2
	v_fmac_f32_e32 v123, v137, v6
	v_pk_mul_f32 v[130:131], v[36:37], v[12:13] op_sel_hi:[1,0]
	v_pk_fma_f32 v[132:133], v[36:37], v[12:13], v[130:131] op_sel:[1,1,0] op_sel_hi:[0,1,1] neg_lo:[0,1,0]
	v_fmac_f32_e32 v120, v132, v2
	v_fmac_f32_e32 v124, v133, v6
	v_pk_mul_f32 v[134:135], v[38:39], v[12:13] op_sel_hi:[1,0]
	v_pk_fma_f32 v[136:137], v[38:39], v[12:13], v[134:135] op_sel:[1,1,0] op_sel_hi:[0,1,1] neg_lo:[0,1,0]
	v_fmac_f32_e32 v121, v136, v2
	v_fmac_f32_e32 v125, v137, v6
	v_pk_mul_f32 v[130:131], v[40:41], v[14:15] op_sel_hi:[1,0]
	v_pk_fma_f32 v[132:133], v[40:41], v[14:15], v[130:131] op_sel:[1,1,0] op_sel_hi:[0,1,1] neg_lo:[0,1,0]
	v_fmac_f32_e32 v118, v132, v3
	v_fmac_f32_e32 v122, v133, v7
	v_pk_mul_f32 v[134:135], v[42:43], v[14:15] op_sel_hi:[1,0]
	v_pk_fma_f32 v[136:137], v[42:43], v[14:15], v[134:135] op_sel:[1,1,0] op_sel_hi:[0,1,1] neg_lo:[0,1,0]
	v_fmac_f32_e32 v119, v136, v3
	v_fmac_f32_e32 v123, v137, v7
	v_pk_mul_f32 v[130:131], v[44:45], v[14:15] op_sel_hi:[1,0]
	v_pk_fma_f32 v[132:133], v[44:45], v[14:15], v[130:131] op_sel:[1,1,0] op_sel_hi:[0,1,1] neg_lo:[0,1,0]
	v_fmac_f32_e32 v120, v132, v3
	v_fmac_f32_e32 v124, v133, v7
	v_pk_mul_f32 v[134:135], v[46:47], v[14:15] op_sel_hi:[1,0]
	v_pk_fma_f32 v[136:137], v[46:47], v[14:15], v[134:135] op_sel:[1,1,0] op_sel_hi:[0,1,1] neg_lo:[0,1,0]
	v_fmac_f32_e32 v121, v136, v3
	v_fmac_f32_e32 v125, v137, v7
	global_load_dwordx4 v[0:3], v126, s[12:13] offset:96
	global_load_dwordx4 v[4:7], v126, s[14:15] offset:96
	global_load_dwordx4 v[8:11], v128, s[16:17] offset:192
	global_load_dwordx4 v[12:15], v128, s[16:17] offset:208
	global_load_dwordx4 v[16:19], v127, s[18:19]
	global_load_dwordx4 v[20:23], v127, s[18:19] offset:16
	global_load_dwordx4 v[24:27], v127, s[18:19] offset:128
	global_load_dwordx4 v[28:31], v127, s[18:19] offset:144
	global_load_dwordx4 v[32:35], v127, s[18:19] offset:256
	global_load_dwordx4 v[36:39], v127, s[18:19] offset:272
	global_load_dwordx4 v[40:43], v127, s[18:19] offset:384
	global_load_dwordx4 v[44:47], v127, s[18:19] offset:400
	s_add_u32 s18, s18, 0x200
	s_addc_u32 s19, s19, 0
	s_waitcnt vmcnt(12)
; __device__ __forceinline__ float2 cmul(float2 a, float2 b) { return make_float2(a.x * b.x - a.y * b.y, a.x * b.y + a.y * b.x); }
; __device__ __forceinline__ void phase1(const Params& P) {
;     ...
;             for (int p = 0; p < 64; ++p) {
; #pragma unroll
;                 for (int q = 0; q < 4; ++q) {
;                     const int e = e0 + q * gsz;
;                     const int cp = e & 15, c = (e >> 4) & 15, tau = (e >> 8) & 31, dg = e >> 13;
;                     const float2 C = make_float2(P.in[17][(dg * 16 + c) * 64 + p], P.in[18][(dg * 16 + c) * 64 + p]);
;                     const float2 z = cmul(LP[(dg * 33 + tau) * 64 + p], BB[(dg * 64 + p) * 16 + cp]);
;                     sacc[q] += C.x * z.x - C.y * z.y;
;                 }
;             }
	v_pk_mul_f32 v[130:131], v[86:87], v[78:79] op_sel_hi:[1,0]
	v_pk_fma_f32 v[132:133], v[86:87], v[78:79], v[130:131] op_sel:[1,1,0] op_sel_hi:[0,1,1] neg_lo:[0,1,0]
	v_fmac_f32_e32 v118, v132, v70
	v_fmac_f32_e32 v122, v133, v74
	v_pk_mul_f32 v[134:135], v[88:89], v[78:79] op_sel_hi:[1,0]
	v_pk_fma_f32 v[136:137], v[88:89], v[78:79], v[134:135] op_sel:[1,1,0] op_sel_hi:[0,1,1] neg_lo:[0,1,0]
	v_fmac_f32_e32 v119, v136, v70
	v_fmac_f32_e32 v123, v137, v74
	v_pk_mul_f32 v[130:131], v[90:91], v[78:79] op_sel_hi:[1,0]
	v_pk_fma_f32 v[132:133], v[90:91], v[78:79], v[130:131] op_sel:[1,1,0] op_sel_hi:[0,1,1] neg_lo:[0,1,0]
	v_fmac_f32_e32 v120, v132, v70
	v_fmac_f32_e32 v124, v133, v74
	v_pk_mul_f32 v[134:135], v[92:93], v[78:79] op_sel_hi:[1,0]
	v_pk_fma_f32 v[136:137], v[92:93], v[78:79], v[134:135] op_sel:[1,1,0] op_sel_hi:[0,1,1] neg_lo:[0,1,0]
	v_fmac_f32_e32 v121, v136, v70
	v_fmac_f32_e32 v125, v137, v74
	v_pk_mul_f32 v[130:131], v[94:95], v[80:81] op_sel_hi:[1,0]
	v_pk_fma_f32 v[132:133], v[94:95], v[80:81], v[130:131] op_sel:[1,1,0] op_sel_hi:[0,1,1] neg_lo:[0,1,0]
	v_fmac_f32_e32 v118, v132, v71
	v_fmac_f32_e32 v122, v133, v75
	v_pk_mul_f32 v[134:135], v[96:97], v[80:81] op_sel_hi:[1,0]
	v_pk_fma_f32 v[136:137], v[96:97], v[80:81], v[134:135] op_sel:[1,1,0] op_sel_hi:[0,1,1] neg_lo:[0,1,0]
	v_fmac_f32_e32 v119, v136, v71
	v_fmac_f32_e32 v123, v137, v75
	v_pk_mul_f32 v[130:131], v[98:99], v[80:81] op_sel_hi:[1,0]
	v_pk_fma_f32 v[132:133], v[98:99], v[80:81], v[130:131] op_sel:[1,1,0] op_sel_hi:[0,1,1] neg_lo:[0,1,0]
	v_fmac_f32_e32 v120, v132, v71
	v_fmac_f32_e32 v124, v133, v75
	v_pk_mul_f32 v[134:135], v[100:101], v[80:81] op_sel_hi:[1,0]
	v_pk_fma_f32 v[136:137], v[100:101], v[80:81], v[134:135] op_sel:[1,1,0] op_sel_hi:[0,1,1] neg_lo:[0,1,0]
	v_fmac_f32_e32 v121, v136, v71
	v_fmac_f32_e32 v125, v137, v75
	v_pk_mul_f32 v[130:131], v[102:103], v[82:83] op_sel_hi:[1,0]
	v_pk_fma_f32 v[132:133], v[102:103], v[82:83], v[130:131] op_sel:[1,1,0] op_sel_hi:[0,1,1] neg_lo:[0,1,0]
	v_fmac_f32_e32 v118, v132, v72
	v_fmac_f32_e32 v122, v133, v76
	v_pk_mul_f32 v[134:135], v[104:105], v[82:83] op_sel_hi:[1,0]
	v_pk_fma_f32 v[136:137], v[104:105], v[82:83], v[134:135] op_sel:[1,1,0] op_sel_hi:[0,1,1] neg_lo:[0,1,0]
	v_fmac_f32_e32 v119, v136, v72
	v_fmac_f32_e32 v123, v137, v76
	v_pk_mul_f32 v[130:131], v[106:107], v[82:83] op_sel_hi:[1,0]
	v_pk_fma_f32 v[132:133], v[106:107], v[82:83], v[130:131] op_sel:[1,1,0] op_sel_hi:[0,1,1] neg_lo:[0,1,0]
	v_fmac_f32_e32 v120, v132, v72
	v_fmac_f32_e32 v124, v133, v76
	v_pk_mul_f32 v[134:135], v[108:109], v[82:83] op_sel_hi:[1,0]
	v_pk_fma_f32 v[136:137], v[108:109], v[82:83], v[134:135] op_sel:[1,1,0] op_sel_hi:[0,1,1] neg_lo:[0,1,0]
	v_fmac_f32_e32 v121, v136, v72
	v_fmac_f32_e32 v125, v137, v76
	v_pk_mul_f32 v[130:131], v[110:111], v[84:85] op_sel_hi:[1,0]
	v_pk_fma_f32 v[132:133], v[110:111], v[84:85], v[130:131] op_sel:[1,1,0] op_sel_hi:[0,1,1] neg_lo:[0,1,0]
	v_fmac_f32_e32 v118, v132, v73
	v_fmac_f32_e32 v122, v133, v77
	v_pk_mul_f32 v[134:135], v[112:113], v[84:85] op_sel_hi:[1,0]
	v_pk_fma_f32 v[136:137], v[112:113], v[84:85], v[134:135] op_sel:[1,1,0] op_sel_hi:[0,1,1] neg_lo:[0,1,0]
	v_fmac_f32_e32 v119, v136, v73
	v_fmac_f32_e32 v123, v137, v77
	v_pk_mul_f32 v[130:131], v[114:115], v[84:85] op_sel_hi:[1,0]
	v_pk_fma_f32 v[132:133], v[114:115], v[84:85], v[130:131] op_sel:[1,1,0] op_sel_hi:[0,1,1] neg_lo:[0,1,0]
	v_fmac_f32_e32 v120, v132, v73
	v_fmac_f32_e32 v124, v133, v77
	v_pk_mul_f32 v[134:135], v[116:117], v[84:85] op_sel_hi:[1,0]
	v_pk_fma_f32 v[136:137], v[116:117], v[84:85], v[134:135] op_sel:[1,1,0] op_sel_hi:[0,1,1] neg_lo:[0,1,0]
	v_fmac_f32_e32 v121, v136, v73
	v_fmac_f32_e32 v125, v137, v77
	global_load_dwordx4 v[70:73], v126, s[12:13] offset:112
	global_load_dwordx4 v[74:77], v126, s[14:15] offset:112
	global_load_dwordx4 v[78:81], v128, s[16:17] offset:224
	global_load_dwordx4 v[82:85], v128, s[16:17] offset:240
	global_load_dwordx4 v[86:89], v127, s[18:19]
	global_load_dwordx4 v[90:93], v127, s[18:19] offset:16
	global_load_dwordx4 v[94:97], v127, s[18:19] offset:128
	global_load_dwordx4 v[98:101], v127, s[18:19] offset:144
	global_load_dwordx4 v[102:105], v127, s[18:19] offset:256
	global_load_dwordx4 v[106:109], v127, s[18:19] offset:272
	global_load_dwordx4 v[110:113], v127, s[18:19] offset:384
	global_load_dwordx4 v[114:117], v127, s[18:19] offset:400
	s_add_u32 s18, s18, 0x200
	s_addc_u32 s19, s19, 0
	s_waitcnt vmcnt(12)
; __device__ __forceinline__ float2 cmul(float2 a, float2 b) { return make_float2(a.x * b.x - a.y * b.y, a.x * b.y + a.y * b.x); }
; __device__ __forceinline__ void phase1(const Params& P) {
;     ...
;             for (int p = 0; p < 64; ++p) {
; #pragma unroll
;                 for (int q = 0; q < 4; ++q) {
;                     const int e = e0 + q * gsz;
;                     const int cp = e & 15, c = (e >> 4) & 15, tau = (e >> 8) & 31, dg = e >> 13;
;                     const float2 C = make_float2(P.in[17][(dg * 16 + c) * 64 + p], P.in[18][(dg * 16 + c) * 64 + p]);
;                     const float2 z = cmul(LP[(dg * 33 + tau) * 64 + p], BB[(dg * 64 + p) * 16 + cp]);
;                     sacc[q] += C.x * z.x - C.y * z.y;
;                 }
;             }
	v_pk_mul_f32 v[130:131], v[16:17], v[8:9] op_sel_hi:[1,0]
	v_pk_fma_f32 v[132:133], v[16:17], v[8:9], v[130:131] op_sel:[1,1,0] op_sel_hi:[0,1,1] neg_lo:[0,1,0]
	v_fmac_f32_e32 v118, v132, v0
	v_fmac_f32_e32 v122, v133, v4
	v_pk_mul_f32 v[134:135], v[18:19], v[8:9] op_sel_hi:[1,0]
	v_pk_fma_f32 v[136:137], v[18:19], v[8:9], v[134:135] op_sel:[1,1,0] op_sel_hi:[0,1,1] neg_lo:[0,1,0]
	v_fmac_f32_e32 v119, v136, v0
	v_fmac_f32_e32 v123, v137, v4
	v_pk_mul_f32 v[130:131], v[20:21], v[8:9] op_sel_hi:[1,0]
	v_pk_fma_f32 v[132:133], v[20:21], v[8:9], v[130:131] op_sel:[1,1,0] op_sel_hi:[0,1,1] neg_lo:[0,1,0]
	v_fmac_f32_e32 v120, v132, v0
	v_fmac_f32_e32 v124, v133, v4
	v_pk_mul_f32 v[134:135], v[22:23], v[8:9] op_sel_hi:[1,0]
	v_pk_fma_f32 v[136:137], v[22:23], v[8:9], v[134:135] op_sel:[1,1,0] op_sel_hi:[0,1,1] neg_lo:[0,1,0]
	v_fmac_f32_e32 v121, v136, v0
	v_fmac_f32_e32 v125, v137, v4
	v_pk_mul_f32 v[130:131], v[24:25], v[10:11] op_sel_hi:[1,0]
	v_pk_fma_f32 v[132:133], v[24:25], v[10:11], v[130:131] op_sel:[1,1,0] op_sel_hi:[0,1,1] neg_lo:[0,1,0]
	v_fmac_f32_e32 v118, v132, v1
	v_fmac_f32_e32 v122, v133, v5
	v_pk_mul_f32 v[134:135], v[26:27], v[10:11] op_sel_hi:[1,0]
	v_pk_fma_f32 v[136:137], v[26:27], v[10:11], v[134:135] op_sel:[1,1,0] op_sel_hi:[0,1,1] neg_lo:[0,1,0]
	v_fmac_f32_e32 v119, v136, v1
	v_fmac_f32_e32 v123, v137, v5
	v_pk_mul_f32 v[130:131], v[28:29], v[10:11] op_sel_hi:[1,0]
	v_pk_fma_f32 v[132:133], v[28:29], v[10:11], v[130:131] op_sel:[1,1,0] op_sel_hi:[0,1,1] neg_lo:[0,1,0]
	v_fmac_f32_e32 v120, v132, v1
	v_fmac_f32_e32 v124, v133, v5
	v_pk_mul_f32 v[134:135], v[30:31], v[10:11] op_sel_hi:[1,0]
	v_pk_fma_f32 v[136:137], v[30:31], v[10:11], v[134:135] op_sel:[1,1,0] op_sel_hi:[0,1,1] neg_lo:[0,1,0]
	v_fmac_f32_e32 v121, v136, v1
	v_fmac_f32_e32 v125, v137, v5
	v_pk_mul_f32 v[130:131], v[32:33], v[12:13] op_sel_hi:[1,0]
	v_pk_fma_f32 v[132:133], v[32:33], v[12:13], v[130:131] op_sel:[1,1,0] op_sel_hi:[0,1,1] neg_lo:[0,1,0]
	v_fmac_f32_e32 v118, v132, v2
	v_fmac_f32_e32 v122, v133, v6
	v_pk_mul_f32 v[134:135], v[34:35], v[12:13] op_sel_hi:[1,0]
	v_pk_fma_f32 v[136:137], v[34:35], v[12:13], v[134:135] op_sel:[1,1,0] op_sel_hi:[0,1,1] neg_lo:[0,1,0]
	v_fmac_f32_e32 v119, v136, v2
	v_fmac_f32_e32 v123, v137, v6
	v_pk_mul_f32 v[130:131], v[36:37], v[12:13] op_sel_hi:[1,0]
	v_pk_fma_f32 v[132:133], v[36:37], v[12:13], v[130:131] op_sel:[1,1,0] op_sel_hi:[0,1,1] neg_lo:[0,1,0]
	v_fmac_f32_e32 v120, v132, v2
	v_fmac_f32_e32 v124, v133, v6
	v_pk_mul_f32 v[134:135], v[38:39], v[12:13] op_sel_hi:[1,0]
	v_pk_fma_f32 v[136:137], v[38:39], v[12:13], v[134:135] op_sel:[1,1,0] op_sel_hi:[0,1,1] neg_lo:[0,1,0]
	v_fmac_f32_e32 v121, v136, v2
	v_fmac_f32_e32 v125, v137, v6
	v_pk_mul_f32 v[130:131], v[40:41], v[14:15] op_sel_hi:[1,0]
	v_pk_fma_f32 v[132:133], v[40:41], v[14:15], v[130:131] op_sel:[1,1,0] op_sel_hi:[0,1,1] neg_lo:[0,1,0]
	v_fmac_f32_e32 v118, v132, v3
	v_fmac_f32_e32 v122, v133, v7
	v_pk_mul_f32 v[134:135], v[42:43], v[14:15] op_sel_hi:[1,0]
	v_pk_fma_f32 v[136:137], v[42:43], v[14:15], v[134:135] op_sel:[1,1,0] op_sel_hi:[0,1,1] neg_lo:[0,1,0]
	v_fmac_f32_e32 v119, v136, v3
	v_fmac_f32_e32 v123, v137, v7
	v_pk_mul_f32 v[130:131], v[44:45], v[14:15] op_sel_hi:[1,0]
	v_pk_fma_f32 v[132:133], v[44:45], v[14:15], v[130:131] op_sel:[1,1,0] op_sel_hi:[0,1,1] neg_lo:[0,1,0]
	v_fmac_f32_e32 v120, v132, v3
	v_fmac_f32_e32 v124, v133, v7
	v_pk_mul_f32 v[134:135], v[46:47], v[14:15] op_sel_hi:[1,0]
	v_pk_fma_f32 v[136:137], v[46:47], v[14:15], v[134:135] op_sel:[1,1,0] op_sel_hi:[0,1,1] neg_lo:[0,1,0]
	v_fmac_f32_e32 v121, v136, v3
	v_fmac_f32_e32 v125, v137, v7
	global_load_dwordx4 v[0:3], v126, s[12:13] offset:128
	global_load_dwordx4 v[4:7], v126, s[14:15] offset:128
	global_load_dwordx4 v[8:11], v128, s[16:17] offset:256
	global_load_dwordx4 v[12:15], v128, s[16:17] offset:272
	global_load_dwordx4 v[16:19], v127, s[18:19]
	global_load_dwordx4 v[20:23], v127, s[18:19] offset:16
	global_load_dwordx4 v[24:27], v127, s[18:19] offset:128
	global_load_dwordx4 v[28:31], v127, s[18:19] offset:144
	global_load_dwordx4 v[32:35], v127, s[18:19] offset:256
	global_load_dwordx4 v[36:39], v127, s[18:19] offset:272
	global_load_dwordx4 v[40:43], v127, s[18:19] offset:384
	global_load_dwordx4 v[44:47], v127, s[18:19] offset:400
	s_add_u32 s18, s18, 0x200
	s_addc_u32 s19, s19, 0
	s_waitcnt vmcnt(12)
; __device__ __forceinline__ float2 cmul(float2 a, float2 b) { return make_float2(a.x * b.x - a.y * b.y, a.x * b.y + a.y * b.x); }
; __device__ __forceinline__ void phase1(const Params& P) {
;     ...
;             for (int p = 0; p < 64; ++p) {
; #pragma unroll
;                 for (int q = 0; q < 4; ++q) {
;                     const int e = e0 + q * gsz;
;                     const int cp = e & 15, c = (e >> 4) & 15, tau = (e >> 8) & 31, dg = e >> 13;
;                     const float2 C = make_float2(P.in[17][(dg * 16 + c) * 64 + p], P.in[18][(dg * 16 + c) * 64 + p]);
;                     const float2 z = cmul(LP[(dg * 33 + tau) * 64 + p], BB[(dg * 64 + p) * 16 + cp]);
;                     sacc[q] += C.x * z.x - C.y * z.y;
;                 }
;             }
	v_pk_mul_f32 v[130:131], v[86:87], v[78:79] op_sel_hi:[1,0]
	v_pk_fma_f32 v[132:133], v[86:87], v[78:79], v[130:131] op_sel:[1,1,0] op_sel_hi:[0,1,1] neg_lo:[0,1,0]
	v_fmac_f32_e32 v118, v132, v70
	v_fmac_f32_e32 v122, v133, v74
	v_pk_mul_f32 v[134:135], v[88:89], v[78:79] op_sel_hi:[1,0]
	v_pk_fma_f32 v[136:137], v[88:89], v[78:79], v[134:135] op_sel:[1,1,0] op_sel_hi:[0,1,1] neg_lo:[0,1,0]
	v_fmac_f32_e32 v119, v136, v70
	v_fmac_f32_e32 v123, v137, v74
	v_pk_mul_f32 v[130:131], v[90:91], v[78:79] op_sel_hi:[1,0]
	v_pk_fma_f32 v[132:133], v[90:91], v[78:79], v[130:131] op_sel:[1,1,0] op_sel_hi:[0,1,1] neg_lo:[0,1,0]
	v_fmac_f32_e32 v120, v132, v70
	v_fmac_f32_e32 v124, v133, v74
	v_pk_mul_f32 v[134:135], v[92:93], v[78:79] op_sel_hi:[1,0]
	v_pk_fma_f32 v[136:137], v[92:93], v[78:79], v[134:135] op_sel:[1,1,0] op_sel_hi:[0,1,1] neg_lo:[0,1,0]
	v_fmac_f32_e32 v121, v136, v70
	v_fmac_f32_e32 v125, v137, v74
	v_pk_mul_f32 v[130:131], v[94:95], v[80:81] op_sel_hi:[1,0]
	v_pk_fma_f32 v[132:133], v[94:95], v[80:81], v[130:131] op_sel:[1,1,0] op_sel_hi:[0,1,1] neg_lo:[0,1,0]
	v_fmac_f32_e32 v118, v132, v71
	v_fmac_f32_e32 v122, v133, v75
	v_pk_mul_f32 v[134:135], v[96:97], v[80:81] op_sel_hi:[1,0]
	v_pk_fma_f32 v[136:137], v[96:97], v[80:81], v[134:135] op_sel:[1,1,0] op_sel_hi:[0,1,1] neg_lo:[0,1,0]
	v_fmac_f32_e32 v119, v136, v71
	v_fmac_f32_e32 v123, v137, v75
	v_pk_mul_f32 v[130:131], v[98:99], v[80:81] op_sel_hi:[1,0]
	v_pk_fma_f32 v[132:133], v[98:99], v[80:81], v[130:131] op_sel:[1,1,0] op_sel_hi:[0,1,1] neg_lo:[0,1,0]
	v_fmac_f32_e32 v120, v132, v71
	v_fmac_f32_e32 v124, v133, v75
	v_pk_mul_f32 v[134:135], v[100:101], v[80:81] op_sel_hi:[1,0]
	v_pk_fma_f32 v[136:137], v[100:101], v[80:81], v[134:135] op_sel:[1,1,0] op_sel_hi:[0,1,1] neg_lo:[0,1,0]
	v_fmac_f32_e32 v121, v136, v71
	v_fmac_f32_e32 v125, v137, v75
	v_pk_mul_f32 v[130:131], v[102:103], v[82:83] op_sel_hi:[1,0]
	v_pk_fma_f32 v[132:133], v[102:103], v[82:83], v[130:131] op_sel:[1,1,0] op_sel_hi:[0,1,1] neg_lo:[0,1,0]
	v_fmac_f32_e32 v118, v132, v72
	v_fmac_f32_e32 v122, v133, v76
	v_pk_mul_f32 v[134:135], v[104:105], v[82:83] op_sel_hi:[1,0]
	v_pk_fma_f32 v[136:137], v[104:105], v[82:83], v[134:135] op_sel:[1,1,0] op_sel_hi:[0,1,1] neg_lo:[0,1,0]
	v_fmac_f32_e32 v119, v136, v72
	v_fmac_f32_e32 v123, v137, v76
	v_pk_mul_f32 v[130:131], v[106:107], v[82:83] op_sel_hi:[1,0]
	v_pk_fma_f32 v[132:133], v[106:107], v[82:83], v[130:131] op_sel:[1,1,0] op_sel_hi:[0,1,1] neg_lo:[0,1,0]
	v_fmac_f32_e32 v120, v132, v72
	v_fmac_f32_e32 v124, v133, v76
	v_pk_mul_f32 v[134:135], v[108:109], v[82:83] op_sel_hi:[1,0]
	v_pk_fma_f32 v[136:137], v[108:109], v[82:83], v[134:135] op_sel:[1,1,0] op_sel_hi:[0,1,1] neg_lo:[0,1,0]
	v_fmac_f32_e32 v121, v136, v72
	v_fmac_f32_e32 v125, v137, v76
	v_pk_mul_f32 v[130:131], v[110:111], v[84:85] op_sel_hi:[1,0]
	v_pk_fma_f32 v[132:133], v[110:111], v[84:85], v[130:131] op_sel:[1,1,0] op_sel_hi:[0,1,1] neg_lo:[0,1,0]
	v_fmac_f32_e32 v118, v132, v73
	v_fmac_f32_e32 v122, v133, v77
	v_pk_mul_f32 v[134:135], v[112:113], v[84:85] op_sel_hi:[1,0]
	v_pk_fma_f32 v[136:137], v[112:113], v[84:85], v[134:135] op_sel:[1,1,0] op_sel_hi:[0,1,1] neg_lo:[0,1,0]
	v_fmac_f32_e32 v119, v136, v73
	v_fmac_f32_e32 v123, v137, v77
	v_pk_mul_f32 v[130:131], v[114:115], v[84:85] op_sel_hi:[1,0]
	v_pk_fma_f32 v[132:133], v[114:115], v[84:85], v[130:131] op_sel:[1,1,0] op_sel_hi:[0,1,1] neg_lo:[0,1,0]
	v_fmac_f32_e32 v120, v132, v73
	v_fmac_f32_e32 v124, v133, v77
	v_pk_mul_f32 v[134:135], v[116:117], v[84:85] op_sel_hi:[1,0]
	v_pk_fma_f32 v[136:137], v[116:117], v[84:85], v[134:135] op_sel:[1,1,0] op_sel_hi:[0,1,1] neg_lo:[0,1,0]
	v_fmac_f32_e32 v121, v136, v73
	v_fmac_f32_e32 v125, v137, v77
	global_load_dwordx4 v[70:73], v126, s[12:13] offset:144
	global_load_dwordx4 v[74:77], v126, s[14:15] offset:144
	global_load_dwordx4 v[78:81], v128, s[16:17] offset:288
	global_load_dwordx4 v[82:85], v128, s[16:17] offset:304
	global_load_dwordx4 v[86:89], v127, s[18:19]
	global_load_dwordx4 v[90:93], v127, s[18:19] offset:16
	global_load_dwordx4 v[94:97], v127, s[18:19] offset:128
	global_load_dwordx4 v[98:101], v127, s[18:19] offset:144
	global_load_dwordx4 v[102:105], v127, s[18:19] offset:256
	global_load_dwordx4 v[106:109], v127, s[18:19] offset:272
	global_load_dwordx4 v[110:113], v127, s[18:19] offset:384
	global_load_dwordx4 v[114:117], v127, s[18:19] offset:400
	s_add_u32 s18, s18, 0x200
	s_addc_u32 s19, s19, 0
	s_waitcnt vmcnt(12)
; __device__ __forceinline__ float2 cmul(float2 a, float2 b) { return make_float2(a.x * b.x - a.y * b.y, a.x * b.y + a.y * b.x); }
; __device__ __forceinline__ void phase1(const Params& P) {
;     ...
;             for (int p = 0; p < 64; ++p) {
; #pragma unroll
;                 for (int q = 0; q < 4; ++q) {
;                     const int e = e0 + q * gsz;
;                     const int cp = e & 15, c = (e >> 4) & 15, tau = (e >> 8) & 31, dg = e >> 13;
;                     const float2 C = make_float2(P.in[17][(dg * 16 + c) * 64 + p], P.in[18][(dg * 16 + c) * 64 + p]);
;                     const float2 z = cmul(LP[(dg * 33 + tau) * 64 + p], BB[(dg * 64 + p) * 16 + cp]);
;                     sacc[q] += C.x * z.x - C.y * z.y;
;                 }
;             }
	v_pk_mul_f32 v[130:131], v[16:17], v[8:9] op_sel_hi:[1,0]
	v_pk_fma_f32 v[132:133], v[16:17], v[8:9], v[130:131] op_sel:[1,1,0] op_sel_hi:[0,1,1] neg_lo:[0,1,0]
	v_fmac_f32_e32 v118, v132, v0
	v_fmac_f32_e32 v122, v133, v4
	v_pk_mul_f32 v[134:135], v[18:19], v[8:9] op_sel_hi:[1,0]
	v_pk_fma_f32 v[136:137], v[18:19], v[8:9], v[134:135] op_sel:[1,1,0] op_sel_hi:[0,1,1] neg_lo:[0,1,0]
	v_fmac_f32_e32 v119, v136, v0
	v_fmac_f32_e32 v123, v137, v4
	v_pk_mul_f32 v[130:131], v[20:21], v[8:9] op_sel_hi:[1,0]
	v_pk_fma_f32 v[132:133], v[20:21], v[8:9], v[130:131] op_sel:[1,1,0] op_sel_hi:[0,1,1] neg_lo:[0,1,0]
	v_fmac_f32_e32 v120, v132, v0
	v_fmac_f32_e32 v124, v133, v4
	v_pk_mul_f32 v[134:135], v[22:23], v[8:9] op_sel_hi:[1,0]
	v_pk_fma_f32 v[136:137], v[22:23], v[8:9], v[134:135] op_sel:[1,1,0] op_sel_hi:[0,1,1] neg_lo:[0,1,0]
	v_fmac_f32_e32 v121, v136, v0
	v_fmac_f32_e32 v125, v137, v4
	v_pk_mul_f32 v[130:131], v[24:25], v[10:11] op_sel_hi:[1,0]
	v_pk_fma_f32 v[132:133], v[24:25], v[10:11], v[130:131] op_sel:[1,1,0] op_sel_hi:[0,1,1] neg_lo:[0,1,0]
	v_fmac_f32_e32 v118, v132, v1
	v_fmac_f32_e32 v122, v133, v5
	v_pk_mul_f32 v[134:135], v[26:27], v[10:11] op_sel_hi:[1,0]
	v_pk_fma_f32 v[136:137], v[26:27], v[10:11], v[134:135] op_sel:[1,1,0] op_sel_hi:[0,1,1] neg_lo:[0,1,0]
	v_fmac_f32_e32 v119, v136, v1
	v_fmac_f32_e32 v123, v137, v5
	v_pk_mul_f32 v[130:131], v[28:29], v[10:11] op_sel_hi:[1,0]
	v_pk_fma_f32 v[132:133], v[28:29], v[10:11], v[130:131] op_sel:[1,1,0] op_sel_hi:[0,1,1] neg_lo:[0,1,0]
	v_fmac_f32_e32 v120, v132, v1
	v_fmac_f32_e32 v124, v133, v5
	v_pk_mul_f32 v[134:135], v[30:31], v[10:11] op_sel_hi:[1,0]
	v_pk_fma_f32 v[136:137], v[30:31], v[10:11], v[134:135] op_sel:[1,1,0] op_sel_hi:[0,1,1] neg_lo:[0,1,0]
	v_fmac_f32_e32 v121, v136, v1
	v_fmac_f32_e32 v125, v137, v5
	v_pk_mul_f32 v[130:131], v[32:33], v[12:13] op_sel_hi:[1,0]
	v_pk_fma_f32 v[132:133], v[32:33], v[12:13], v[130:131] op_sel:[1,1,0] op_sel_hi:[0,1,1] neg_lo:[0,1,0]
	v_fmac_f32_e32 v118, v132, v2
	v_fmac_f32_e32 v122, v133, v6
	v_pk_mul_f32 v[134:135], v[34:35], v[12:13] op_sel_hi:[1,0]
	v_pk_fma_f32 v[136:137], v[34:35], v[12:13], v[134:135] op_sel:[1,1,0] op_sel_hi:[0,1,1] neg_lo:[0,1,0]
	v_fmac_f32_e32 v119, v136, v2
	v_fmac_f32_e32 v123, v137, v6
	v_pk_mul_f32 v[130:131], v[36:37], v[12:13] op_sel_hi:[1,0]
	v_pk_fma_f32 v[132:133], v[36:37], v[12:13], v[130:131] op_sel:[1,1,0] op_sel_hi:[0,1,1] neg_lo:[0,1,0]
	v_fmac_f32_e32 v120, v132, v2
	v_fmac_f32_e32 v124, v133, v6
	v_pk_mul_f32 v[134:135], v[38:39], v[12:13] op_sel_hi:[1,0]
	v_pk_fma_f32 v[136:137], v[38:39], v[12:13], v[134:135] op_sel:[1,1,0] op_sel_hi:[0,1,1] neg_lo:[0,1,0]
	v_fmac_f32_e32 v121, v136, v2
	v_fmac_f32_e32 v125, v137, v6
	v_pk_mul_f32 v[130:131], v[40:41], v[14:15] op_sel_hi:[1,0]
	v_pk_fma_f32 v[132:133], v[40:41], v[14:15], v[130:131] op_sel:[1,1,0] op_sel_hi:[0,1,1] neg_lo:[0,1,0]
	v_fmac_f32_e32 v118, v132, v3
	v_fmac_f32_e32 v122, v133, v7
	v_pk_mul_f32 v[134:135], v[42:43], v[14:15] op_sel_hi:[1,0]
	v_pk_fma_f32 v[136:137], v[42:43], v[14:15], v[134:135] op_sel:[1,1,0] op_sel_hi:[0,1,1] neg_lo:[0,1,0]
	v_fmac_f32_e32 v119, v136, v3
	v_fmac_f32_e32 v123, v137, v7
	v_pk_mul_f32 v[130:131], v[44:45], v[14:15] op_sel_hi:[1,0]
	v_pk_fma_f32 v[132:133], v[44:45], v[14:15], v[130:131] op_sel:[1,1,0] op_sel_hi:[0,1,1] neg_lo:[0,1,0]
	v_fmac_f32_e32 v120, v132, v3
	v_fmac_f32_e32 v124, v133, v7
	v_pk_mul_f32 v[134:135], v[46:47], v[14:15] op_sel_hi:[1,0]
	v_pk_fma_f32 v[136:137], v[46:47], v[14:15], v[134:135] op_sel:[1,1,0] op_sel_hi:[0,1,1] neg_lo:[0,1,0]
	v_fmac_f32_e32 v121, v136, v3
	v_fmac_f32_e32 v125, v137, v7
	global_load_dwordx4 v[0:3], v126, s[12:13] offset:160
	global_load_dwordx4 v[4:7], v126, s[14:15] offset:160
	global_load_dwordx4 v[8:11], v128, s[16:17] offset:320
	global_load_dwordx4 v[12:15], v128, s[16:17] offset:336
	global_load_dwordx4 v[16:19], v127, s[18:19]
	global_load_dwordx4 v[20:23], v127, s[18:19] offset:16
	global_load_dwordx4 v[24:27], v127, s[18:19] offset:128
	global_load_dwordx4 v[28:31], v127, s[18:19] offset:144
	global_load_dwordx4 v[32:35], v127, s[18:19] offset:256
	global_load_dwordx4 v[36:39], v127, s[18:19] offset:272
	global_load_dwordx4 v[40:43], v127, s[18:19] offset:384
	global_load_dwordx4 v[44:47], v127, s[18:19] offset:400
	s_add_u32 s18, s18, 0x200
	s_addc_u32 s19, s19, 0
	s_waitcnt vmcnt(12)
; __device__ __forceinline__ float2 cmul(float2 a, float2 b) { return make_float2(a.x * b.x - a.y * b.y, a.x * b.y + a.y * b.x); }
; __device__ __forceinline__ void phase1(const Params& P) {
;     ...
;             for (int p = 0; p < 64; ++p) {
; #pragma unroll
;                 for (int q = 0; q < 4; ++q) {
;                     const int e = e0 + q * gsz;
;                     const int cp = e & 15, c = (e >> 4) & 15, tau = (e >> 8) & 31, dg = e >> 13;
;                     const float2 C = make_float2(P.in[17][(dg * 16 + c) * 64 + p], P.in[18][(dg * 16 + c) * 64 + p]);
;                     const float2 z = cmul(LP[(dg * 33 + tau) * 64 + p], BB[(dg * 64 + p) * 16 + cp]);
;                     sacc[q] += C.x * z.x - C.y * z.y;
;                 }
;             }
	v_pk_mul_f32 v[130:131], v[86:87], v[78:79] op_sel_hi:[1,0]
	v_pk_fma_f32 v[132:133], v[86:87], v[78:79], v[130:131] op_sel:[1,1,0] op_sel_hi:[0,1,1] neg_lo:[0,1,0]
	v_fmac_f32_e32 v118, v132, v70
	v_fmac_f32_e32 v122, v133, v74
	v_pk_mul_f32 v[134:135], v[88:89], v[78:79] op_sel_hi:[1,0]
	v_pk_fma_f32 v[136:137], v[88:89], v[78:79], v[134:135] op_sel:[1,1,0] op_sel_hi:[0,1,1] neg_lo:[0,1,0]
	v_fmac_f32_e32 v119, v136, v70
	v_fmac_f32_e32 v123, v137, v74
	v_pk_mul_f32 v[130:131], v[90:91], v[78:79] op_sel_hi:[1,0]
	v_pk_fma_f32 v[132:133], v[90:91], v[78:79], v[130:131] op_sel:[1,1,0] op_sel_hi:[0,1,1] neg_lo:[0,1,0]
	v_fmac_f32_e32 v120, v132, v70
	v_fmac_f32_e32 v124, v133, v74
	v_pk_mul_f32 v[134:135], v[92:93], v[78:79] op_sel_hi:[1,0]
	v_pk_fma_f32 v[136:137], v[92:93], v[78:79], v[134:135] op_sel:[1,1,0] op_sel_hi:[0,1,1] neg_lo:[0,1,0]
	v_fmac_f32_e32 v121, v136, v70
	v_fmac_f32_e32 v125, v137, v74
	v_pk_mul_f32 v[130:131], v[94:95], v[80:81] op_sel_hi:[1,0]
	v_pk_fma_f32 v[132:133], v[94:95], v[80:81], v[130:131] op_sel:[1,1,0] op_sel_hi:[0,1,1] neg_lo:[0,1,0]
	v_fmac_f32_e32 v118, v132, v71
	v_fmac_f32_e32 v122, v133, v75
	v_pk_mul_f32 v[134:135], v[96:97], v[80:81] op_sel_hi:[1,0]
	v_pk_fma_f32 v[136:137], v[96:97], v[80:81], v[134:135] op_sel:[1,1,0] op_sel_hi:[0,1,1] neg_lo:[0,1,0]
	v_fmac_f32_e32 v119, v136, v71
	v_fmac_f32_e32 v123, v137, v75
	v_pk_mul_f32 v[130:131], v[98:99], v[80:81] op_sel_hi:[1,0]
	v_pk_fma_f32 v[132:133], v[98:99], v[80:81], v[130:131] op_sel:[1,1,0] op_sel_hi:[0,1,1] neg_lo:[0,1,0]
	v_fmac_f32_e32 v120, v132, v71
	v_fmac_f32_e32 v124, v133, v75
	v_pk_mul_f32 v[134:135], v[100:101], v[80:81] op_sel_hi:[1,0]
	v_pk_fma_f32 v[136:137], v[100:101], v[80:81], v[134:135] op_sel:[1,1,0] op_sel_hi:[0,1,1] neg_lo:[0,1,0]
	v_fmac_f32_e32 v121, v136, v71
	v_fmac_f32_e32 v125, v137, v75
	v_pk_mul_f32 v[130:131], v[102:103], v[82:83] op_sel_hi:[1,0]
	v_pk_fma_f32 v[132:133], v[102:103], v[82:83], v[130:131] op_sel:[1,1,0] op_sel_hi:[0,1,1] neg_lo:[0,1,0]
	v_fmac_f32_e32 v118, v132, v72
	v_fmac_f32_e32 v122, v133, v76
	v_pk_mul_f32 v[134:135], v[104:105], v[82:83] op_sel_hi:[1,0]
	v_pk_fma_f32 v[136:137], v[104:105], v[82:83], v[134:135] op_sel:[1,1,0] op_sel_hi:[0,1,1] neg_lo:[0,1,0]
	v_fmac_f32_e32 v119, v136, v72
	v_fmac_f32_e32 v123, v137, v76
	v_pk_mul_f32 v[130:131], v[106:107], v[82:83] op_sel_hi:[1,0]
	v_pk_fma_f32 v[132:133], v[106:107], v[82:83], v[130:131] op_sel:[1,1,0] op_sel_hi:[0,1,1] neg_lo:[0,1,0]
	v_fmac_f32_e32 v120, v132, v72
	v_fmac_f32_e32 v124, v133, v76
	v_pk_mul_f32 v[134:135], v[108:109], v[82:83] op_sel_hi:[1,0]
	v_pk_fma_f32 v[136:137], v[108:109], v[82:83], v[134:135] op_sel:[1,1,0] op_sel_hi:[0,1,1] neg_lo:[0,1,0]
	v_fmac_f32_e32 v121, v136, v72
	v_fmac_f32_e32 v125, v137, v76
	v_pk_mul_f32 v[130:131], v[110:111], v[84:85] op_sel_hi:[1,0]
	v_pk_fma_f32 v[132:133], v[110:111], v[84:85], v[130:131] op_sel:[1,1,0] op_sel_hi:[0,1,1] neg_lo:[0,1,0]
	v_fmac_f32_e32 v118, v132, v73
	v_fmac_f32_e32 v122, v133, v77
	v_pk_mul_f32 v[134:135], v[112:113], v[84:85] op_sel_hi:[1,0]
	v_pk_fma_f32 v[136:137], v[112:113], v[84:85], v[134:135] op_sel:[1,1,0] op_sel_hi:[0,1,1] neg_lo:[0,1,0]
	v_fmac_f32_e32 v119, v136, v73
	v_fmac_f32_e32 v123, v137, v77
	v_pk_mul_f32 v[130:131], v[114:115], v[84:85] op_sel_hi:[1,0]
	v_pk_fma_f32 v[132:133], v[114:115], v[84:85], v[130:131] op_sel:[1,1,0] op_sel_hi:[0,1,1] neg_lo:[0,1,0]
	v_fmac_f32_e32 v120, v132, v73
	v_fmac_f32_e32 v124, v133, v77
	v_pk_mul_f32 v[134:135], v[116:117], v[84:85] op_sel_hi:[1,0]
	v_pk_fma_f32 v[136:137], v[116:117], v[84:85], v[134:135] op_sel:[1,1,0] op_sel_hi:[0,1,1] neg_lo:[0,1,0]
	v_fmac_f32_e32 v121, v136, v73
	v_fmac_f32_e32 v125, v137, v77
	global_load_dwordx4 v[70:73], v126, s[12:13] offset:176
	global_load_dwordx4 v[74:77], v126, s[14:15] offset:176
	global_load_dwordx4 v[78:81], v128, s[16:17] offset:352
	global_load_dwordx4 v[82:85], v128, s[16:17] offset:368
	global_load_dwordx4 v[86:89], v127, s[18:19]
	global_load_dwordx4 v[90:93], v127, s[18:19] offset:16
	global_load_dwordx4 v[94:97], v127, s[18:19] offset:128
	global_load_dwordx4 v[98:101], v127, s[18:19] offset:144
	global_load_dwordx4 v[102:105], v127, s[18:19] offset:256
	global_load_dwordx4 v[106:109], v127, s[18:19] offset:272
	global_load_dwordx4 v[110:113], v127, s[18:19] offset:384
	global_load_dwordx4 v[114:117], v127, s[18:19] offset:400
	s_add_u32 s18, s18, 0x200
	s_addc_u32 s19, s19, 0
	s_waitcnt vmcnt(12)
; __device__ __forceinline__ float2 cmul(float2 a, float2 b) { return make_float2(a.x * b.x - a.y * b.y, a.x * b.y + a.y * b.x); }
; __device__ __forceinline__ void phase1(const Params& P) {
;     ...
;             for (int p = 0; p < 64; ++p) {
; #pragma unroll
;                 for (int q = 0; q < 4; ++q) {
;                     const int e = e0 + q * gsz;
;                     const int cp = e & 15, c = (e >> 4) & 15, tau = (e >> 8) & 31, dg = e >> 13;
;                     const float2 C = make_float2(P.in[17][(dg * 16 + c) * 64 + p], P.in[18][(dg * 16 + c) * 64 + p]);
;                     const float2 z = cmul(LP[(dg * 33 + tau) * 64 + p], BB[(dg * 64 + p) * 16 + cp]);
;                     sacc[q] += C.x * z.x - C.y * z.y;
;                 }
;             }
	v_pk_mul_f32 v[130:131], v[16:17], v[8:9] op_sel_hi:[1,0]
	v_pk_fma_f32 v[132:133], v[16:17], v[8:9], v[130:131] op_sel:[1,1,0] op_sel_hi:[0,1,1] neg_lo:[0,1,0]
	v_fmac_f32_e32 v118, v132, v0
	v_fmac_f32_e32 v122, v133, v4
	v_pk_mul_f32 v[134:135], v[18:19], v[8:9] op_sel_hi:[1,0]
	v_pk_fma_f32 v[136:137], v[18:19], v[8:9], v[134:135] op_sel:[1,1,0] op_sel_hi:[0,1,1] neg_lo:[0,1,0]
	v_fmac_f32_e32 v119, v136, v0
	v_fmac_f32_e32 v123, v137, v4
	v_pk_mul_f32 v[130:131], v[20:21], v[8:9] op_sel_hi:[1,0]
	v_pk_fma_f32 v[132:133], v[20:21], v[8:9], v[130:131] op_sel:[1,1,0] op_sel_hi:[0,1,1] neg_lo:[0,1,0]
	v_fmac_f32_e32 v120, v132, v0
	v_fmac_f32_e32 v124, v133, v4
	v_pk_mul_f32 v[134:135], v[22:23], v[8:9] op_sel_hi:[1,0]
	v_pk_fma_f32 v[136:137], v[22:23], v[8:9], v[134:135] op_sel:[1,1,0] op_sel_hi:[0,1,1] neg_lo:[0,1,0]
	v_fmac_f32_e32 v121, v136, v0
	v_fmac_f32_e32 v125, v137, v4
	v_pk_mul_f32 v[130:131], v[24:25], v[10:11] op_sel_hi:[1,0]
	v_pk_fma_f32 v[132:133], v[24:25], v[10:11], v[130:131] op_sel:[1,1,0] op_sel_hi:[0,1,1] neg_lo:[0,1,0]
	v_fmac_f32_e32 v118, v132, v1
	v_fmac_f32_e32 v122, v133, v5
	v_pk_mul_f32 v[134:135], v[26:27], v[10:11] op_sel_hi:[1,0]
	v_pk_fma_f32 v[136:137], v[26:27], v[10:11], v[134:135] op_sel:[1,1,0] op_sel_hi:[0,1,1] neg_lo:[0,1,0]
	v_fmac_f32_e32 v119, v136, v1
	v_fmac_f32_e32 v123, v137, v5
	v_pk_mul_f32 v[130:131], v[28:29], v[10:11] op_sel_hi:[1,0]
	v_pk_fma_f32 v[132:133], v[28:29], v[10:11], v[130:131] op_sel:[1,1,0] op_sel_hi:[0,1,1] neg_lo:[0,1,0]
	v_fmac_f32_e32 v120, v132, v1
	v_fmac_f32_e32 v124, v133, v5
	v_pk_mul_f32 v[134:135], v[30:31], v[10:11] op_sel_hi:[1,0]
	v_pk_fma_f32 v[136:137], v[30:31], v[10:11], v[134:135] op_sel:[1,1,0] op_sel_hi:[0,1,1] neg_lo:[0,1,0]
	v_fmac_f32_e32 v121, v136, v1
	v_fmac_f32_e32 v125, v137, v5
	v_pk_mul_f32 v[130:131], v[32:33], v[12:13] op_sel_hi:[1,0]
	v_pk_fma_f32 v[132:133], v[32:33], v[12:13], v[130:131] op_sel:[1,1,0] op_sel_hi:[0,1,1] neg_lo:[0,1,0]
	v_fmac_f32_e32 v118, v132, v2
	v_fmac_f32_e32 v122, v133, v6
	v_pk_mul_f32 v[134:135], v[34:35], v[12:13] op_sel_hi:[1,0]
	v_pk_fma_f32 v[136:137], v[34:35], v[12:13], v[134:135] op_sel:[1,1,0] op_sel_hi:[0,1,1] neg_lo:[0,1,0]
	v_fmac_f32_e32 v119, v136, v2
	v_fmac_f32_e32 v123, v137, v6
	v_pk_mul_f32 v[130:131], v[36:37], v[12:13] op_sel_hi:[1,0]
	v_pk_fma_f32 v[132:133], v[36:37], v[12:13], v[130:131] op_sel:[1,1,0] op_sel_hi:[0,1,1] neg_lo:[0,1,0]
	v_fmac_f32_e32 v120, v132, v2
	v_fmac_f32_e32 v124, v133, v6
	v_pk_mul_f32 v[134:135], v[38:39], v[12:13] op_sel_hi:[1,0]
	v_pk_fma_f32 v[136:137], v[38:39], v[12:13], v[134:135] op_sel:[1,1,0] op_sel_hi:[0,1,1] neg_lo:[0,1,0]
	v_fmac_f32_e32 v121, v136, v2
	v_fmac_f32_e32 v125, v137, v6
	v_pk_mul_f32 v[130:131], v[40:41], v[14:15] op_sel_hi:[1,0]
	v_pk_fma_f32 v[132:133], v[40:41], v[14:15], v[130:131] op_sel:[1,1,0] op_sel_hi:[0,1,1] neg_lo:[0,1,0]
	v_fmac_f32_e32 v118, v132, v3
	v_fmac_f32_e32 v122, v133, v7
	v_pk_mul_f32 v[134:135], v[42:43], v[14:15] op_sel_hi:[1,0]
	v_pk_fma_f32 v[136:137], v[42:43], v[14:15], v[134:135] op_sel:[1,1,0] op_sel_hi:[0,1,1] neg_lo:[0,1,0]
	v_fmac_f32_e32 v119, v136, v3
	v_fmac_f32_e32 v123, v137, v7
	v_pk_mul_f32 v[130:131], v[44:45], v[14:15] op_sel_hi:[1,0]
	v_pk_fma_f32 v[132:133], v[44:45], v[14:15], v[130:131] op_sel:[1,1,0] op_sel_hi:[0,1,1] neg_lo:[0,1,0]
	v_fmac_f32_e32 v120, v132, v3
	v_fmac_f32_e32 v124, v133, v7
	v_pk_mul_f32 v[134:135], v[46:47], v[14:15] op_sel_hi:[1,0]
	v_pk_fma_f32 v[136:137], v[46:47], v[14:15], v[134:135] op_sel:[1,1,0] op_sel_hi:[0,1,1] neg_lo:[0,1,0]
	v_fmac_f32_e32 v121, v136, v3
	v_fmac_f32_e32 v125, v137, v7
	global_load_dwordx4 v[0:3], v126, s[12:13] offset:192
	global_load_dwordx4 v[4:7], v126, s[14:15] offset:192
	global_load_dwordx4 v[8:11], v128, s[16:17] offset:384
	global_load_dwordx4 v[12:15], v128, s[16:17] offset:400
	global_load_dwordx4 v[16:19], v127, s[18:19]
	global_load_dwordx4 v[20:23], v127, s[18:19] offset:16
	global_load_dwordx4 v[24:27], v127, s[18:19] offset:128
	global_load_dwordx4 v[28:31], v127, s[18:19] offset:144
	global_load_dwordx4 v[32:35], v127, s[18:19] offset:256
	global_load_dwordx4 v[36:39], v127, s[18:19] offset:272
	global_load_dwordx4 v[40:43], v127, s[18:19] offset:384
	global_load_dwordx4 v[44:47], v127, s[18:19] offset:400
	s_add_u32 s18, s18, 0x200
	s_addc_u32 s19, s19, 0
	s_waitcnt vmcnt(12)
; __device__ __forceinline__ float2 cmul(float2 a, float2 b) { return make_float2(a.x * b.x - a.y * b.y, a.x * b.y + a.y * b.x); }
; __device__ __forceinline__ void phase1(const Params& P) {
;     ...
;             for (int p = 0; p < 64; ++p) {
; #pragma unroll
;                 for (int q = 0; q < 4; ++q) {
;                     const int e = e0 + q * gsz;
;                     const int cp = e & 15, c = (e >> 4) & 15, tau = (e >> 8) & 31, dg = e >> 13;
;                     const float2 C = make_float2(P.in[17][(dg * 16 + c) * 64 + p], P.in[18][(dg * 16 + c) * 64 + p]);
;                     const float2 z = cmul(LP[(dg * 33 + tau) * 64 + p], BB[(dg * 64 + p) * 16 + cp]);
;                     sacc[q] += C.x * z.x - C.y * z.y;
;                 }
;             }
	v_pk_mul_f32 v[130:131], v[86:87], v[78:79] op_sel_hi:[1,0]
	v_pk_fma_f32 v[132:133], v[86:87], v[78:79], v[130:131] op_sel:[1,1,0] op_sel_hi:[0,1,1] neg_lo:[0,1,0]
	v_fmac_f32_e32 v118, v132, v70
	v_fmac_f32_e32 v122, v133, v74
	v_pk_mul_f32 v[134:135], v[88:89], v[78:79] op_sel_hi:[1,0]
	v_pk_fma_f32 v[136:137], v[88:89], v[78:79], v[134:135] op_sel:[1,1,0] op_sel_hi:[0,1,1] neg_lo:[0,1,0]
	v_fmac_f32_e32 v119, v136, v70
	v_fmac_f32_e32 v123, v137, v74
	v_pk_mul_f32 v[130:131], v[90:91], v[78:79] op_sel_hi:[1,0]
	v_pk_fma_f32 v[132:133], v[90:91], v[78:79], v[130:131] op_sel:[1,1,0] op_sel_hi:[0,1,1] neg_lo:[0,1,0]
	v_fmac_f32_e32 v120, v132, v70
	v_fmac_f32_e32 v124, v133, v74
	v_pk_mul_f32 v[134:135], v[92:93], v[78:79] op_sel_hi:[1,0]
	v_pk_fma_f32 v[136:137], v[92:93], v[78:79], v[134:135] op_sel:[1,1,0] op_sel_hi:[0,1,1] neg_lo:[0,1,0]
	v_fmac_f32_e32 v121, v136, v70
	v_fmac_f32_e32 v125, v137, v74
	v_pk_mul_f32 v[130:131], v[94:95], v[80:81] op_sel_hi:[1,0]
	v_pk_fma_f32 v[132:133], v[94:95], v[80:81], v[130:131] op_sel:[1,1,0] op_sel_hi:[0,1,1] neg_lo:[0,1,0]
	v_fmac_f32_e32 v118, v132, v71
	v_fmac_f32_e32 v122, v133, v75
	v_pk_mul_f32 v[134:135], v[96:97], v[80:81] op_sel_hi:[1,0]
	v_pk_fma_f32 v[136:137], v[96:97], v[80:81], v[134:135] op_sel:[1,1,0] op_sel_hi:[0,1,1] neg_lo:[0,1,0]
	v_fmac_f32_e32 v119, v136, v71
	v_fmac_f32_e32 v123, v137, v75
	v_pk_mul_f32 v[130:131], v[98:99], v[80:81] op_sel_hi:[1,0]
	v_pk_fma_f32 v[132:133], v[98:99], v[80:81], v[130:131] op_sel:[1,1,0] op_sel_hi:[0,1,1] neg_lo:[0,1,0]
	v_fmac_f32_e32 v120, v132, v71
	v_fmac_f32_e32 v124, v133, v75
	v_pk_mul_f32 v[134:135], v[100:101], v[80:81] op_sel_hi:[1,0]
	v_pk_fma_f32 v[136:137], v[100:101], v[80:81], v[134:135] op_sel:[1,1,0] op_sel_hi:[0,1,1] neg_lo:[0,1,0]
	v_fmac_f32_e32 v121, v136, v71
	v_fmac_f32_e32 v125, v137, v75
	v_pk_mul_f32 v[130:131], v[102:103], v[82:83] op_sel_hi:[1,0]
	v_pk_fma_f32 v[132:133], v[102:103], v[82:83], v[130:131] op_sel:[1,1,0] op_sel_hi:[0,1,1] neg_lo:[0,1,0]
	v_fmac_f32_e32 v118, v132, v72
	v_fmac_f32_e32 v122, v133, v76
	v_pk_mul_f32 v[134:135], v[104:105], v[82:83] op_sel_hi:[1,0]
	v_pk_fma_f32 v[136:137], v[104:105], v[82:83], v[134:135] op_sel:[1,1,0] op_sel_hi:[0,1,1] neg_lo:[0,1,0]
	v_fmac_f32_e32 v119, v136, v72
	v_fmac_f32_e32 v123, v137, v76
	v_pk_mul_f32 v[130:131], v[106:107], v[82:83] op_sel_hi:[1,0]
	v_pk_fma_f32 v[132:133], v[106:107], v[82:83], v[130:131] op_sel:[1,1,0] op_sel_hi:[0,1,1] neg_lo:[0,1,0]
	v_fmac_f32_e32 v120, v132, v72
	v_fmac_f32_e32 v124, v133, v76
	v_pk_mul_f32 v[134:135], v[108:109], v[82:83] op_sel_hi:[1,0]
	v_pk_fma_f32 v[136:137], v[108:109], v[82:83], v[134:135] op_sel:[1,1,0] op_sel_hi:[0,1,1] neg_lo:[0,1,0]
	v_fmac_f32_e32 v121, v136, v72
	v_fmac_f32_e32 v125, v137, v76
	v_pk_mul_f32 v[130:131], v[110:111], v[84:85] op_sel_hi:[1,0]
	v_pk_fma_f32 v[132:133], v[110:111], v[84:85], v[130:131] op_sel:[1,1,0] op_sel_hi:[0,1,1] neg_lo:[0,1,0]
	v_fmac_f32_e32 v118, v132, v73
	v_fmac_f32_e32 v122, v133, v77
	v_pk_mul_f32 v[134:135], v[112:113], v[84:85] op_sel_hi:[1,0]
	v_pk_fma_f32 v[136:137], v[112:113], v[84:85], v[134:135] op_sel:[1,1,0] op_sel_hi:[0,1,1] neg_lo:[0,1,0]
	v_fmac_f32_e32 v119, v136, v73
	v_fmac_f32_e32 v123, v137, v77
	v_pk_mul_f32 v[130:131], v[114:115], v[84:85] op_sel_hi:[1,0]
	v_pk_fma_f32 v[132:133], v[114:115], v[84:85], v[130:131] op_sel:[1,1,0] op_sel_hi:[0,1,1] neg_lo:[0,1,0]
	v_fmac_f32_e32 v120, v132, v73
	v_fmac_f32_e32 v124, v133, v77
	v_pk_mul_f32 v[134:135], v[116:117], v[84:85] op_sel_hi:[1,0]
	v_pk_fma_f32 v[136:137], v[116:117], v[84:85], v[134:135] op_sel:[1,1,0] op_sel_hi:[0,1,1] neg_lo:[0,1,0]
	v_fmac_f32_e32 v121, v136, v73
	v_fmac_f32_e32 v125, v137, v77
	global_load_dwordx4 v[70:73], v126, s[12:13] offset:208
	global_load_dwordx4 v[74:77], v126, s[14:15] offset:208
	global_load_dwordx4 v[78:81], v128, s[16:17] offset:416
	global_load_dwordx4 v[82:85], v128, s[16:17] offset:432
	global_load_dwordx4 v[86:89], v127, s[18:19]
	global_load_dwordx4 v[90:93], v127, s[18:19] offset:16
	global_load_dwordx4 v[94:97], v127, s[18:19] offset:128
	global_load_dwordx4 v[98:101], v127, s[18:19] offset:144
	global_load_dwordx4 v[102:105], v127, s[18:19] offset:256
	global_load_dwordx4 v[106:109], v127, s[18:19] offset:272
	global_load_dwordx4 v[110:113], v127, s[18:19] offset:384
	global_load_dwordx4 v[114:117], v127, s[18:19] offset:400
	s_add_u32 s18, s18, 0x200
	s_addc_u32 s19, s19, 0
	s_waitcnt vmcnt(12)
; __device__ __forceinline__ float2 cmul(float2 a, float2 b) { return make_float2(a.x * b.x - a.y * b.y, a.x * b.y + a.y * b.x); }
; __device__ __forceinline__ void phase1(const Params& P) {
;     ...
;             for (int p = 0; p < 64; ++p) {
; #pragma unroll
;                 for (int q = 0; q < 4; ++q) {
;                     const int e = e0 + q * gsz;
;                     const int cp = e & 15, c = (e >> 4) & 15, tau = (e >> 8) & 31, dg = e >> 13;
;                     const float2 C = make_float2(P.in[17][(dg * 16 + c) * 64 + p], P.in[18][(dg * 16 + c) * 64 + p]);
;                     const float2 z = cmul(LP[(dg * 33 + tau) * 64 + p], BB[(dg * 64 + p) * 16 + cp]);
;                     sacc[q] += C.x * z.x - C.y * z.y;
;                 }
;             }
	v_pk_mul_f32 v[130:131], v[16:17], v[8:9] op_sel_hi:[1,0]
	v_pk_fma_f32 v[132:133], v[16:17], v[8:9], v[130:131] op_sel:[1,1,0] op_sel_hi:[0,1,1] neg_lo:[0,1,0]
	v_fmac_f32_e32 v118, v132, v0
	v_fmac_f32_e32 v122, v133, v4
	v_pk_mul_f32 v[134:135], v[18:19], v[8:9] op_sel_hi:[1,0]
	v_pk_fma_f32 v[136:137], v[18:19], v[8:9], v[134:135] op_sel:[1,1,0] op_sel_hi:[0,1,1] neg_lo:[0,1,0]
	v_fmac_f32_e32 v119, v136, v0
	v_fmac_f32_e32 v123, v137, v4
	v_pk_mul_f32 v[130:131], v[20:21], v[8:9] op_sel_hi:[1,0]
	v_pk_fma_f32 v[132:133], v[20:21], v[8:9], v[130:131] op_sel:[1,1,0] op_sel_hi:[0,1,1] neg_lo:[0,1,0]
	v_fmac_f32_e32 v120, v132, v0
	v_fmac_f32_e32 v124, v133, v4
	v_pk_mul_f32 v[134:135], v[22:23], v[8:9] op_sel_hi:[1,0]
	v_pk_fma_f32 v[136:137], v[22:23], v[8:9], v[134:135] op_sel:[1,1,0] op_sel_hi:[0,1,1] neg_lo:[0,1,0]
	v_fmac_f32_e32 v121, v136, v0
	v_fmac_f32_e32 v125, v137, v4
	v_pk_mul_f32 v[130:131], v[24:25], v[10:11] op_sel_hi:[1,0]
	v_pk_fma_f32 v[132:133], v[24:25], v[10:11], v[130:131] op_sel:[1,1,0] op_sel_hi:[0,1,1] neg_lo:[0,1,0]
	v_fmac_f32_e32 v118, v132, v1
	v_fmac_f32_e32 v122, v133, v5
	v_pk_mul_f32 v[134:135], v[26:27], v[10:11] op_sel_hi:[1,0]
	v_pk_fma_f32 v[136:137], v[26:27], v[10:11], v[134:135] op_sel:[1,1,0] op_sel_hi:[0,1,1] neg_lo:[0,1,0]
	v_fmac_f32_e32 v119, v136, v1
	v_fmac_f32_e32 v123, v137, v5
	v_pk_mul_f32 v[130:131], v[28:29], v[10:11] op_sel_hi:[1,0]
	v_pk_fma_f32 v[132:133], v[28:29], v[10:11], v[130:131] op_sel:[1,1,0] op_sel_hi:[0,1,1] neg_lo:[0,1,0]
	v_fmac_f32_e32 v120, v132, v1
	v_fmac_f32_e32 v124, v133, v5
	v_pk_mul_f32 v[134:135], v[30:31], v[10:11] op_sel_hi:[1,0]
	v_pk_fma_f32 v[136:137], v[30:31], v[10:11], v[134:135] op_sel:[1,1,0] op_sel_hi:[0,1,1] neg_lo:[0,1,0]
	v_fmac_f32_e32 v121, v136, v1
	v_fmac_f32_e32 v125, v137, v5
	v_pk_mul_f32 v[130:131], v[32:33], v[12:13] op_sel_hi:[1,0]
	v_pk_fma_f32 v[132:133], v[32:33], v[12:13], v[130:131] op_sel:[1,1,0] op_sel_hi:[0,1,1] neg_lo:[0,1,0]
	v_fmac_f32_e32 v118, v132, v2
	v_fmac_f32_e32 v122, v133, v6
	v_pk_mul_f32 v[134:135], v[34:35], v[12:13] op_sel_hi:[1,0]
	v_pk_fma_f32 v[136:137], v[34:35], v[12:13], v[134:135] op_sel:[1,1,0] op_sel_hi:[0,1,1] neg_lo:[0,1,0]
	v_fmac_f32_e32 v119, v136, v2
	v_fmac_f32_e32 v123, v137, v6
	v_pk_mul_f32 v[130:131], v[36:37], v[12:13] op_sel_hi:[1,0]
	v_pk_fma_f32 v[132:133], v[36:37], v[12:13], v[130:131] op_sel:[1,1,0] op_sel_hi:[0,1,1] neg_lo:[0,1,0]
	v_fmac_f32_e32 v120, v132, v2
	v_fmac_f32_e32 v124, v133, v6
	v_pk_mul_f32 v[134:135], v[38:39], v[12:13] op_sel_hi:[1,0]
	v_pk_fma_f32 v[136:137], v[38:39], v[12:13], v[134:135] op_sel:[1,1,0] op_sel_hi:[0,1,1] neg_lo:[0,1,0]
	v_fmac_f32_e32 v121, v136, v2
	v_fmac_f32_e32 v125, v137, v6
	v_pk_mul_f32 v[130:131], v[40:41], v[14:15] op_sel_hi:[1,0]
	v_pk_fma_f32 v[132:133], v[40:41], v[14:15], v[130:131] op_sel:[1,1,0] op_sel_hi:[0,1,1] neg_lo:[0,1,0]
	v_fmac_f32_e32 v118, v132, v3
	v_fmac_f32_e32 v122, v133, v7
	v_pk_mul_f32 v[134:135], v[42:43], v[14:15] op_sel_hi:[1,0]
	v_pk_fma_f32 v[136:137], v[42:43], v[14:15], v[134:135] op_sel:[1,1,0] op_sel_hi:[0,1,1] neg_lo:[0,1,0]
	v_fmac_f32_e32 v119, v136, v3
	v_fmac_f32_e32 v123, v137, v7
	v_pk_mul_f32 v[130:131], v[44:45], v[14:15] op_sel_hi:[1,0]
	v_pk_fma_f32 v[132:133], v[44:45], v[14:15], v[130:131] op_sel:[1,1,0] op_sel_hi:[0,1,1] neg_lo:[0,1,0]
	v_fmac_f32_e32 v120, v132, v3
	v_fmac_f32_e32 v124, v133, v7
	v_pk_mul_f32 v[134:135], v[46:47], v[14:15] op_sel_hi:[1,0]
	v_pk_fma_f32 v[136:137], v[46:47], v[14:15], v[134:135] op_sel:[1,1,0] op_sel_hi:[0,1,1] neg_lo:[0,1,0]
	v_fmac_f32_e32 v121, v136, v3
	v_fmac_f32_e32 v125, v137, v7
	global_load_dwordx4 v[0:3], v126, s[12:13] offset:224
	global_load_dwordx4 v[4:7], v126, s[14:15] offset:224
	global_load_dwordx4 v[8:11], v128, s[16:17] offset:448
	global_load_dwordx4 v[12:15], v128, s[16:17] offset:464
	global_load_dwordx4 v[16:19], v127, s[18:19]
	global_load_dwordx4 v[20:23], v127, s[18:19] offset:16
	global_load_dwordx4 v[24:27], v127, s[18:19] offset:128
	global_load_dwordx4 v[28:31], v127, s[18:19] offset:144
	global_load_dwordx4 v[32:35], v127, s[18:19] offset:256
	global_load_dwordx4 v[36:39], v127, s[18:19] offset:272
	global_load_dwordx4 v[40:43], v127, s[18:19] offset:384
	global_load_dwordx4 v[44:47], v127, s[18:19] offset:400
	s_add_u32 s18, s18, 0x200
	s_addc_u32 s19, s19, 0
	s_waitcnt vmcnt(12)
; __device__ __forceinline__ float2 cmul(float2 a, float2 b) { return make_float2(a.x * b.x - a.y * b.y, a.x * b.y + a.y * b.x); }
; __device__ __forceinline__ void phase1(const Params& P) {
;     ...
;             for (int p = 0; p < 64; ++p) {
; #pragma unroll
;                 for (int q = 0; q < 4; ++q) {
;                     const int e = e0 + q * gsz;
;                     const int cp = e & 15, c = (e >> 4) & 15, tau = (e >> 8) & 31, dg = e >> 13;
;                     const float2 C = make_float2(P.in[17][(dg * 16 + c) * 64 + p], P.in[18][(dg * 16 + c) * 64 + p]);
;                     const float2 z = cmul(LP[(dg * 33 + tau) * 64 + p], BB[(dg * 64 + p) * 16 + cp]);
;                     sacc[q] += C.x * z.x - C.y * z.y;
;                 }
;             }
	v_pk_mul_f32 v[130:131], v[86:87], v[78:79] op_sel_hi:[1,0]
	v_pk_fma_f32 v[132:133], v[86:87], v[78:79], v[130:131] op_sel:[1,1,0] op_sel_hi:[0,1,1] neg_lo:[0,1,0]
	v_fmac_f32_e32 v118, v132, v70
	v_fmac_f32_e32 v122, v133, v74
	v_pk_mul_f32 v[134:135], v[88:89], v[78:79] op_sel_hi:[1,0]
	v_pk_fma_f32 v[136:137], v[88:89], v[78:79], v[134:135] op_sel:[1,1,0] op_sel_hi:[0,1,1] neg_lo:[0,1,0]
	v_fmac_f32_e32 v119, v136, v70
	v_fmac_f32_e32 v123, v137, v74
	v_pk_mul_f32 v[130:131], v[90:91], v[78:79] op_sel_hi:[1,0]
	v_pk_fma_f32 v[132:133], v[90:91], v[78:79], v[130:131] op_sel:[1,1,0] op_sel_hi:[0,1,1] neg_lo:[0,1,0]
	v_fmac_f32_e32 v120, v132, v70
	v_fmac_f32_e32 v124, v133, v74
	v_pk_mul_f32 v[134:135], v[92:93], v[78:79] op_sel_hi:[1,0]
	v_pk_fma_f32 v[136:137], v[92:93], v[78:79], v[134:135] op_sel:[1,1,0] op_sel_hi:[0,1,1] neg_lo:[0,1,0]
	v_fmac_f32_e32 v121, v136, v70
	v_fmac_f32_e32 v125, v137, v74
	v_pk_mul_f32 v[130:131], v[94:95], v[80:81] op_sel_hi:[1,0]
	v_pk_fma_f32 v[132:133], v[94:95], v[80:81], v[130:131] op_sel:[1,1,0] op_sel_hi:[0,1,1] neg_lo:[0,1,0]
	v_fmac_f32_e32 v118, v132, v71
	v_fmac_f32_e32 v122, v133, v75
	v_pk_mul_f32 v[134:135], v[96:97], v[80:81] op_sel_hi:[1,0]
	v_pk_fma_f32 v[136:137], v[96:97], v[80:81], v[134:135] op_sel:[1,1,0] op_sel_hi:[0,1,1] neg_lo:[0,1,0]
	v_fmac_f32_e32 v119, v136, v71
	v_fmac_f32_e32 v123, v137, v75
	v_pk_mul_f32 v[130:131], v[98:99], v[80:81] op_sel_hi:[1,0]
	v_pk_fma_f32 v[132:133], v[98:99], v[80:81], v[130:131] op_sel:[1,1,0] op_sel_hi:[0,1,1] neg_lo:[0,1,0]
	v_fmac_f32_e32 v120, v132, v71
	v_fmac_f32_e32 v124, v133, v75
	v_pk_mul_f32 v[134:135], v[100:101], v[80:81] op_sel_hi:[1,0]
	v_pk_fma_f32 v[136:137], v[100:101], v[80:81], v[134:135] op_sel:[1,1,0] op_sel_hi:[0,1,1] neg_lo:[0,1,0]
	v_fmac_f32_e32 v121, v136, v71
	v_fmac_f32_e32 v125, v137, v75
	v_pk_mul_f32 v[130:131], v[102:103], v[82:83] op_sel_hi:[1,0]
	v_pk_fma_f32 v[132:133], v[102:103], v[82:83], v[130:131] op_sel:[1,1,0] op_sel_hi:[0,1,1] neg_lo:[0,1,0]
	v_fmac_f32_e32 v118, v132, v72
	v_fmac_f32_e32 v122, v133, v76
	v_pk_mul_f32 v[134:135], v[104:105], v[82:83] op_sel_hi:[1,0]
	v_pk_fma_f32 v[136:137], v[104:105], v[82:83], v[134:135] op_sel:[1,1,0] op_sel_hi:[0,1,1] neg_lo:[0,1,0]
	v_fmac_f32_e32 v119, v136, v72
	v_fmac_f32_e32 v123, v137, v76
	v_pk_mul_f32 v[130:131], v[106:107], v[82:83] op_sel_hi:[1,0]
	v_pk_fma_f32 v[132:133], v[106:107], v[82:83], v[130:131] op_sel:[1,1,0] op_sel_hi:[0,1,1] neg_lo:[0,1,0]
	v_fmac_f32_e32 v120, v132, v72
	v_fmac_f32_e32 v124, v133, v76
	v_pk_mul_f32 v[134:135], v[108:109], v[82:83] op_sel_hi:[1,0]
	v_pk_fma_f32 v[136:137], v[108:109], v[82:83], v[134:135] op_sel:[1,1,0] op_sel_hi:[0,1,1] neg_lo:[0,1,0]
	v_fmac_f32_e32 v121, v136, v72
	v_fmac_f32_e32 v125, v137, v76
	v_pk_mul_f32 v[130:131], v[110:111], v[84:85] op_sel_hi:[1,0]
	v_pk_fma_f32 v[132:133], v[110:111], v[84:85], v[130:131] op_sel:[1,1,0] op_sel_hi:[0,1,1] neg_lo:[0,1,0]
	v_fmac_f32_e32 v118, v132, v73
	v_fmac_f32_e32 v122, v133, v77
	v_pk_mul_f32 v[134:135], v[112:113], v[84:85] op_sel_hi:[1,0]
	v_pk_fma_f32 v[136:137], v[112:113], v[84:85], v[134:135] op_sel:[1,1,0] op_sel_hi:[0,1,1] neg_lo:[0,1,0]
	v_fmac_f32_e32 v119, v136, v73
	v_fmac_f32_e32 v123, v137, v77
	v_pk_mul_f32 v[130:131], v[114:115], v[84:85] op_sel_hi:[1,0]
	v_pk_fma_f32 v[132:133], v[114:115], v[84:85], v[130:131] op_sel:[1,1,0] op_sel_hi:[0,1,1] neg_lo:[0,1,0]
	v_fmac_f32_e32 v120, v132, v73
	v_fmac_f32_e32 v124, v133, v77
	v_pk_mul_f32 v[134:135], v[116:117], v[84:85] op_sel_hi:[1,0]
	v_pk_fma_f32 v[136:137], v[116:117], v[84:85], v[134:135] op_sel:[1,1,0] op_sel_hi:[0,1,1] neg_lo:[0,1,0]
	v_fmac_f32_e32 v121, v136, v73
	v_fmac_f32_e32 v125, v137, v77
	global_load_dwordx4 v[70:73], v126, s[12:13] offset:240
	global_load_dwordx4 v[74:77], v126, s[14:15] offset:240
	global_load_dwordx4 v[78:81], v128, s[16:17] offset:480
	global_load_dwordx4 v[82:85], v128, s[16:17] offset:496
	global_load_dwordx4 v[86:89], v127, s[18:19]
	global_load_dwordx4 v[90:93], v127, s[18:19] offset:16
	global_load_dwordx4 v[94:97], v127, s[18:19] offset:128
	global_load_dwordx4 v[98:101], v127, s[18:19] offset:144
	global_load_dwordx4 v[102:105], v127, s[18:19] offset:256
	global_load_dwordx4 v[106:109], v127, s[18:19] offset:272
	global_load_dwordx4 v[110:113], v127, s[18:19] offset:384
	global_load_dwordx4 v[114:117], v127, s[18:19] offset:400
	s_add_u32 s18, s18, 0x200
	s_addc_u32 s19, s19, 0
	s_waitcnt vmcnt(12)
; __device__ __forceinline__ float2 cmul(float2 a, float2 b) { return make_float2(a.x * b.x - a.y * b.y, a.x * b.y + a.y * b.x); }
; __device__ __forceinline__ void phase1(const Params& P) {
;     ...
;             for (int p = 0; p < 64; ++p) {
; #pragma unroll
;                 for (int q = 0; q < 4; ++q) {
;                     const int e = e0 + q * gsz;
;                     const int cp = e & 15, c = (e >> 4) & 15, tau = (e >> 8) & 31, dg = e >> 13;
;                     const float2 C = make_float2(P.in[17][(dg * 16 + c) * 64 + p], P.in[18][(dg * 16 + c) * 64 + p]);
;                     const float2 z = cmul(LP[(dg * 33 + tau) * 64 + p], BB[(dg * 64 + p) * 16 + cp]);
;                     sacc[q] += C.x * z.x - C.y * z.y;
;                 }
;             }
	v_pk_mul_f32 v[130:131], v[16:17], v[8:9] op_sel_hi:[1,0]
	v_pk_fma_f32 v[132:133], v[16:17], v[8:9], v[130:131] op_sel:[1,1,0] op_sel_hi:[0,1,1] neg_lo:[0,1,0]
	v_fmac_f32_e32 v118, v132, v0
	v_fmac_f32_e32 v122, v133, v4
	v_pk_mul_f32 v[134:135], v[18:19], v[8:9] op_sel_hi:[1,0]
	v_pk_fma_f32 v[136:137], v[18:19], v[8:9], v[134:135] op_sel:[1,1,0] op_sel_hi:[0,1,1] neg_lo:[0,1,0]
	v_fmac_f32_e32 v119, v136, v0
	v_fmac_f32_e32 v123, v137, v4
	v_pk_mul_f32 v[130:131], v[20:21], v[8:9] op_sel_hi:[1,0]
	v_pk_fma_f32 v[132:133], v[20:21], v[8:9], v[130:131] op_sel:[1,1,0] op_sel_hi:[0,1,1] neg_lo:[0,1,0]
	v_fmac_f32_e32 v120, v132, v0
	v_fmac_f32_e32 v124, v133, v4
	v_pk_mul_f32 v[134:135], v[22:23], v[8:9] op_sel_hi:[1,0]
	v_pk_fma_f32 v[136:137], v[22:23], v[8:9], v[134:135] op_sel:[1,1,0] op_sel_hi:[0,1,1] neg_lo:[0,1,0]
	v_fmac_f32_e32 v121, v136, v0
	v_fmac_f32_e32 v125, v137, v4
	v_pk_mul_f32 v[130:131], v[24:25], v[10:11] op_sel_hi:[1,0]
	v_pk_fma_f32 v[132:133], v[24:25], v[10:11], v[130:131] op_sel:[1,1,0] op_sel_hi:[0,1,1] neg_lo:[0,1,0]
	v_fmac_f32_e32 v118, v132, v1
	v_fmac_f32_e32 v122, v133, v5
	v_pk_mul_f32 v[134:135], v[26:27], v[10:11] op_sel_hi:[1,0]
	v_pk_fma_f32 v[136:137], v[26:27], v[10:11], v[134:135] op_sel:[1,1,0] op_sel_hi:[0,1,1] neg_lo:[0,1,0]
	v_fmac_f32_e32 v119, v136, v1
	v_fmac_f32_e32 v123, v137, v5
	v_pk_mul_f32 v[130:131], v[28:29], v[10:11] op_sel_hi:[1,0]
	v_pk_fma_f32 v[132:133], v[28:29], v[10:11], v[130:131] op_sel:[1,1,0] op_sel_hi:[0,1,1] neg_lo:[0,1,0]
	v_fmac_f32_e32 v120, v132, v1
	v_fmac_f32_e32 v124, v133, v5
	v_pk_mul_f32 v[134:135], v[30:31], v[10:11] op_sel_hi:[1,0]
	v_pk_fma_f32 v[136:137], v[30:31], v[10:11], v[134:135] op_sel:[1,1,0] op_sel_hi:[0,1,1] neg_lo:[0,1,0]
	v_fmac_f32_e32 v121, v136, v1
	v_fmac_f32_e32 v125, v137, v5
	v_pk_mul_f32 v[130:131], v[32:33], v[12:13] op_sel_hi:[1,0]
	v_pk_fma_f32 v[132:133], v[32:33], v[12:13], v[130:131] op_sel:[1,1,0] op_sel_hi:[0,1,1] neg_lo:[0,1,0]
	v_fmac_f32_e32 v118, v132, v2
	v_fmac_f32_e32 v122, v133, v6
	v_pk_mul_f32 v[134:135], v[34:35], v[12:13] op_sel_hi:[1,0]
	v_pk_fma_f32 v[136:137], v[34:35], v[12:13], v[134:135] op_sel:[1,1,0] op_sel_hi:[0,1,1] neg_lo:[0,1,0]
	v_fmac_f32_e32 v119, v136, v2
	v_fmac_f32_e32 v123, v137, v6
	v_pk_mul_f32 v[130:131], v[36:37], v[12:13] op_sel_hi:[1,0]
	v_pk_fma_f32 v[132:133], v[36:37], v[12:13], v[130:131] op_sel:[1,1,0] op_sel_hi:[0,1,1] neg_lo:[0,1,0]
	v_fmac_f32_e32 v120, v132, v2
	v_fmac_f32_e32 v124, v133, v6
	v_pk_mul_f32 v[134:135], v[38:39], v[12:13] op_sel_hi:[1,0]
	v_pk_fma_f32 v[136:137], v[38:39], v[12:13], v[134:135] op_sel:[1,1,0] op_sel_hi:[0,1,1] neg_lo:[0,1,0]
	v_fmac_f32_e32 v121, v136, v2
	v_fmac_f32_e32 v125, v137, v6
	v_pk_mul_f32 v[130:131], v[40:41], v[14:15] op_sel_hi:[1,0]
	v_pk_fma_f32 v[132:133], v[40:41], v[14:15], v[130:131] op_sel:[1,1,0] op_sel_hi:[0,1,1] neg_lo:[0,1,0]
	v_fmac_f32_e32 v118, v132, v3
	v_fmac_f32_e32 v122, v133, v7
	v_pk_mul_f32 v[134:135], v[42:43], v[14:15] op_sel_hi:[1,0]
	v_pk_fma_f32 v[136:137], v[42:43], v[14:15], v[134:135] op_sel:[1,1,0] op_sel_hi:[0,1,1] neg_lo:[0,1,0]
	v_fmac_f32_e32 v119, v136, v3
	v_fmac_f32_e32 v123, v137, v7
	v_pk_mul_f32 v[130:131], v[44:45], v[14:15] op_sel_hi:[1,0]
	v_pk_fma_f32 v[132:133], v[44:45], v[14:15], v[130:131] op_sel:[1,1,0] op_sel_hi:[0,1,1] neg_lo:[0,1,0]
	v_fmac_f32_e32 v120, v132, v3
	v_fmac_f32_e32 v124, v133, v7
	v_pk_mul_f32 v[134:135], v[46:47], v[14:15] op_sel_hi:[1,0]
	v_pk_fma_f32 v[136:137], v[46:47], v[14:15], v[134:135] op_sel:[1,1,0] op_sel_hi:[0,1,1] neg_lo:[0,1,0]
	v_fmac_f32_e32 v121, v136, v3
	v_fmac_f32_e32 v125, v137, v7
	s_waitcnt vmcnt(0)
; __device__ __forceinline__ float2 cmul(float2 a, float2 b) { return make_float2(a.x * b.x - a.y * b.y, a.x * b.y + a.y * b.x); }
; __device__ __forceinline__ void phase1(const Params& P) {
;     ...
;             for (int p = 0; p < 64; ++p) {
; #pragma unroll
;                 for (int q = 0; q < 4; ++q) {
;                     const int e = e0 + q * gsz;
;                     const int cp = e & 15, c = (e >> 4) & 15, tau = (e >> 8) & 31, dg = e >> 13;
;                     const float2 C = make_float2(P.in[17][(dg * 16 + c) * 64 + p], P.in[18][(dg * 16 + c) * 64 + p]);
;                     const float2 z = cmul(LP[(dg * 33 + tau) * 64 + p], BB[(dg * 64 + p) * 16 + cp]);
;                     sacc[q] += C.x * z.x - C.y * z.y;
;                 }
;             }
; #pragma unroll
;             for (int q = 0; q < 4; ++q) KD[e0 + q * gsz] = sacc[q];
;         }
;         for (; e0 < N; e0 += gsz) {
	v_pk_mul_f32 v[130:131], v[86:87], v[78:79] op_sel_hi:[1,0]
	v_pk_fma_f32 v[132:133], v[86:87], v[78:79], v[130:131] op_sel:[1,1,0] op_sel_hi:[0,1,1] neg_lo:[0,1,0]
	v_fmac_f32_e32 v118, v132, v70
	v_fmac_f32_e32 v122, v133, v74
	v_pk_mul_f32 v[134:135], v[88:89], v[78:79] op_sel_hi:[1,0]
	v_pk_fma_f32 v[136:137], v[88:89], v[78:79], v[134:135] op_sel:[1,1,0] op_sel_hi:[0,1,1] neg_lo:[0,1,0]
	v_fmac_f32_e32 v119, v136, v70
	v_fmac_f32_e32 v123, v137, v74
	v_pk_mul_f32 v[130:131], v[90:91], v[78:79] op_sel_hi:[1,0]
	v_pk_fma_f32 v[132:133], v[90:91], v[78:79], v[130:131] op_sel:[1,1,0] op_sel_hi:[0,1,1] neg_lo:[0,1,0]
	v_fmac_f32_e32 v120, v132, v70
	v_fmac_f32_e32 v124, v133, v74
	v_pk_mul_f32 v[134:135], v[92:93], v[78:79] op_sel_hi:[1,0]
	v_pk_fma_f32 v[136:137], v[92:93], v[78:79], v[134:135] op_sel:[1,1,0] op_sel_hi:[0,1,1] neg_lo:[0,1,0]
	v_fmac_f32_e32 v121, v136, v70
	v_fmac_f32_e32 v125, v137, v74
	v_pk_mul_f32 v[130:131], v[94:95], v[80:81] op_sel_hi:[1,0]
	v_pk_fma_f32 v[132:133], v[94:95], v[80:81], v[130:131] op_sel:[1,1,0] op_sel_hi:[0,1,1] neg_lo:[0,1,0]
	v_fmac_f32_e32 v118, v132, v71
	v_fmac_f32_e32 v122, v133, v75
	v_pk_mul_f32 v[134:135], v[96:97], v[80:81] op_sel_hi:[1,0]
	v_pk_fma_f32 v[136:137], v[96:97], v[80:81], v[134:135] op_sel:[1,1,0] op_sel_hi:[0,1,1] neg_lo:[0,1,0]
	v_fmac_f32_e32 v119, v136, v71
	v_fmac_f32_e32 v123, v137, v75
	v_pk_mul_f32 v[130:131], v[98:99], v[80:81] op_sel_hi:[1,0]
	v_pk_fma_f32 v[132:133], v[98:99], v[80:81], v[130:131] op_sel:[1,1,0] op_sel_hi:[0,1,1] neg_lo:[0,1,0]
	v_fmac_f32_e32 v120, v132, v71
	v_fmac_f32_e32 v124, v133, v75
	v_pk_mul_f32 v[134:135], v[100:101], v[80:81] op_sel_hi:[1,0]
	v_pk_fma_f32 v[136:137], v[100:101], v[80:81], v[134:135] op_sel:[1,1,0] op_sel_hi:[0,1,1] neg_lo:[0,1,0]
	v_fmac_f32_e32 v121, v136, v71
	v_fmac_f32_e32 v125, v137, v75
	v_pk_mul_f32 v[130:131], v[102:103], v[82:83] op_sel_hi:[1,0]
	v_pk_fma_f32 v[132:133], v[102:103], v[82:83], v[130:131] op_sel:[1,1,0] op_sel_hi:[0,1,1] neg_lo:[0,1,0]
	v_fmac_f32_e32 v118, v132, v72
	v_fmac_f32_e32 v122, v133, v76
	v_pk_mul_f32 v[134:135], v[104:105], v[82:83] op_sel_hi:[1,0]
	v_pk_fma_f32 v[136:137], v[104:105], v[82:83], v[134:135] op_sel:[1,1,0] op_sel_hi:[0,1,1] neg_lo:[0,1,0]
	v_fmac_f32_e32 v119, v136, v72
	v_fmac_f32_e32 v123, v137, v76
	v_pk_mul_f32 v[130:131], v[106:107], v[82:83] op_sel_hi:[1,0]
	v_pk_fma_f32 v[132:133], v[106:107], v[82:83], v[130:131] op_sel:[1,1,0] op_sel_hi:[0,1,1] neg_lo:[0,1,0]
	v_fmac_f32_e32 v120, v132, v72
	v_fmac_f32_e32 v124, v133, v76
	v_pk_mul_f32 v[134:135], v[108:109], v[82:83] op_sel_hi:[1,0]
	v_pk_fma_f32 v[136:137], v[108:109], v[82:83], v[134:135] op_sel:[1,1,0] op_sel_hi:[0,1,1] neg_lo:[0,1,0]
	v_fmac_f32_e32 v121, v136, v72
	v_fmac_f32_e32 v125, v137, v76
	v_pk_mul_f32 v[130:131], v[110:111], v[84:85] op_sel_hi:[1,0]
	v_pk_fma_f32 v[132:133], v[110:111], v[84:85], v[130:131] op_sel:[1,1,0] op_sel_hi:[0,1,1] neg_lo:[0,1,0]
	v_fmac_f32_e32 v118, v132, v73
	v_fmac_f32_e32 v122, v133, v77
	v_pk_mul_f32 v[134:135], v[112:113], v[84:85] op_sel_hi:[1,0]
	v_pk_fma_f32 v[136:137], v[112:113], v[84:85], v[134:135] op_sel:[1,1,0] op_sel_hi:[0,1,1] neg_lo:[0,1,0]
	v_fmac_f32_e32 v119, v136, v73
	v_fmac_f32_e32 v123, v137, v77
	v_pk_mul_f32 v[130:131], v[114:115], v[84:85] op_sel_hi:[1,0]
	v_pk_fma_f32 v[132:133], v[114:115], v[84:85], v[130:131] op_sel:[1,1,0] op_sel_hi:[0,1,1] neg_lo:[0,1,0]
	v_fmac_f32_e32 v120, v132, v73
	v_fmac_f32_e32 v124, v133, v77
	v_pk_mul_f32 v[134:135], v[116:117], v[84:85] op_sel_hi:[1,0]
	v_pk_fma_f32 v[136:137], v[116:117], v[84:85], v[134:135] op_sel:[1,1,0] op_sel_hi:[0,1,1] neg_lo:[0,1,0]
	v_fmac_f32_e32 v121, v136, v73
	v_fmac_f32_e32 v125, v137, v77
	v_sub_f32_e32 v118, v118, v122
	v_sub_f32_e32 v119, v119, v123
	v_sub_f32_e32 v120, v120, v124
	v_sub_f32_e32 v121, v121, v125
	s_lshl_b32 s7, s4, 10
	s_add_u32 s12, s0, s7
	s_addc_u32 s13, s1, 0
	v_lshlrev_b32_e32 v130, 4, v170
	global_store_dwordx4 v130, v[118:121], s[12:13]
	v_mov_b32_e32 v0, 0x80000
	s_branch .Lkd_pad
	s_nop 0
	s_nop 0
	s_nop 0
	s_nop 0
	s_nop 0
	s_nop 0
	s_nop 0
	s_nop 0
	s_nop 0
.Lkd_pad:
.LBB0_200:
	s_or_b64 exec, exec, s[2:3]
	s_mov_b32 s2, 0x80000
	v_cmp_gt_i32_e32 vcc, s2, v0
	s_and_saveexec_b64 s[2:3], vcc
	s_cbranch_execz .LBB0_205
	v_and_b32_e32 v16, 15, v0
	v_lshlrev_b32_e32 v17, 2, v0
	s_lshl_b32 s11, s90, 11
	v_or_b32_e32 v18, 48, v16
	v_or_b32_e32 v19, 32, v16
	v_or_b32_e32 v20, 16, v16
	s_mov_b64 s[4:5], 0
	s_movk_i32 s16, 0x3c0
	s_mov_b64 s[6:7], 0x5000000
	s_mov_b32 s17, 0x5108000
	s_mov_b32 s18, 0x5000000
	s_mov_b64 s[12:13], 0x200
	s_mov_b32 s19, 0x7ffff
